# dropped the redundant post-barrier s_waitcnt lgkmcnt(0) at each compute-segment head (12 loops)
# speedup vs baseline: 1.0063x; 1.0035x over previous
.LBB0_272:
	s_add_u32 s58, s22, 0xfff00000
	s_addc_u32 s59, s23, -1
	s_mov_b32 m0, s36
	ds_read_b128 v[154:157], v148
	global_load_lds_dwordx4 v130, s[58:59]
	s_mov_b32 m0, s37
	ds_read_b128 v[158:161], v148 offset:1024
	global_load_lds_dwordx4 v134, s[58:59]
	s_mov_b32 m0, s40
	ds_read_b128 v[164:167], v148 offset:2048
	global_load_lds_dwordx4 v142, s[22:23]
	s_mov_b32 m0, s41
	ds_read_b128 v[168:171], v148 offset:3072
	global_load_lds_dwordx4 v144, s[22:23]
	ds_read_b128 v[172:175], v149
	ds_read_b128 v[176:179], v149 offset:1024
	ds_read_b128 v[180:183], v149 offset:2048
	ds_read_b128 v[184:187], v149 offset:3072
	s_add_u32 s24, s22, 0xfff00080
	s_addc_u32 s25, s23, -1
	s_cmp_eq_u32 s56, 60
	s_cselect_b32 s27, s51, s25
	s_cselect_b32 s26, s52, s24
	s_cselect_b32 s25, s7, s55
	s_cselect_b32 s24, s53, s54
	ds_read_b128 v[188:191], v150
	ds_read_b128 v[192:195], v150 offset:1024
	ds_read_b128 v[196:199], v150 offset:2048
	ds_read_b128 v[200:203], v150 offset:3072
	ds_read_b128 v[204:207], v150 offset:4096
	ds_read_b128 v[208:211], v150 offset:5120
	ds_read_b128 v[212:215], v150 offset:6144
	ds_read_b128 v[216:219], v150 offset:7168
	s_waitcnt vmcnt(8)
	s_waitcnt lgkmcnt(0)
	s_barrier
	v_mfma_f32_16x16x32_bf16 v[126:129], v[154:157], v[188:191], v[126:129]
	v_mfma_f32_16x16x32_bf16 v[126:129], v[158:161], v[192:195], v[126:129]
	v_mfma_f32_16x16x32_bf16 v[122:125], v[168:171], v[192:195], v[122:125]
	v_mfma_f32_16x16x32_bf16 v[122:125], v[164:167], v[188:191], v[122:125]
	v_mfma_f32_16x16x32_bf16 v[114:117], v[164:167], v[196:199], v[114:117]
	v_mfma_f32_16x16x32_bf16 v[114:117], v[168:171], v[200:203], v[114:117]
	v_mfma_f32_16x16x32_bf16 v[118:121], v[158:161], v[200:203], v[118:121]
	v_mfma_f32_16x16x32_bf16 v[118:121], v[154:157], v[196:199], v[118:121]
	v_mfma_f32_16x16x32_bf16 v[102:105], v[154:157], v[204:207], v[102:105]
	v_mfma_f32_16x16x32_bf16 v[102:105], v[158:161], v[208:211], v[102:105]
	v_mfma_f32_16x16x32_bf16 v[98:101], v[168:171], v[208:211], v[98:101]
	v_mfma_f32_16x16x32_bf16 v[98:101], v[164:167], v[204:207], v[98:101]
	v_mfma_f32_16x16x32_bf16 v[82:85], v[164:167], v[212:215], v[82:85]
	v_mfma_f32_16x16x32_bf16 v[82:85], v[168:171], v[216:219], v[82:85]
	v_mfma_f32_16x16x32_bf16 v[86:89], v[158:161], v[216:219], v[86:89]
	v_mfma_f32_16x16x32_bf16 v[86:89], v[154:157], v[212:215], v[86:89]
	v_mfma_f32_16x16x32_bf16 v[70:73], v[172:175], v[212:215], v[70:73]
	v_mfma_f32_16x16x32_bf16 v[70:73], v[176:179], v[216:219], v[70:73]
	v_mfma_f32_16x16x32_bf16 v[66:69], v[184:187], v[216:219], v[66:69]
	v_mfma_f32_16x16x32_bf16 v[66:69], v[180:183], v[212:215], v[66:69]
	v_mfma_f32_16x16x32_bf16 v[74:77], v[180:183], v[204:207], v[74:77]
	v_mfma_f32_16x16x32_bf16 v[74:77], v[184:187], v[208:211], v[74:77]
	v_mfma_f32_16x16x32_bf16 v[78:81], v[176:179], v[208:211], v[78:81]
	v_mfma_f32_16x16x32_bf16 v[78:81], v[172:175], v[204:207], v[78:81]
	v_mfma_f32_16x16x32_bf16 v[94:97], v[172:175], v[196:199], v[94:97]
	v_mfma_f32_16x16x32_bf16 v[94:97], v[176:179], v[200:203], v[94:97]
	v_mfma_f32_16x16x32_bf16 v[90:93], v[184:187], v[200:203], v[90:93]
	v_mfma_f32_16x16x32_bf16 v[90:93], v[180:183], v[196:199], v[90:93]
	v_mfma_f32_16x16x32_bf16 v[106:109], v[180:183], v[188:191], v[106:109]
	v_mfma_f32_16x16x32_bf16 v[106:109], v[184:187], v[192:195], v[106:109]
	v_mfma_f32_16x16x32_bf16 v[110:113], v[176:179], v[192:195], v[110:113]
	v_mfma_f32_16x16x32_bf16 v[110:113], v[172:175], v[188:191], v[110:113]
	s_barrier
	s_mov_b32 m0, s42
	s_add_u32 s58, s24, 0x100000
	global_load_lds_dwordx4 v132, s[24:25]
	s_mov_b32 m0, s43
	s_addc_u32 s59, s25, 0
	global_load_lds_dwordx4 v136, s[24:25]
	s_mov_b32 m0, s44
	ds_read_b128 v[188:191], v150 offset:16384
	global_load_lds_dwordx4 v132, s[58:59]
	s_mov_b32 m0, s45
	ds_read_b128 v[192:195], v150 offset:17408
	global_load_lds_dwordx4 v136, s[58:59]
	ds_read_b128 v[196:199], v150 offset:18432
	ds_read_b128 v[200:203], v150 offset:19456
	ds_read_b128 v[204:207], v150 offset:20480
	ds_read_b128 v[208:211], v150 offset:21504
	ds_read_b128 v[212:215], v150 offset:22528
	ds_read_b128 v[216:219], v150 offset:23552
	s_waitcnt vmcnt(6)
	s_waitcnt lgkmcnt(0)
	s_barrier
	v_mfma_f32_16x16x32_bf16 v[62:65], v[154:157], v[188:191], v[62:65]
	v_mfma_f32_16x16x32_bf16 v[62:65], v[158:161], v[192:195], v[62:65]
	v_mfma_f32_16x16x32_bf16 v[58:61], v[168:171], v[192:195], v[58:61]
	v_mfma_f32_16x16x32_bf16 v[58:61], v[164:167], v[188:191], v[58:61]
	v_mfma_f32_16x16x32_bf16 v[50:53], v[164:167], v[196:199], v[50:53]
	v_mfma_f32_16x16x32_bf16 v[50:53], v[168:171], v[200:203], v[50:53]
	v_mfma_f32_16x16x32_bf16 v[54:57], v[158:161], v[200:203], v[54:57]
	v_mfma_f32_16x16x32_bf16 v[54:57], v[154:157], v[196:199], v[54:57]
	v_mfma_f32_16x16x32_bf16 v[38:41], v[154:157], v[204:207], v[38:41]
	v_mfma_f32_16x16x32_bf16 v[38:41], v[158:161], v[208:211], v[38:41]
	v_mfma_f32_16x16x32_bf16 v[34:37], v[168:171], v[208:211], v[34:37]
	v_mfma_f32_16x16x32_bf16 v[34:37], v[164:167], v[204:207], v[34:37]
	v_mfma_f32_16x16x32_bf16 v[18:21], v[164:167], v[212:215], v[18:21]
	v_mfma_f32_16x16x32_bf16 v[18:21], v[168:171], v[216:219], v[18:21]
	v_mfma_f32_16x16x32_bf16 v[22:25], v[158:161], v[216:219], v[22:25]
	v_mfma_f32_16x16x32_bf16 v[22:25], v[154:157], v[212:215], v[22:25]
	v_mfma_f32_16x16x32_bf16 v[6:9], v[172:175], v[212:215], v[6:9]
	v_mfma_f32_16x16x32_bf16 v[6:9], v[176:179], v[216:219], v[6:9]
	v_mfma_f32_16x16x32_bf16 v[2:5], v[184:187], v[216:219], v[2:5]
	v_mfma_f32_16x16x32_bf16 v[2:5], v[180:183], v[212:215], v[2:5]
	v_mfma_f32_16x16x32_bf16 v[10:13], v[180:183], v[204:207], v[10:13]
	v_mfma_f32_16x16x32_bf16 v[10:13], v[184:187], v[208:211], v[10:13]
	v_mfma_f32_16x16x32_bf16 v[14:17], v[176:179], v[208:211], v[14:17]
	v_mfma_f32_16x16x32_bf16 v[14:17], v[172:175], v[204:207], v[14:17]
	v_mfma_f32_16x16x32_bf16 v[30:33], v[172:175], v[196:199], v[30:33]
	v_mfma_f32_16x16x32_bf16 v[30:33], v[176:179], v[200:203], v[30:33]
	v_mfma_f32_16x16x32_bf16 v[26:29], v[184:187], v[200:203], v[26:29]
	v_mfma_f32_16x16x32_bf16 v[26:29], v[180:183], v[196:199], v[26:29]
	v_mfma_f32_16x16x32_bf16 v[42:45], v[180:183], v[188:191], v[42:45]
	v_mfma_f32_16x16x32_bf16 v[42:45], v[184:187], v[192:195], v[42:45]
	v_mfma_f32_16x16x32_bf16 v[46:49], v[176:179], v[192:195], v[46:49]
	v_mfma_f32_16x16x32_bf16 v[46:49], v[172:175], v[188:191], v[46:49]
	s_barrier
	s_mov_b32 m0, s30
	ds_read_b128 v[154:157], v151
	global_load_lds_dwordx4 v130, s[26:27]
	s_mov_b32 m0, s31
	ds_read_b128 v[158:161], v151 offset:1024
	global_load_lds_dwordx4 v134, s[26:27]
	s_add_u32 s26, s26, 0x100000
	s_addc_u32 s27, s27, 0
	s_mov_b32 m0, s33
	ds_read_b128 v[164:167], v151 offset:2048
	global_load_lds_dwordx4 v130, s[26:27]
	s_mov_b32 m0, s34
	ds_read_b128 v[168:171], v151 offset:3072
	global_load_lds_dwordx4 v134, s[26:27]
	ds_read_b128 v[172:175], v152
	ds_read_b128 v[176:179], v152 offset:1024
	ds_read_b128 v[180:183], v152 offset:2048
	ds_read_b128 v[184:187], v152 offset:3072
	ds_read_b128 v[188:191], v150 offset:32768
	ds_read_b128 v[192:195], v150 offset:33792
	ds_read_b128 v[196:199], v150 offset:34816
	ds_read_b128 v[200:203], v150 offset:35840
	ds_read_b128 v[204:207], v150 offset:36864
	ds_read_b128 v[208:211], v150 offset:37888
	ds_read_b128 v[212:215], v150 offset:38912
	ds_read_b128 v[216:219], v150 offset:39936
	s_waitcnt vmcnt(8)
	s_waitcnt lgkmcnt(0)
	s_barrier
	v_mfma_f32_16x16x32_bf16 v[126:129], v[154:157], v[188:191], v[126:129]
	v_mfma_f32_16x16x32_bf16 v[126:129], v[158:161], v[192:195], v[126:129]
	v_mfma_f32_16x16x32_bf16 v[122:125], v[168:171], v[192:195], v[122:125]
	v_mfma_f32_16x16x32_bf16 v[122:125], v[164:167], v[188:191], v[122:125]
	v_mfma_f32_16x16x32_bf16 v[114:117], v[164:167], v[196:199], v[114:117]
	v_mfma_f32_16x16x32_bf16 v[114:117], v[168:171], v[200:203], v[114:117]
	v_mfma_f32_16x16x32_bf16 v[118:121], v[158:161], v[200:203], v[118:121]
	v_mfma_f32_16x16x32_bf16 v[118:121], v[154:157], v[196:199], v[118:121]
	v_mfma_f32_16x16x32_bf16 v[102:105], v[154:157], v[204:207], v[102:105]
	v_mfma_f32_16x16x32_bf16 v[102:105], v[158:161], v[208:211], v[102:105]
	v_mfma_f32_16x16x32_bf16 v[98:101], v[168:171], v[208:211], v[98:101]
	v_mfma_f32_16x16x32_bf16 v[98:101], v[164:167], v[204:207], v[98:101]
	v_mfma_f32_16x16x32_bf16 v[82:85], v[164:167], v[212:215], v[82:85]
	v_mfma_f32_16x16x32_bf16 v[82:85], v[168:171], v[216:219], v[82:85]
	v_mfma_f32_16x16x32_bf16 v[86:89], v[158:161], v[216:219], v[86:89]
	v_mfma_f32_16x16x32_bf16 v[86:89], v[154:157], v[212:215], v[86:89]
	v_mfma_f32_16x16x32_bf16 v[70:73], v[172:175], v[212:215], v[70:73]
	v_mfma_f32_16x16x32_bf16 v[70:73], v[176:179], v[216:219], v[70:73]
	v_mfma_f32_16x16x32_bf16 v[66:69], v[184:187], v[216:219], v[66:69]
	v_mfma_f32_16x16x32_bf16 v[66:69], v[180:183], v[212:215], v[66:69]
	v_mfma_f32_16x16x32_bf16 v[74:77], v[180:183], v[204:207], v[74:77]
	v_mfma_f32_16x16x32_bf16 v[74:77], v[184:187], v[208:211], v[74:77]
	v_mfma_f32_16x16x32_bf16 v[78:81], v[176:179], v[208:211], v[78:81]
	v_mfma_f32_16x16x32_bf16 v[78:81], v[172:175], v[204:207], v[78:81]
	v_mfma_f32_16x16x32_bf16 v[94:97], v[172:175], v[196:199], v[94:97]
	v_mfma_f32_16x16x32_bf16 v[94:97], v[176:179], v[200:203], v[94:97]
	v_mfma_f32_16x16x32_bf16 v[90:93], v[184:187], v[200:203], v[90:93]
	v_mfma_f32_16x16x32_bf16 v[90:93], v[180:183], v[196:199], v[90:93]
	v_mfma_f32_16x16x32_bf16 v[106:109], v[180:183], v[188:191], v[106:109]
	v_mfma_f32_16x16x32_bf16 v[106:109], v[184:187], v[192:195], v[106:109]
	v_mfma_f32_16x16x32_bf16 v[110:113], v[176:179], v[192:195], v[110:113]
	v_mfma_f32_16x16x32_bf16 v[110:113], v[172:175], v[188:191], v[110:113]
	s_barrier
	s_mov_b32 m0, s47
	s_add_u32 s24, s24, 0x80
	s_addc_u32 s25, s25, 0
	global_load_lds_dwordx4 v132, s[24:25]
	s_mov_b32 m0, s48
	ds_read_b128 v[188:191], v150 offset:49152
	global_load_lds_dwordx4 v136, s[24:25]
	s_add_i32 s26, s46, s29
	s_mov_b32 m0, s26
	s_add_u32 s24, s24, 0x100000
	s_addc_u32 s25, s25, 0
	global_load_lds_dwordx4 v132, s[24:25]
	s_add_i32 m0, s26, 0x2000
	ds_read_b128 v[192:195], v150 offset:50176
	global_load_lds_dwordx4 v136, s[24:25]
	ds_read_b128 v[196:199], v150 offset:51200
	ds_read_b128 v[200:203], v150 offset:52224
	ds_read_b128 v[204:207], v150 offset:53248
	ds_read_b128 v[208:211], v150 offset:54272
	ds_read_b128 v[212:215], v150 offset:55296
	ds_read_b128 v[216:219], v150 offset:56320
	s_waitcnt vmcnt(6)
	s_waitcnt lgkmcnt(0)
	s_barrier
	v_mfma_f32_16x16x32_bf16 v[62:65], v[154:157], v[188:191], v[62:65]
	v_mfma_f32_16x16x32_bf16 v[62:65], v[158:161], v[192:195], v[62:65]
	v_mfma_f32_16x16x32_bf16 v[58:61], v[168:171], v[192:195], v[58:61]
	v_mfma_f32_16x16x32_bf16 v[58:61], v[164:167], v[188:191], v[58:61]
	v_mfma_f32_16x16x32_bf16 v[50:53], v[164:167], v[196:199], v[50:53]
	v_mfma_f32_16x16x32_bf16 v[50:53], v[168:171], v[200:203], v[50:53]
	v_mfma_f32_16x16x32_bf16 v[54:57], v[158:161], v[200:203], v[54:57]
	v_mfma_f32_16x16x32_bf16 v[54:57], v[154:157], v[196:199], v[54:57]
	v_mfma_f32_16x16x32_bf16 v[38:41], v[154:157], v[204:207], v[38:41]
	v_mfma_f32_16x16x32_bf16 v[38:41], v[158:161], v[208:211], v[38:41]
	v_mfma_f32_16x16x32_bf16 v[34:37], v[168:171], v[208:211], v[34:37]
	v_mfma_f32_16x16x32_bf16 v[34:37], v[164:167], v[204:207], v[34:37]
	v_mfma_f32_16x16x32_bf16 v[18:21], v[164:167], v[212:215], v[18:21]
	v_mfma_f32_16x16x32_bf16 v[18:21], v[168:171], v[216:219], v[18:21]
	v_mfma_f32_16x16x32_bf16 v[22:25], v[158:161], v[216:219], v[22:25]
	v_mfma_f32_16x16x32_bf16 v[22:25], v[154:157], v[212:215], v[22:25]
	v_mfma_f32_16x16x32_bf16 v[6:9], v[172:175], v[212:215], v[6:9]
	v_mfma_f32_16x16x32_bf16 v[6:9], v[176:179], v[216:219], v[6:9]
	v_mfma_f32_16x16x32_bf16 v[2:5], v[184:187], v[216:219], v[2:5]
	v_mfma_f32_16x16x32_bf16 v[2:5], v[180:183], v[212:215], v[2:5]
	v_mfma_f32_16x16x32_bf16 v[10:13], v[180:183], v[204:207], v[10:13]
	v_mfma_f32_16x16x32_bf16 v[10:13], v[184:187], v[208:211], v[10:13]
	v_mfma_f32_16x16x32_bf16 v[14:17], v[176:179], v[208:211], v[14:17]
	v_mfma_f32_16x16x32_bf16 v[14:17], v[172:175], v[204:207], v[14:17]
	v_mfma_f32_16x16x32_bf16 v[30:33], v[172:175], v[196:199], v[30:33]
	v_mfma_f32_16x16x32_bf16 v[30:33], v[176:179], v[200:203], v[30:33]
	v_mfma_f32_16x16x32_bf16 v[26:29], v[184:187], v[200:203], v[26:29]
	v_mfma_f32_16x16x32_bf16 v[26:29], v[180:183], v[196:199], v[26:29]
	v_mfma_f32_16x16x32_bf16 v[42:45], v[180:183], v[188:191], v[42:45]
	v_mfma_f32_16x16x32_bf16 v[42:45], v[184:187], v[192:195], v[42:45]
	v_mfma_f32_16x16x32_bf16 v[46:49], v[176:179], v[192:195], v[46:49]
	v_mfma_f32_16x16x32_bf16 v[46:49], v[172:175], v[188:191], v[46:49]
	s_barrier
	s_add_i32 s56, s56, 2
	s_add_u32 s22, s22, 0x100
	s_addc_u32 s23, s23, 0
	s_add_u32 s54, s54, 0x100
	s_addc_u32 s55, s55, 0
	s_cmp_gt_u32 s56, 61
	s_cbranch_scc0 .LBB0_272
	s_and_b64 vcc, exec, s[16:17]
	s_cbranch_vccz .LBB0_277
	s_barrier
	v_lshl_add_u32 v138, s50, 8, v1
	s_cmp_gt_i32 s49, 63
	s_mov_b64 s[22:23], -1
	s_cbranch_scc1 .LBB0_278

.LBB0_1009:
	ds_read_b128 v[142:145], v155
	ds_read_b128 v[158:161], v155 offset:1024
	ds_read_b128 v[168:171], v155 offset:2048
	ds_read_b128 v[176:179], v155 offset:3072
	ds_read_b128 v[180:183], v156
	ds_read_b128 v[184:187], v156 offset:1024
	ds_read_b128 v[188:191], v156 offset:2048
	ds_read_b128 v[192:195], v156 offset:3072
	s_add_u32 s24, s22, 0xfff00080
	s_addc_u32 s25, s23, -1
	s_cmp_eq_u32 s51, 60
	s_cselect_b32 s27, s19, s25
	s_cselect_b32 s26, s47, s24
	s_cselect_b32 s25, s7, s50
	s_cselect_b32 s24, s48, s49
	s_mov_b32 m0, s40
	ds_read_b128 v[202:205], v157
	ds_read_b128 v[206:209], v157 offset:1024
	ds_read_b128 v[210:213], v157 offset:2048
	ds_read_b128 v[214:217], v157 offset:3072
	ds_read_b128 v[218:221], v157 offset:4096
	ds_read_b128 v[222:225], v157 offset:5120
	ds_read_b128 v[226:229], v157 offset:6144
	ds_read_b128 v[230:233], v157 offset:7168
	global_load_lds_dwordx4 v138, s[22:23]
	s_mov_b32 m0, s41
	s_nop 0
	global_load_lds_dwordx4 v140, s[22:23]
	s_waitcnt vmcnt(8)
	s_waitcnt lgkmcnt(0)
	s_barrier
	v_mfma_f32_16x16x32_bf16 v[126:129], v[142:145], v[202:205], v[126:129]
	v_mfma_f32_16x16x32_bf16 v[126:129], v[158:161], v[206:209], v[126:129]
	v_mfma_f32_16x16x32_bf16 v[122:125], v[176:179], v[206:209], v[122:125]
	v_mfma_f32_16x16x32_bf16 v[122:125], v[168:171], v[202:205], v[122:125]
	v_mfma_f32_16x16x32_bf16 v[106:109], v[168:171], v[210:213], v[106:109]
	v_mfma_f32_16x16x32_bf16 v[106:109], v[176:179], v[214:217], v[106:109]
	v_mfma_f32_16x16x32_bf16 v[110:113], v[158:161], v[214:217], v[110:113]
	v_mfma_f32_16x16x32_bf16 v[110:113], v[142:145], v[210:213], v[110:113]
	v_mfma_f32_16x16x32_bf16 v[94:97], v[142:145], v[218:221], v[94:97]
	v_mfma_f32_16x16x32_bf16 v[94:97], v[158:161], v[222:225], v[94:97]
	v_mfma_f32_16x16x32_bf16 v[90:93], v[176:179], v[222:225], v[90:93]
	v_mfma_f32_16x16x32_bf16 v[90:93], v[168:171], v[218:221], v[90:93]
	v_mfma_f32_16x16x32_bf16 v[74:77], v[168:171], v[226:229], v[74:77]
	v_mfma_f32_16x16x32_bf16 v[74:77], v[176:179], v[230:233], v[74:77]
	v_mfma_f32_16x16x32_bf16 v[78:81], v[158:161], v[230:233], v[78:81]
	v_mfma_f32_16x16x32_bf16 v[78:81], v[142:145], v[226:229], v[78:81]
	v_mfma_f32_16x16x32_bf16 v[70:73], v[180:183], v[226:229], v[70:73]
	v_mfma_f32_16x16x32_bf16 v[70:73], v[184:187], v[230:233], v[70:73]
	v_mfma_f32_16x16x32_bf16 v[66:69], v[192:195], v[230:233], v[66:69]
	v_mfma_f32_16x16x32_bf16 v[66:69], v[188:191], v[226:229], v[66:69]
	v_mfma_f32_16x16x32_bf16 v[82:85], v[188:191], v[218:221], v[82:85]
	v_mfma_f32_16x16x32_bf16 v[82:85], v[192:195], v[222:225], v[82:85]
	v_mfma_f32_16x16x32_bf16 v[86:89], v[184:187], v[222:225], v[86:89]
	v_mfma_f32_16x16x32_bf16 v[86:89], v[180:183], v[218:221], v[86:89]
	v_mfma_f32_16x16x32_bf16 v[102:105], v[180:183], v[210:213], v[102:105]
	v_mfma_f32_16x16x32_bf16 v[102:105], v[184:187], v[214:217], v[102:105]
	v_mfma_f32_16x16x32_bf16 v[98:101], v[192:195], v[214:217], v[98:101]
	v_mfma_f32_16x16x32_bf16 v[98:101], v[188:191], v[210:213], v[98:101]
	v_mfma_f32_16x16x32_bf16 v[114:117], v[188:191], v[202:205], v[114:117]
	v_mfma_f32_16x16x32_bf16 v[114:117], v[192:195], v[206:209], v[114:117]
	v_mfma_f32_16x16x32_bf16 v[118:121], v[184:187], v[206:209], v[118:121]
	v_mfma_f32_16x16x32_bf16 v[118:121], v[180:183], v[202:205], v[118:121]
	s_barrier
	s_mov_b32 m0, s42
	s_add_u32 s52, s24, 0x100000
	ds_read_b128 v[202:205], v157 offset:16384
	ds_read_b128 v[206:209], v157 offset:17408
	ds_read_b128 v[210:213], v157 offset:18432
	ds_read_b128 v[214:217], v157 offset:19456
	ds_read_b128 v[218:221], v157 offset:20480
	ds_read_b128 v[222:225], v157 offset:21504
	ds_read_b128 v[226:229], v157 offset:22528
	ds_read_b128 v[230:233], v157 offset:23552
	global_load_lds_dwordx4 v132, s[24:25]
	s_mov_b32 m0, s43
	s_addc_u32 s53, s25, 0
	global_load_lds_dwordx4 v136, s[24:25]
	s_mov_b32 m0, s44
	s_nop 0
	global_load_lds_dwordx4 v132, s[52:53]
	s_add_i32 m0, s44, 0x2000
	s_nop 0
	global_load_lds_dwordx4 v136, s[52:53]
	s_mov_b32 m0, s33
	s_nop 0
	global_load_lds_dwordx4 v130, s[26:27]
	s_mov_b32 m0, s34
	s_nop 0
	global_load_lds_dwordx4 v134, s[26:27]
	s_waitcnt vmcnt(8)
	s_waitcnt lgkmcnt(0)
	s_barrier
	v_mfma_f32_16x16x32_bf16 v[62:65], v[142:145], v[202:205], v[62:65]
	v_mfma_f32_16x16x32_bf16 v[62:65], v[158:161], v[206:209], v[62:65]
	v_mfma_f32_16x16x32_bf16 v[58:61], v[176:179], v[206:209], v[58:61]
	v_mfma_f32_16x16x32_bf16 v[58:61], v[168:171], v[202:205], v[58:61]
	v_mfma_f32_16x16x32_bf16 v[42:45], v[168:171], v[210:213], v[42:45]
	v_mfma_f32_16x16x32_bf16 v[42:45], v[176:179], v[214:217], v[42:45]
	v_mfma_f32_16x16x32_bf16 v[46:49], v[158:161], v[214:217], v[46:49]
	v_mfma_f32_16x16x32_bf16 v[46:49], v[142:145], v[210:213], v[46:49]
	v_mfma_f32_16x16x32_bf16 v[30:33], v[142:145], v[218:221], v[30:33]
	v_mfma_f32_16x16x32_bf16 v[30:33], v[158:161], v[222:225], v[30:33]
	v_mfma_f32_16x16x32_bf16 v[26:29], v[176:179], v[222:225], v[26:29]
	v_mfma_f32_16x16x32_bf16 v[26:29], v[168:171], v[218:221], v[26:29]
	v_mfma_f32_16x16x32_bf16 v[10:13], v[168:171], v[226:229], v[10:13]
	v_mfma_f32_16x16x32_bf16 v[10:13], v[176:179], v[230:233], v[10:13]
	v_mfma_f32_16x16x32_bf16 v[14:17], v[158:161], v[230:233], v[14:17]
	v_mfma_f32_16x16x32_bf16 v[14:17], v[142:145], v[226:229], v[14:17]
	v_mfma_f32_16x16x32_bf16 v[6:9], v[180:183], v[226:229], v[6:9]
	v_mfma_f32_16x16x32_bf16 v[6:9], v[184:187], v[230:233], v[6:9]
	v_mfma_f32_16x16x32_bf16 v[2:5], v[192:195], v[230:233], v[2:5]
	v_mfma_f32_16x16x32_bf16 v[2:5], v[188:191], v[226:229], v[2:5]
	v_mfma_f32_16x16x32_bf16 v[18:21], v[188:191], v[218:221], v[18:21]
	v_mfma_f32_16x16x32_bf16 v[18:21], v[192:195], v[222:225], v[18:21]
	v_mfma_f32_16x16x32_bf16 v[22:25], v[184:187], v[222:225], v[22:25]
	v_mfma_f32_16x16x32_bf16 v[22:25], v[180:183], v[218:221], v[22:25]
	v_mfma_f32_16x16x32_bf16 v[38:41], v[180:183], v[210:213], v[38:41]
	v_mfma_f32_16x16x32_bf16 v[38:41], v[184:187], v[214:217], v[38:41]
	v_mfma_f32_16x16x32_bf16 v[34:37], v[192:195], v[214:217], v[34:37]
	v_mfma_f32_16x16x32_bf16 v[34:37], v[188:191], v[210:213], v[34:37]
	v_mfma_f32_16x16x32_bf16 v[50:53], v[188:191], v[202:205], v[50:53]
	v_mfma_f32_16x16x32_bf16 v[50:53], v[192:195], v[206:209], v[50:53]
	v_mfma_f32_16x16x32_bf16 v[54:57], v[184:187], v[206:209], v[54:57]
	v_mfma_f32_16x16x32_bf16 v[54:57], v[180:183], v[202:205], v[54:57]
	s_barrier
	s_add_i32 s52, 0, 0x18000
	v_add_u32_e32 v166, s52, v153
	s_add_i32 s53, 0, 0x1c000
	ds_read_b128 v[142:145], v166
	ds_read_b128 v[158:161], v166 offset:1024
	ds_read_b128 v[168:171], v166 offset:2048
	ds_read_b128 v[176:179], v166 offset:3072
	v_add_u32_e32 v166, s53, v153
	ds_read_b128 v[180:183], v166
	ds_read_b128 v[184:187], v166 offset:1024
	ds_read_b128 v[188:191], v166 offset:2048
	ds_read_b128 v[192:195], v166 offset:3072
	s_add_u32 s26, s26, 0x100000
	s_addc_u32 s27, s27, 0
	s_mov_b32 m0, s35
	ds_read_b128 v[202:205], v157 offset:32768
	ds_read_b128 v[206:209], v157 offset:33792
	ds_read_b128 v[210:213], v157 offset:34816
	ds_read_b128 v[214:217], v157 offset:35840
	ds_read_b128 v[218:221], v157 offset:36864
	ds_read_b128 v[222:225], v157 offset:37888
	ds_read_b128 v[226:229], v157 offset:38912
	ds_read_b128 v[230:233], v157 offset:39936
	global_load_lds_dwordx4 v130, s[26:27]
	s_mov_b32 m0, s36
	s_nop 0
	global_load_lds_dwordx4 v134, s[26:27]
	s_waitcnt vmcnt(8)
	s_waitcnt lgkmcnt(0)
	s_barrier
	v_mfma_f32_16x16x32_bf16 v[126:129], v[142:145], v[202:205], v[126:129]
	v_mfma_f32_16x16x32_bf16 v[126:129], v[158:161], v[206:209], v[126:129]
	v_mfma_f32_16x16x32_bf16 v[122:125], v[176:179], v[206:209], v[122:125]
	v_mfma_f32_16x16x32_bf16 v[122:125], v[168:171], v[202:205], v[122:125]
	v_mfma_f32_16x16x32_bf16 v[106:109], v[168:171], v[210:213], v[106:109]
	v_mfma_f32_16x16x32_bf16 v[106:109], v[176:179], v[214:217], v[106:109]
	v_mfma_f32_16x16x32_bf16 v[110:113], v[158:161], v[214:217], v[110:113]
	v_mfma_f32_16x16x32_bf16 v[110:113], v[142:145], v[210:213], v[110:113]
	v_mfma_f32_16x16x32_bf16 v[94:97], v[142:145], v[218:221], v[94:97]
	v_mfma_f32_16x16x32_bf16 v[94:97], v[158:161], v[222:225], v[94:97]
	v_mfma_f32_16x16x32_bf16 v[90:93], v[176:179], v[222:225], v[90:93]
	v_mfma_f32_16x16x32_bf16 v[90:93], v[168:171], v[218:221], v[90:93]
	v_mfma_f32_16x16x32_bf16 v[74:77], v[168:171], v[226:229], v[74:77]
	v_mfma_f32_16x16x32_bf16 v[74:77], v[176:179], v[230:233], v[74:77]
	v_mfma_f32_16x16x32_bf16 v[78:81], v[158:161], v[230:233], v[78:81]
	v_mfma_f32_16x16x32_bf16 v[78:81], v[142:145], v[226:229], v[78:81]
	v_mfma_f32_16x16x32_bf16 v[70:73], v[180:183], v[226:229], v[70:73]
	v_mfma_f32_16x16x32_bf16 v[70:73], v[184:187], v[230:233], v[70:73]
	v_mfma_f32_16x16x32_bf16 v[66:69], v[192:195], v[230:233], v[66:69]
	v_mfma_f32_16x16x32_bf16 v[66:69], v[188:191], v[226:229], v[66:69]
	v_mfma_f32_16x16x32_bf16 v[82:85], v[188:191], v[218:221], v[82:85]
	v_mfma_f32_16x16x32_bf16 v[82:85], v[192:195], v[222:225], v[82:85]
	v_mfma_f32_16x16x32_bf16 v[86:89], v[184:187], v[222:225], v[86:89]
	v_mfma_f32_16x16x32_bf16 v[86:89], v[180:183], v[218:221], v[86:89]
	v_mfma_f32_16x16x32_bf16 v[102:105], v[180:183], v[210:213], v[102:105]
	v_mfma_f32_16x16x32_bf16 v[102:105], v[184:187], v[214:217], v[102:105]
	v_mfma_f32_16x16x32_bf16 v[98:101], v[192:195], v[214:217], v[98:101]
	v_mfma_f32_16x16x32_bf16 v[98:101], v[188:191], v[210:213], v[98:101]
	v_mfma_f32_16x16x32_bf16 v[114:117], v[188:191], v[202:205], v[114:117]
	v_mfma_f32_16x16x32_bf16 v[114:117], v[192:195], v[206:209], v[114:117]
	v_mfma_f32_16x16x32_bf16 v[118:121], v[184:187], v[206:209], v[118:121]
	v_mfma_f32_16x16x32_bf16 v[118:121], v[180:183], v[202:205], v[118:121]
	s_barrier
	s_add_u32 s98, s26, 0xfff00080
	s_addc_u32 s99, s27, -1
	s_add_u32 s24, s24, 0x80
	s_addc_u32 s25, s25, 0
	s_add_i32 s26, s52, s30
	s_mov_b32 m0, s26
	ds_read_b128 v[202:205], v157 offset:49152
	ds_read_b128 v[206:209], v157 offset:50176
	ds_read_b128 v[210:213], v157 offset:51200
	ds_read_b128 v[214:217], v157 offset:52224
	ds_read_b128 v[218:221], v157 offset:53248
	ds_read_b128 v[222:225], v157 offset:54272
	ds_read_b128 v[226:229], v157 offset:55296
	ds_read_b128 v[230:233], v157 offset:56320
	global_load_lds_dwordx4 v132, s[24:25]
	s_add_i32 m0, s26, 0x2000
	s_add_i32 s26, s53, s30
	global_load_lds_dwordx4 v136, s[24:25]
	s_add_u32 s24, s24, 0x100000
	s_addc_u32 s25, s25, 0
	s_mov_b32 m0, s26
	s_nop 0
	global_load_lds_dwordx4 v132, s[24:25]
	s_add_i32 m0, s26, 0x2000
	s_nop 0
	global_load_lds_dwordx4 v136, s[24:25]
	s_mov_b32 m0, s38
	s_nop 0
	global_load_lds_dwordx4 v130, s[98:99]
	s_mov_b32 m0, s39
	s_nop 0
	global_load_lds_dwordx4 v134, s[98:99]
	s_waitcnt vmcnt(8)
	s_waitcnt lgkmcnt(0)
	s_barrier
	v_mfma_f32_16x16x32_bf16 v[62:65], v[142:145], v[202:205], v[62:65]
	v_mfma_f32_16x16x32_bf16 v[62:65], v[158:161], v[206:209], v[62:65]
	v_mfma_f32_16x16x32_bf16 v[58:61], v[176:179], v[206:209], v[58:61]
	v_mfma_f32_16x16x32_bf16 v[58:61], v[168:171], v[202:205], v[58:61]
	v_mfma_f32_16x16x32_bf16 v[42:45], v[168:171], v[210:213], v[42:45]
	v_mfma_f32_16x16x32_bf16 v[42:45], v[176:179], v[214:217], v[42:45]
	v_mfma_f32_16x16x32_bf16 v[46:49], v[158:161], v[214:217], v[46:49]
	v_mfma_f32_16x16x32_bf16 v[46:49], v[142:145], v[210:213], v[46:49]
	v_mfma_f32_16x16x32_bf16 v[30:33], v[142:145], v[218:221], v[30:33]
	v_mfma_f32_16x16x32_bf16 v[30:33], v[158:161], v[222:225], v[30:33]
	v_mfma_f32_16x16x32_bf16 v[26:29], v[176:179], v[222:225], v[26:29]
	v_mfma_f32_16x16x32_bf16 v[26:29], v[168:171], v[218:221], v[26:29]
	v_mfma_f32_16x16x32_bf16 v[10:13], v[168:171], v[226:229], v[10:13]
	v_mfma_f32_16x16x32_bf16 v[10:13], v[176:179], v[230:233], v[10:13]
	v_mfma_f32_16x16x32_bf16 v[14:17], v[158:161], v[230:233], v[14:17]
	v_mfma_f32_16x16x32_bf16 v[14:17], v[142:145], v[226:229], v[14:17]
	v_mfma_f32_16x16x32_bf16 v[6:9], v[180:183], v[226:229], v[6:9]
	v_mfma_f32_16x16x32_bf16 v[6:9], v[184:187], v[230:233], v[6:9]
	v_mfma_f32_16x16x32_bf16 v[2:5], v[192:195], v[230:233], v[2:5]
	v_mfma_f32_16x16x32_bf16 v[2:5], v[188:191], v[226:229], v[2:5]
	v_mfma_f32_16x16x32_bf16 v[18:21], v[188:191], v[218:221], v[18:21]
	v_mfma_f32_16x16x32_bf16 v[18:21], v[192:195], v[222:225], v[18:21]
	v_mfma_f32_16x16x32_bf16 v[22:25], v[184:187], v[222:225], v[22:25]
	v_mfma_f32_16x16x32_bf16 v[22:25], v[180:183], v[218:221], v[22:25]
	v_mfma_f32_16x16x32_bf16 v[38:41], v[180:183], v[210:213], v[38:41]
	v_mfma_f32_16x16x32_bf16 v[38:41], v[184:187], v[214:217], v[38:41]
	v_mfma_f32_16x16x32_bf16 v[34:37], v[192:195], v[214:217], v[34:37]
	v_mfma_f32_16x16x32_bf16 v[34:37], v[188:191], v[210:213], v[34:37]
	v_mfma_f32_16x16x32_bf16 v[50:53], v[188:191], v[202:205], v[50:53]
	v_mfma_f32_16x16x32_bf16 v[50:53], v[192:195], v[206:209], v[50:53]
	v_mfma_f32_16x16x32_bf16 v[54:57], v[184:187], v[206:209], v[54:57]
	v_mfma_f32_16x16x32_bf16 v[54:57], v[180:183], v[202:205], v[54:57]
	s_barrier
	s_add_i32 s51, s51, 2
	s_add_u32 s22, s22, 0x100
	s_addc_u32 s23, s23, 0
	s_add_u32 s49, s49, 0x100
	s_addc_u32 s50, s50, 0
	s_cmp_gt_u32 s51, 61
	s_cbranch_scc0 .LBB0_1009
	s_and_b64 vcc, exec, s[16:17]
	s_cbranch_vccz .LBB0_1012
	s_barrier

.LBB0_1019:
	s_add_i32 s21, s20, 0x100
	s_and_b64 s[18:19], s[18:19], exec
	s_cselect_b32 s19, 0, s21
	s_cselect_b32 s18, 0, 0
	s_add_u32 s22, s8, s19
	s_addc_u32 s23, s9, s18
	ds_read_b128 v[144:147], v139
	ds_read_b128 v[150:153], v139 offset:1024
	ds_read_b128 v[154:157], v139 offset:2048
	ds_read_b128 v[158:161], v139 offset:3072
	ds_read_b128 v[168:171], v140
	ds_read_b128 v[176:179], v140 offset:1024
	ds_read_b128 v[180:183], v140 offset:2048
	ds_read_b128 v[184:187], v140 offset:3072
	s_add_u32 s24, s10, s19
	s_addc_u32 s25, s11, s18
	s_add_u32 s30, s12, s20
	s_addc_u32 s31, s13, 0
	s_add_u32 s26, s24, 0x100000
	s_addc_u32 s27, s25, 0
	s_add_u32 s20, s22, 0x100000
	s_addc_u32 s21, s23, 0
	s_add_u32 s18, s24, 0x100080
	s_addc_u32 s19, s25, 0
	v_lshl_add_u64 v[172:173], s[30:31], 0, v[130:131]
	s_mov_b32 m0, s40
	v_lshl_add_u64 v[172:173], v[172:173], 0, s[14:15]
	ds_read_b128 v[188:191], v141
	ds_read_b128 v[192:195], v141 offset:1024
	ds_read_b128 v[202:205], v141 offset:2048
	ds_read_b128 v[206:209], v141 offset:3072
	ds_read_b128 v[210:213], v141 offset:4096
	ds_read_b128 v[214:217], v141 offset:5120
	ds_read_b128 v[218:221], v141 offset:6144
	ds_read_b128 v[222:225], v141 offset:7168
	global_load_lds_dwordx4 v[172:173], off
	v_lshl_add_u64 v[172:173], s[30:31], 0, v[134:135]
	v_lshl_add_u64 v[172:173], v[172:173], 0, s[14:15]
	s_mov_b32 m0, s41
	s_nop 0
	global_load_lds_dwordx4 v[172:173], off
	s_waitcnt vmcnt(8)
	s_waitcnt lgkmcnt(0)
	s_barrier
	v_mfma_f32_16x16x32_bf16 v[126:129], v[144:147], v[188:191], v[126:129]
	v_mfma_f32_16x16x32_bf16 v[126:129], v[150:153], v[192:195], v[126:129]
	v_mfma_f32_16x16x32_bf16 v[122:125], v[158:161], v[192:195], v[122:125]
	v_mfma_f32_16x16x32_bf16 v[122:125], v[154:157], v[188:191], v[122:125]
	v_mfma_f32_16x16x32_bf16 v[114:117], v[154:157], v[202:205], v[114:117]
	v_mfma_f32_16x16x32_bf16 v[114:117], v[158:161], v[206:209], v[114:117]
	v_mfma_f32_16x16x32_bf16 v[118:121], v[150:153], v[206:209], v[118:121]
	v_mfma_f32_16x16x32_bf16 v[118:121], v[144:147], v[202:205], v[118:121]
	v_mfma_f32_16x16x32_bf16 v[102:105], v[144:147], v[210:213], v[102:105]
	v_mfma_f32_16x16x32_bf16 v[102:105], v[150:153], v[214:217], v[102:105]
	v_mfma_f32_16x16x32_bf16 v[98:101], v[158:161], v[214:217], v[98:101]
	v_mfma_f32_16x16x32_bf16 v[98:101], v[154:157], v[210:213], v[98:101]
	v_mfma_f32_16x16x32_bf16 v[82:85], v[154:157], v[218:221], v[82:85]
	v_mfma_f32_16x16x32_bf16 v[82:85], v[158:161], v[222:225], v[82:85]
	v_mfma_f32_16x16x32_bf16 v[86:89], v[150:153], v[222:225], v[86:89]
	v_mfma_f32_16x16x32_bf16 v[86:89], v[144:147], v[218:221], v[86:89]
	v_mfma_f32_16x16x32_bf16 v[70:73], v[168:171], v[218:221], v[70:73]
	v_mfma_f32_16x16x32_bf16 v[70:73], v[176:179], v[222:225], v[70:73]
	v_mfma_f32_16x16x32_bf16 v[66:69], v[184:187], v[222:225], v[66:69]
	v_mfma_f32_16x16x32_bf16 v[66:69], v[180:183], v[218:221], v[66:69]
	v_mfma_f32_16x16x32_bf16 v[74:77], v[180:183], v[210:213], v[74:77]
	v_mfma_f32_16x16x32_bf16 v[74:77], v[184:187], v[214:217], v[74:77]
	v_mfma_f32_16x16x32_bf16 v[78:81], v[176:179], v[214:217], v[78:81]
	v_mfma_f32_16x16x32_bf16 v[78:81], v[168:171], v[210:213], v[78:81]
	v_mfma_f32_16x16x32_bf16 v[94:97], v[168:171], v[202:205], v[94:97]
	v_mfma_f32_16x16x32_bf16 v[94:97], v[176:179], v[206:209], v[94:97]
	v_mfma_f32_16x16x32_bf16 v[90:93], v[184:187], v[206:209], v[90:93]
	v_mfma_f32_16x16x32_bf16 v[90:93], v[180:183], v[202:205], v[90:93]
	v_mfma_f32_16x16x32_bf16 v[106:109], v[180:183], v[188:191], v[106:109]
	v_mfma_f32_16x16x32_bf16 v[106:109], v[184:187], v[192:195], v[106:109]
	v_mfma_f32_16x16x32_bf16 v[110:113], v[176:179], v[192:195], v[110:113]
	v_mfma_f32_16x16x32_bf16 v[110:113], v[168:171], v[188:191], v[110:113]
	s_barrier
	s_mov_b32 m0, s42
	v_lshl_add_u64 v[172:173], s[24:25], 0, v[132:133]
	ds_read_b128 v[188:191], v141 offset:16384
	ds_read_b128 v[192:195], v141 offset:17408
	ds_read_b128 v[202:205], v141 offset:18432
	ds_read_b128 v[206:209], v141 offset:19456
	ds_read_b128 v[210:213], v141 offset:20480
	ds_read_b128 v[214:217], v141 offset:21504
	ds_read_b128 v[218:221], v141 offset:22528
	ds_read_b128 v[222:225], v141 offset:23552
	global_load_lds_dwordx4 v[172:173], off
	v_lshl_add_u64 v[196:197], s[24:25], 0, v[136:137]
	s_mov_b32 m0, s43
	v_lshl_add_u64 v[226:227], s[26:27], 0, v[132:133]
	global_load_lds_dwordx4 v[196:197], off
	s_mov_b32 m0, s44
	v_lshl_add_u64 v[228:229], s[22:23], 0, v[134:135]
	global_load_lds_dwordx4 v[226:227], off
	v_lshl_add_u64 v[226:227], s[26:27], 0, v[136:137]
	s_mov_b32 m0, s45
	s_nop 0
	global_load_lds_dwordx4 v[226:227], off
	v_lshl_add_u64 v[226:227], s[22:23], 0, v[130:131]
	s_mov_b32 m0, s7
	s_nop 0
	global_load_lds_dwordx4 v[226:227], off
	s_mov_b32 m0, s34
	s_nop 0
	global_load_lds_dwordx4 v[228:229], off
	s_waitcnt vmcnt(8)
	s_waitcnt lgkmcnt(0)
	s_barrier
	v_mfma_f32_16x16x32_bf16 v[62:65], v[144:147], v[188:191], v[62:65]
	v_mfma_f32_16x16x32_bf16 v[62:65], v[150:153], v[192:195], v[62:65]
	v_mfma_f32_16x16x32_bf16 v[58:61], v[158:161], v[192:195], v[58:61]
	v_mfma_f32_16x16x32_bf16 v[58:61], v[154:157], v[188:191], v[58:61]
	v_mfma_f32_16x16x32_bf16 v[50:53], v[154:157], v[202:205], v[50:53]
	v_mfma_f32_16x16x32_bf16 v[50:53], v[158:161], v[206:209], v[50:53]
	v_mfma_f32_16x16x32_bf16 v[54:57], v[150:153], v[206:209], v[54:57]
	v_mfma_f32_16x16x32_bf16 v[54:57], v[144:147], v[202:205], v[54:57]
	v_mfma_f32_16x16x32_bf16 v[38:41], v[144:147], v[210:213], v[38:41]
	v_mfma_f32_16x16x32_bf16 v[38:41], v[150:153], v[214:217], v[38:41]
	v_mfma_f32_16x16x32_bf16 v[34:37], v[158:161], v[214:217], v[34:37]
	v_mfma_f32_16x16x32_bf16 v[34:37], v[154:157], v[210:213], v[34:37]
	v_mfma_f32_16x16x32_bf16 v[18:21], v[154:157], v[218:221], v[18:21]
	v_mfma_f32_16x16x32_bf16 v[18:21], v[158:161], v[222:225], v[18:21]
	v_mfma_f32_16x16x32_bf16 v[22:25], v[150:153], v[222:225], v[22:25]
	v_mfma_f32_16x16x32_bf16 v[22:25], v[144:147], v[218:221], v[22:25]
	v_mfma_f32_16x16x32_bf16 v[6:9], v[168:171], v[218:221], v[6:9]
	v_mfma_f32_16x16x32_bf16 v[6:9], v[176:179], v[222:225], v[6:9]
	v_mfma_f32_16x16x32_bf16 v[2:5], v[184:187], v[222:225], v[2:5]
	v_mfma_f32_16x16x32_bf16 v[2:5], v[180:183], v[218:221], v[2:5]
	v_mfma_f32_16x16x32_bf16 v[10:13], v[180:183], v[210:213], v[10:13]
	v_mfma_f32_16x16x32_bf16 v[10:13], v[184:187], v[214:217], v[10:13]
	v_mfma_f32_16x16x32_bf16 v[14:17], v[176:179], v[214:217], v[14:17]
	v_mfma_f32_16x16x32_bf16 v[14:17], v[168:171], v[210:213], v[14:17]
	v_mfma_f32_16x16x32_bf16 v[30:33], v[168:171], v[202:205], v[30:33]
	v_mfma_f32_16x16x32_bf16 v[30:33], v[176:179], v[206:209], v[30:33]
	v_mfma_f32_16x16x32_bf16 v[26:29], v[184:187], v[206:209], v[26:29]
	v_mfma_f32_16x16x32_bf16 v[26:29], v[180:183], v[202:205], v[26:29]
	v_mfma_f32_16x16x32_bf16 v[42:45], v[180:183], v[188:191], v[42:45]
	v_mfma_f32_16x16x32_bf16 v[42:45], v[184:187], v[192:195], v[42:45]
	v_mfma_f32_16x16x32_bf16 v[46:49], v[176:179], v[192:195], v[46:49]
	v_mfma_f32_16x16x32_bf16 v[46:49], v[168:171], v[188:191], v[46:49]
	s_barrier
	ds_read_b128 v[144:147], v142
	ds_read_b128 v[150:153], v142 offset:1024
	ds_read_b128 v[154:157], v142 offset:2048
	ds_read_b128 v[158:161], v142 offset:3072
	ds_read_b128 v[168:171], v143
	ds_read_b128 v[176:179], v143 offset:1024
	ds_read_b128 v[180:183], v143 offset:2048
	ds_read_b128 v[184:187], v143 offset:3072
	s_mov_b32 m0, s35
	v_lshl_add_u64 v[230:231], s[20:21], 0, v[130:131]
	ds_read_b128 v[188:191], v141 offset:32768
	ds_read_b128 v[192:195], v141 offset:33792
	ds_read_b128 v[202:205], v141 offset:34816
	ds_read_b128 v[206:209], v141 offset:35840
	ds_read_b128 v[210:213], v141 offset:36864
	ds_read_b128 v[214:217], v141 offset:37888
	ds_read_b128 v[218:221], v141 offset:38912
	ds_read_b128 v[222:225], v141 offset:39936
	global_load_lds_dwordx4 v[230:231], off
	v_lshl_add_u64 v[230:231], s[20:21], 0, v[134:135]
	s_mov_b32 m0, s36
	s_nop 0
	global_load_lds_dwordx4 v[230:231], off
	s_waitcnt vmcnt(8)
	s_waitcnt lgkmcnt(0)
	s_barrier
	v_mfma_f32_16x16x32_bf16 v[126:129], v[144:147], v[188:191], v[126:129]
	v_mfma_f32_16x16x32_bf16 v[126:129], v[150:153], v[192:195], v[126:129]
	v_mfma_f32_16x16x32_bf16 v[122:125], v[158:161], v[192:195], v[122:125]
	v_mfma_f32_16x16x32_bf16 v[122:125], v[154:157], v[188:191], v[122:125]
	v_mfma_f32_16x16x32_bf16 v[114:117], v[154:157], v[202:205], v[114:117]
	v_mfma_f32_16x16x32_bf16 v[114:117], v[158:161], v[206:209], v[114:117]
	v_mfma_f32_16x16x32_bf16 v[118:121], v[150:153], v[206:209], v[118:121]
	v_mfma_f32_16x16x32_bf16 v[118:121], v[144:147], v[202:205], v[118:121]
	v_mfma_f32_16x16x32_bf16 v[102:105], v[144:147], v[210:213], v[102:105]
	v_mfma_f32_16x16x32_bf16 v[102:105], v[150:153], v[214:217], v[102:105]
	v_mfma_f32_16x16x32_bf16 v[98:101], v[158:161], v[214:217], v[98:101]
	v_mfma_f32_16x16x32_bf16 v[98:101], v[154:157], v[210:213], v[98:101]
	v_mfma_f32_16x16x32_bf16 v[82:85], v[154:157], v[218:221], v[82:85]
	v_mfma_f32_16x16x32_bf16 v[82:85], v[158:161], v[222:225], v[82:85]
	v_mfma_f32_16x16x32_bf16 v[86:89], v[150:153], v[222:225], v[86:89]
	v_mfma_f32_16x16x32_bf16 v[86:89], v[144:147], v[218:221], v[86:89]
	v_mfma_f32_16x16x32_bf16 v[70:73], v[168:171], v[218:221], v[70:73]
	v_mfma_f32_16x16x32_bf16 v[70:73], v[176:179], v[222:225], v[70:73]
	v_mfma_f32_16x16x32_bf16 v[66:69], v[184:187], v[222:225], v[66:69]
	v_mfma_f32_16x16x32_bf16 v[66:69], v[180:183], v[218:221], v[66:69]
	v_mfma_f32_16x16x32_bf16 v[74:77], v[180:183], v[210:213], v[74:77]
	v_mfma_f32_16x16x32_bf16 v[74:77], v[184:187], v[214:217], v[74:77]
	v_mfma_f32_16x16x32_bf16 v[78:81], v[176:179], v[214:217], v[78:81]
	v_mfma_f32_16x16x32_bf16 v[78:81], v[168:171], v[210:213], v[78:81]
	v_mfma_f32_16x16x32_bf16 v[94:97], v[168:171], v[202:205], v[94:97]
	v_mfma_f32_16x16x32_bf16 v[94:97], v[176:179], v[206:209], v[94:97]
	v_mfma_f32_16x16x32_bf16 v[90:93], v[184:187], v[206:209], v[90:93]
	v_mfma_f32_16x16x32_bf16 v[90:93], v[180:183], v[202:205], v[90:93]
	v_mfma_f32_16x16x32_bf16 v[106:109], v[180:183], v[188:191], v[106:109]
	v_mfma_f32_16x16x32_bf16 v[106:109], v[184:187], v[192:195], v[106:109]
	v_mfma_f32_16x16x32_bf16 v[110:113], v[176:179], v[192:195], v[110:113]
	v_mfma_f32_16x16x32_bf16 v[110:113], v[168:171], v[188:191], v[110:113]
	s_barrier
	s_mov_b32 m0, s46
	v_lshl_add_u64 v[172:173], v[172:173], 0, s[14:15]
	ds_read_b128 v[188:191], v141 offset:49152
	ds_read_b128 v[192:195], v141 offset:50176
	ds_read_b128 v[202:205], v141 offset:51200
	ds_read_b128 v[206:209], v141 offset:52224
	ds_read_b128 v[210:213], v141 offset:53248
	ds_read_b128 v[214:217], v141 offset:54272
	ds_read_b128 v[218:221], v141 offset:55296
	ds_read_b128 v[222:225], v141 offset:56320
	global_load_lds_dwordx4 v[172:173], off
	v_lshl_add_u64 v[172:173], v[196:197], 0, s[14:15]
	s_mov_b32 m0, s47
	s_nop 0
	global_load_lds_dwordx4 v[172:173], off
	v_lshl_add_u64 v[172:173], s[18:19], 0, v[132:133]
	s_mov_b32 m0, s48
	s_nop 0
	global_load_lds_dwordx4 v[172:173], off
	v_lshl_add_u64 v[172:173], s[18:19], 0, v[136:137]
	s_mov_b32 m0, s49
	s_nop 0
	global_load_lds_dwordx4 v[172:173], off
	v_lshl_add_u64 v[172:173], v[226:227], 0, s[14:15]
	s_mov_b32 m0, s38
	s_nop 0
	global_load_lds_dwordx4 v[172:173], off
	v_lshl_add_u64 v[172:173], v[228:229], 0, s[14:15]
	s_mov_b32 m0, s39
	s_nop 0
	global_load_lds_dwordx4 v[172:173], off
	s_waitcnt vmcnt(8)
	s_waitcnt lgkmcnt(0)
	s_barrier
	v_mfma_f32_16x16x32_bf16 v[62:65], v[144:147], v[188:191], v[62:65]
	v_mfma_f32_16x16x32_bf16 v[62:65], v[150:153], v[192:195], v[62:65]
	v_mfma_f32_16x16x32_bf16 v[58:61], v[158:161], v[192:195], v[58:61]
	v_mfma_f32_16x16x32_bf16 v[58:61], v[154:157], v[188:191], v[58:61]
	v_mfma_f32_16x16x32_bf16 v[50:53], v[154:157], v[202:205], v[50:53]
	v_mfma_f32_16x16x32_bf16 v[50:53], v[158:161], v[206:209], v[50:53]
	v_mfma_f32_16x16x32_bf16 v[54:57], v[150:153], v[206:209], v[54:57]
	v_mfma_f32_16x16x32_bf16 v[54:57], v[144:147], v[202:205], v[54:57]
	v_mfma_f32_16x16x32_bf16 v[38:41], v[144:147], v[210:213], v[38:41]
	v_mfma_f32_16x16x32_bf16 v[38:41], v[150:153], v[214:217], v[38:41]
	v_mfma_f32_16x16x32_bf16 v[34:37], v[158:161], v[214:217], v[34:37]
	v_mfma_f32_16x16x32_bf16 v[34:37], v[154:157], v[210:213], v[34:37]
	v_mfma_f32_16x16x32_bf16 v[18:21], v[154:157], v[218:221], v[18:21]
	v_mfma_f32_16x16x32_bf16 v[18:21], v[158:161], v[222:225], v[18:21]
	v_mfma_f32_16x16x32_bf16 v[22:25], v[150:153], v[222:225], v[22:25]
	v_mfma_f32_16x16x32_bf16 v[22:25], v[144:147], v[218:221], v[22:25]
	v_mfma_f32_16x16x32_bf16 v[6:9], v[168:171], v[218:221], v[6:9]
	v_mfma_f32_16x16x32_bf16 v[6:9], v[176:179], v[222:225], v[6:9]
	v_mfma_f32_16x16x32_bf16 v[2:5], v[184:187], v[222:225], v[2:5]
	v_mfma_f32_16x16x32_bf16 v[2:5], v[180:183], v[218:221], v[2:5]
	v_mfma_f32_16x16x32_bf16 v[10:13], v[180:183], v[210:213], v[10:13]
	v_mfma_f32_16x16x32_bf16 v[10:13], v[184:187], v[214:217], v[10:13]
	v_mfma_f32_16x16x32_bf16 v[14:17], v[176:179], v[214:217], v[14:17]
	v_mfma_f32_16x16x32_bf16 v[14:17], v[168:171], v[210:213], v[14:17]
	v_mfma_f32_16x16x32_bf16 v[30:33], v[168:171], v[202:205], v[30:33]
	v_mfma_f32_16x16x32_bf16 v[30:33], v[176:179], v[206:209], v[30:33]
	v_mfma_f32_16x16x32_bf16 v[26:29], v[184:187], v[206:209], v[26:29]
	v_mfma_f32_16x16x32_bf16 v[26:29], v[180:183], v[202:205], v[26:29]
	v_mfma_f32_16x16x32_bf16 v[42:45], v[180:183], v[188:191], v[42:45]
	v_mfma_f32_16x16x32_bf16 v[42:45], v[184:187], v[192:195], v[42:45]
	v_mfma_f32_16x16x32_bf16 v[46:49], v[176:179], v[192:195], v[46:49]
	v_mfma_f32_16x16x32_bf16 v[46:49], v[168:171], v[188:191], v[46:49]
	s_barrier
	s_andn2_b64 vcc, exec, s[16:17]
	s_mov_b64 s[18:19], -1
	s_mov_b64 s[16:17], 0
	s_movk_i32 s20, 0x100
	s_cbranch_vccz .LBB0_1019
	s_lshl_b32 s7, s33, 21
	v_readlane_b32 s0, v249, 29
	v_lshl_or_b32 v130, s6, 8, v148
	v_mov_b32_e32 v139, 0
	s_add_u32 s8, s0, s7
	v_readlane_b32 s0, v249, 31
	v_or_b32_e32 v130, s37, v130
	v_cvt_pk_bf16_f32 v70, v70, v71
	v_cvt_pk_bf16_f32 v71, v72, v73
	v_cvt_pk_bf16_f32 v72, v66, v67
	v_add_u32_e32 v66, 0x80, v138
	v_mov_b32_e32 v67, v139
	s_addc_u32 s9, s0, 0
	v_ashrrev_i32_e32 v131, 31, v130
	v_lshlrev_b64 v[132:133], 13, v[138:139]
	v_cvt_pk_bf16_f32 v110, v110, v111
	v_cvt_pk_bf16_f32 v111, v112, v113
	v_cvt_pk_bf16_f32 v112, v106, v107
	v_or_b32_e32 v106, 16, v138
	v_mov_b32_e32 v107, v139
	v_lshlrev_b64 v[66:67], 13, v[66:67]
	v_cvt_pk_bf16_f32 v46, v46, v47
	v_cvt_pk_bf16_f32 v47, v48, v49
	v_cvt_pk_bf16_f32 v48, v42, v43
	v_add_u32_e32 v42, 0x90, v138
	v_mov_b32_e32 v43, v139
	v_lshl_add_u64 v[132:133], s[8:9], 0, v[132:133]
	v_lshlrev_b64 v[130:131], 1, v[130:131]
	v_lshlrev_b64 v[106:107], 13, v[106:107]
	v_cvt_pk_bf16_f32 v94, v94, v95
	v_cvt_pk_bf16_f32 v95, v96, v97
	v_cvt_pk_bf16_f32 v96, v90, v91
	v_or_b32_e32 v90, 32, v138
	v_mov_b32_e32 v91, v139
	v_lshl_add_u64 v[66:67], s[8:9], 0, v[66:67]
	v_lshlrev_b64 v[42:43], 13, v[42:43]
	v_cvt_pk_bf16_f32 v30, v30, v31
	v_cvt_pk_bf16_f32 v31, v32, v33
	v_cvt_pk_bf16_f32 v32, v26, v27
	v_add_u32_e32 v26, 0xa0, v138
	v_mov_b32_e32 v27, v139
	v_lshl_add_u64 v[132:133], v[132:133], 0, v[130:131]
	v_cvt_pk_bf16_f32 v113, v108, v109
	v_lshl_add_u64 v[106:107], s[8:9], 0, v[106:107]
	v_lshlrev_b64 v[90:91], 13, v[90:91]
	v_cvt_pk_bf16_f32 v78, v78, v79
	v_cvt_pk_bf16_f32 v79, v80, v81
	v_cvt_pk_bf16_f32 v80, v74, v75
	v_or_b32_e32 v74, 48, v138
	v_mov_b32_e32 v75, v139
	v_lshl_add_u64 v[66:67], v[66:67], 0, v[130:131]
	v_cvt_pk_bf16_f32 v49, v44, v45
	v_lshl_add_u64 v[42:43], s[8:9], 0, v[42:43]
	v_lshlrev_b64 v[26:27], 13, v[26:27]
	v_add_u32_e32 v138, 0xb0, v138
	global_store_dwordx4 v[132:133], v[110:113], off offset:256
	v_cvt_pk_bf16_f32 v97, v92, v93
	v_lshl_add_u64 v[90:91], s[8:9], 0, v[90:91]
	v_lshl_add_u64 v[110:111], v[106:107], 0, v[130:131]
	v_lshlrev_b64 v[74:75], 13, v[74:75]
	global_store_dwordx4 v[66:67], v[46:49], off offset:256
	v_cvt_pk_bf16_f32 v33, v28, v29
	v_lshl_add_u64 v[26:27], s[8:9], 0, v[26:27]
	v_lshl_add_u64 v[46:47], v[42:43], 0, v[130:131]
	v_cvt_pk_bf16_f32 v14, v14, v15
	v_cvt_pk_bf16_f32 v15, v16, v17
	v_cvt_pk_bf16_f32 v16, v10, v11
	v_lshlrev_b64 v[10:11], 13, v[138:139]
	global_store_dwordx4 v[110:111], v[94:97], off offset:256
	v_cvt_pk_bf16_f32 v81, v76, v77
	v_lshl_add_u64 v[74:75], s[8:9], 0, v[74:75]
	v_lshl_add_u64 v[94:95], v[90:91], 0, v[130:131]
	global_store_dwordx4 v[46:47], v[30:33], off offset:256
	v_cvt_pk_bf16_f32 v17, v12, v13
	v_lshl_add_u64 v[10:11], s[8:9], 0, v[10:11]
	v_lshl_add_u64 v[30:31], v[26:27], 0, v[130:131]
	v_cvt_pk_bf16_f32 v126, v126, v127
	v_cvt_pk_bf16_f32 v127, v128, v129
	v_cvt_pk_bf16_f32 v128, v122, v123
	v_cvt_pk_bf16_f32 v129, v124, v125
	v_cvt_pk_bf16_f32 v106, v118, v119
	v_cvt_pk_bf16_f32 v107, v120, v121
	v_cvt_pk_bf16_f32 v108, v114, v115
	v_cvt_pk_bf16_f32 v109, v116, v117
	v_cvt_pk_bf16_f32 v90, v102, v103
	v_cvt_pk_bf16_f32 v91, v104, v105
	v_cvt_pk_bf16_f32 v92, v98, v99
	v_cvt_pk_bf16_f32 v93, v100, v101
	global_store_dwordx4 v[94:95], v[78:81], off offset:256
	v_cvt_pk_bf16_f32 v76, v82, v83
	v_cvt_pk_bf16_f32 v77, v84, v85
	v_lshl_add_u64 v[78:79], v[74:75], 0, v[130:131]
	v_cvt_pk_bf16_f32 v74, v86, v87
	v_cvt_pk_bf16_f32 v75, v88, v89
	v_cvt_pk_bf16_f32 v73, v68, v69
	v_cvt_pk_bf16_f32 v62, v62, v63
	v_cvt_pk_bf16_f32 v63, v64, v65
	v_cvt_pk_bf16_f32 v64, v58, v59
	v_cvt_pk_bf16_f32 v65, v60, v61
	v_cvt_pk_bf16_f32 v42, v54, v55
	v_cvt_pk_bf16_f32 v43, v56, v57
	v_cvt_pk_bf16_f32 v44, v50, v51
	v_cvt_pk_bf16_f32 v45, v52, v53
	v_cvt_pk_bf16_f32 v26, v38, v39
	v_cvt_pk_bf16_f32 v27, v40, v41
	v_cvt_pk_bf16_f32 v28, v34, v35
	v_cvt_pk_bf16_f32 v29, v36, v37
	global_store_dwordx4 v[30:31], v[14:17], off offset:256
	v_cvt_pk_bf16_f32 v12, v18, v19
	v_cvt_pk_bf16_f32 v13, v20, v21
	v_lshl_add_u64 v[14:15], v[10:11], 0, v[130:131]
	v_cvt_pk_bf16_f32 v10, v22, v23
	v_cvt_pk_bf16_f32 v11, v24, v25
	v_cvt_pk_bf16_f32 v6, v6, v7
	v_cvt_pk_bf16_f32 v7, v8, v9
	v_cvt_pk_bf16_f32 v8, v2, v3
	v_cvt_pk_bf16_f32 v9, v4, v5
	global_store_dwordx4 v[132:133], v[126:129], off
	global_store_dwordx4 v[110:111], v[106:109], off
	global_store_dwordx4 v[94:95], v[90:93], off
	global_store_dwordx4 v[78:79], v[74:77], off
	global_store_dwordx4 v[78:79], v[70:73], off offset:256
	global_store_dwordx4 v[66:67], v[62:65], off
	global_store_dwordx4 v[46:47], v[42:45], off
	global_store_dwordx4 v[30:31], v[26:29], off
	global_store_dwordx4 v[14:15], v[10:13], off
	global_store_dwordx4 v[14:15], v[6:9], off offset:256
	s_waitcnt vmcnt(0)
	s_cmpk_lt_u32 s3, 0x100
	s_cbranch_scc0 .LBB0_1022
	s_barrier

.LBB0_1172:
	s_add_u32 s62, s20, 0xfff00000
	s_addc_u32 s63, s21, -1
	s_mov_b32 m0, s37
	ds_read_b128 v[142:145], v148
	global_load_lds_dwordx4 v130, s[62:63]
	s_mov_b32 m0, s38
	ds_read_b128 v[154:157], v148 offset:1024
	global_load_lds_dwordx4 v134, s[62:63]
	s_mov_b32 m0, s42
	ds_read_b128 v[158:161], v148 offset:2048
	global_load_lds_dwordx4 v138, s[20:21]
	s_mov_b32 m0, s43
	ds_read_b128 v[168:171], v148 offset:3072
	global_load_lds_dwordx4 v140, s[20:21]
	ds_read_b128 v[176:179], v149
	ds_read_b128 v[180:183], v149 offset:1024
	ds_read_b128 v[184:187], v149 offset:2048
	ds_read_b128 v[188:191], v149 offset:3072
	s_add_u32 s22, s20, 0xfff00080
	s_addc_u32 s23, s21, -1
	s_cmp_eq_u32 s61, 60
	s_cselect_b32 s25, s54, s23
	s_cselect_b32 s24, s55, s22
	s_cselect_b32 s23, s7, s60
	s_cselect_b32 s22, s56, s57
	ds_read_b128 v[192:195], v150
	ds_read_b128 v[202:205], v150 offset:1024
	ds_read_b128 v[206:209], v150 offset:2048
	ds_read_b128 v[210:213], v150 offset:3072
	ds_read_b128 v[214:217], v150 offset:4096
	ds_read_b128 v[218:221], v150 offset:5120
	ds_read_b128 v[222:225], v150 offset:6144
	ds_read_b128 v[226:229], v150 offset:7168
	s_waitcnt vmcnt(8)
	s_waitcnt lgkmcnt(0)
	s_barrier
	v_mfma_f32_16x16x32_bf16 v[126:129], v[142:145], v[192:195], v[126:129]
	v_mfma_f32_16x16x32_bf16 v[126:129], v[154:157], v[202:205], v[126:129]
	v_mfma_f32_16x16x32_bf16 v[118:121], v[168:171], v[202:205], v[118:121]
	v_mfma_f32_16x16x32_bf16 v[118:121], v[158:161], v[192:195], v[118:121]
	v_mfma_f32_16x16x32_bf16 v[102:105], v[158:161], v[206:209], v[102:105]
	v_mfma_f32_16x16x32_bf16 v[102:105], v[168:171], v[210:213], v[102:105]
	v_mfma_f32_16x16x32_bf16 v[110:113], v[154:157], v[210:213], v[110:113]
	v_mfma_f32_16x16x32_bf16 v[110:113], v[142:145], v[206:209], v[110:113]
	v_mfma_f32_16x16x32_bf16 v[94:97], v[142:145], v[214:217], v[94:97]
	v_mfma_f32_16x16x32_bf16 v[94:97], v[154:157], v[218:221], v[94:97]
	v_mfma_f32_16x16x32_bf16 v[86:89], v[168:171], v[218:221], v[86:89]
	v_mfma_f32_16x16x32_bf16 v[86:89], v[158:161], v[214:217], v[86:89]
	v_mfma_f32_16x16x32_bf16 v[70:73], v[158:161], v[222:225], v[70:73]
	v_mfma_f32_16x16x32_bf16 v[70:73], v[168:171], v[226:229], v[70:73]
	v_mfma_f32_16x16x32_bf16 v[78:81], v[154:157], v[226:229], v[78:81]
	v_mfma_f32_16x16x32_bf16 v[78:81], v[142:145], v[222:225], v[78:81]
	v_mfma_f32_16x16x32_bf16 v[74:77], v[176:179], v[222:225], v[74:77]
	v_mfma_f32_16x16x32_bf16 v[74:77], v[180:183], v[226:229], v[74:77]
	v_mfma_f32_16x16x32_bf16 v[66:69], v[188:191], v[226:229], v[66:69]
	v_mfma_f32_16x16x32_bf16 v[66:69], v[184:187], v[222:225], v[66:69]
	v_mfma_f32_16x16x32_bf16 v[82:85], v[184:187], v[214:217], v[82:85]
	v_mfma_f32_16x16x32_bf16 v[82:85], v[188:191], v[218:221], v[82:85]
	v_mfma_f32_16x16x32_bf16 v[90:93], v[180:183], v[218:221], v[90:93]
	v_mfma_f32_16x16x32_bf16 v[90:93], v[176:179], v[214:217], v[90:93]
	v_mfma_f32_16x16x32_bf16 v[106:109], v[176:179], v[206:209], v[106:109]
	v_mfma_f32_16x16x32_bf16 v[106:109], v[180:183], v[210:213], v[106:109]
	v_mfma_f32_16x16x32_bf16 v[98:101], v[188:191], v[210:213], v[98:101]
	v_mfma_f32_16x16x32_bf16 v[98:101], v[184:187], v[206:209], v[98:101]
	v_mfma_f32_16x16x32_bf16 v[114:117], v[184:187], v[192:195], v[114:117]
	v_mfma_f32_16x16x32_bf16 v[114:117], v[188:191], v[202:205], v[114:117]
	v_mfma_f32_16x16x32_bf16 v[122:125], v[180:183], v[202:205], v[122:125]
	v_mfma_f32_16x16x32_bf16 v[122:125], v[176:179], v[192:195], v[122:125]
	s_barrier
	s_mov_b32 m0, s44
	s_add_u32 s62, s22, 0x100000
	global_load_lds_dwordx4 v132, s[22:23]
	s_mov_b32 m0, s45
	s_addc_u32 s63, s23, 0
	global_load_lds_dwordx4 v136, s[22:23]
	s_mov_b32 m0, s46
	ds_read_b128 v[192:195], v150 offset:16384
	global_load_lds_dwordx4 v132, s[62:63]
	s_mov_b32 m0, s47
	ds_read_b128 v[202:205], v150 offset:17408
	global_load_lds_dwordx4 v136, s[62:63]
	ds_read_b128 v[206:209], v150 offset:18432
	ds_read_b128 v[210:213], v150 offset:19456
	ds_read_b128 v[214:217], v150 offset:20480
	ds_read_b128 v[218:221], v150 offset:21504
	ds_read_b128 v[222:225], v150 offset:22528
	ds_read_b128 v[226:229], v150 offset:23552
	s_waitcnt vmcnt(6)
	s_waitcnt lgkmcnt(0)
	s_barrier
	v_mfma_f32_16x16x32_bf16 v[62:65], v[142:145], v[192:195], v[62:65]
	v_mfma_f32_16x16x32_bf16 v[62:65], v[154:157], v[202:205], v[62:65]
	v_mfma_f32_16x16x32_bf16 v[54:57], v[168:171], v[202:205], v[54:57]
	v_mfma_f32_16x16x32_bf16 v[54:57], v[158:161], v[192:195], v[54:57]
	v_mfma_f32_16x16x32_bf16 v[38:41], v[158:161], v[206:209], v[38:41]
	v_mfma_f32_16x16x32_bf16 v[38:41], v[168:171], v[210:213], v[38:41]
	v_mfma_f32_16x16x32_bf16 v[46:49], v[154:157], v[210:213], v[46:49]
	v_mfma_f32_16x16x32_bf16 v[46:49], v[142:145], v[206:209], v[46:49]
	v_mfma_f32_16x16x32_bf16 v[30:33], v[142:145], v[214:217], v[30:33]
	v_mfma_f32_16x16x32_bf16 v[30:33], v[154:157], v[218:221], v[30:33]
	v_mfma_f32_16x16x32_bf16 v[22:25], v[168:171], v[218:221], v[22:25]
	v_mfma_f32_16x16x32_bf16 v[22:25], v[158:161], v[214:217], v[22:25]
	v_mfma_f32_16x16x32_bf16 v[6:9], v[158:161], v[222:225], v[6:9]
	v_mfma_f32_16x16x32_bf16 v[6:9], v[168:171], v[226:229], v[6:9]
	v_mfma_f32_16x16x32_bf16 v[14:17], v[154:157], v[226:229], v[14:17]
	v_mfma_f32_16x16x32_bf16 v[14:17], v[142:145], v[222:225], v[14:17]
	v_mfma_f32_16x16x32_bf16 v[10:13], v[176:179], v[222:225], v[10:13]
	v_mfma_f32_16x16x32_bf16 v[10:13], v[180:183], v[226:229], v[10:13]
	v_mfma_f32_16x16x32_bf16 v[2:5], v[188:191], v[226:229], v[2:5]
	v_mfma_f32_16x16x32_bf16 v[2:5], v[184:187], v[222:225], v[2:5]
	v_mfma_f32_16x16x32_bf16 v[18:21], v[184:187], v[214:217], v[18:21]
	v_mfma_f32_16x16x32_bf16 v[18:21], v[188:191], v[218:221], v[18:21]
	v_mfma_f32_16x16x32_bf16 v[26:29], v[180:183], v[218:221], v[26:29]
	v_mfma_f32_16x16x32_bf16 v[26:29], v[176:179], v[214:217], v[26:29]
	v_mfma_f32_16x16x32_bf16 v[42:45], v[176:179], v[206:209], v[42:45]
	v_mfma_f32_16x16x32_bf16 v[42:45], v[180:183], v[210:213], v[42:45]
	v_mfma_f32_16x16x32_bf16 v[34:37], v[188:191], v[210:213], v[34:37]
	v_mfma_f32_16x16x32_bf16 v[34:37], v[184:187], v[206:209], v[34:37]
	v_mfma_f32_16x16x32_bf16 v[50:53], v[184:187], v[192:195], v[50:53]
	v_mfma_f32_16x16x32_bf16 v[50:53], v[188:191], v[202:205], v[50:53]
	v_mfma_f32_16x16x32_bf16 v[58:61], v[180:183], v[202:205], v[58:61]
	v_mfma_f32_16x16x32_bf16 v[58:61], v[176:179], v[192:195], v[58:61]
	s_barrier
	s_mov_b32 m0, s31
	ds_read_b128 v[142:145], v151
	global_load_lds_dwordx4 v130, s[24:25]
	s_mov_b32 m0, s33
	ds_read_b128 v[154:157], v151 offset:1024
	global_load_lds_dwordx4 v134, s[24:25]
	s_add_u32 s24, s24, 0x100000
	s_addc_u32 s25, s25, 0
	s_mov_b32 m0, s34
	ds_read_b128 v[158:161], v151 offset:2048
	global_load_lds_dwordx4 v130, s[24:25]
	s_mov_b32 m0, s35
	ds_read_b128 v[168:171], v151 offset:3072
	global_load_lds_dwordx4 v134, s[24:25]
	ds_read_b128 v[176:179], v152
	ds_read_b128 v[180:183], v152 offset:1024
	ds_read_b128 v[184:187], v152 offset:2048
	ds_read_b128 v[188:191], v152 offset:3072
	ds_read_b128 v[192:195], v150 offset:32768
	ds_read_b128 v[202:205], v150 offset:33792
	ds_read_b128 v[206:209], v150 offset:34816
	ds_read_b128 v[210:213], v150 offset:35840
	ds_read_b128 v[214:217], v150 offset:36864
	ds_read_b128 v[218:221], v150 offset:37888
	ds_read_b128 v[222:225], v150 offset:38912
	ds_read_b128 v[226:229], v150 offset:39936
	s_waitcnt vmcnt(8)
	s_waitcnt lgkmcnt(0)
	s_barrier
	v_mfma_f32_16x16x32_bf16 v[126:129], v[142:145], v[192:195], v[126:129]
	v_mfma_f32_16x16x32_bf16 v[126:129], v[154:157], v[202:205], v[126:129]
	v_mfma_f32_16x16x32_bf16 v[118:121], v[168:171], v[202:205], v[118:121]
	v_mfma_f32_16x16x32_bf16 v[118:121], v[158:161], v[192:195], v[118:121]
	v_mfma_f32_16x16x32_bf16 v[102:105], v[158:161], v[206:209], v[102:105]
	v_mfma_f32_16x16x32_bf16 v[102:105], v[168:171], v[210:213], v[102:105]
	v_mfma_f32_16x16x32_bf16 v[110:113], v[154:157], v[210:213], v[110:113]
	v_mfma_f32_16x16x32_bf16 v[110:113], v[142:145], v[206:209], v[110:113]
	v_mfma_f32_16x16x32_bf16 v[94:97], v[142:145], v[214:217], v[94:97]
	v_mfma_f32_16x16x32_bf16 v[94:97], v[154:157], v[218:221], v[94:97]
	v_mfma_f32_16x16x32_bf16 v[86:89], v[168:171], v[218:221], v[86:89]
	v_mfma_f32_16x16x32_bf16 v[86:89], v[158:161], v[214:217], v[86:89]
	v_mfma_f32_16x16x32_bf16 v[70:73], v[158:161], v[222:225], v[70:73]
	v_mfma_f32_16x16x32_bf16 v[70:73], v[168:171], v[226:229], v[70:73]
	v_mfma_f32_16x16x32_bf16 v[78:81], v[154:157], v[226:229], v[78:81]
	v_mfma_f32_16x16x32_bf16 v[78:81], v[142:145], v[222:225], v[78:81]
	v_mfma_f32_16x16x32_bf16 v[74:77], v[176:179], v[222:225], v[74:77]
	v_mfma_f32_16x16x32_bf16 v[74:77], v[180:183], v[226:229], v[74:77]
	v_mfma_f32_16x16x32_bf16 v[66:69], v[188:191], v[226:229], v[66:69]
	v_mfma_f32_16x16x32_bf16 v[66:69], v[184:187], v[222:225], v[66:69]
	v_mfma_f32_16x16x32_bf16 v[82:85], v[184:187], v[214:217], v[82:85]
	v_mfma_f32_16x16x32_bf16 v[82:85], v[188:191], v[218:221], v[82:85]
	v_mfma_f32_16x16x32_bf16 v[90:93], v[180:183], v[218:221], v[90:93]
	v_mfma_f32_16x16x32_bf16 v[90:93], v[176:179], v[214:217], v[90:93]
	v_mfma_f32_16x16x32_bf16 v[106:109], v[176:179], v[206:209], v[106:109]
	v_mfma_f32_16x16x32_bf16 v[106:109], v[180:183], v[210:213], v[106:109]
	v_mfma_f32_16x16x32_bf16 v[98:101], v[188:191], v[210:213], v[98:101]
	v_mfma_f32_16x16x32_bf16 v[98:101], v[184:187], v[206:209], v[98:101]
	v_mfma_f32_16x16x32_bf16 v[114:117], v[184:187], v[192:195], v[114:117]
	v_mfma_f32_16x16x32_bf16 v[114:117], v[188:191], v[202:205], v[114:117]
	v_mfma_f32_16x16x32_bf16 v[122:125], v[180:183], v[202:205], v[122:125]
	v_mfma_f32_16x16x32_bf16 v[122:125], v[176:179], v[192:195], v[122:125]
	s_barrier
	s_mov_b32 m0, s48
	s_add_u32 s22, s22, 0x80
	s_addc_u32 s23, s23, 0
	global_load_lds_dwordx4 v132, s[22:23]
	s_mov_b32 m0, s49
	ds_read_b128 v[192:195], v150 offset:49152
	global_load_lds_dwordx4 v136, s[22:23]
	s_mov_b32 m0, s50
	s_add_u32 s22, s22, 0x100000
	s_addc_u32 s23, s23, 0
	global_load_lds_dwordx4 v132, s[22:23]
	s_mov_b32 m0, s51
	ds_read_b128 v[202:205], v150 offset:50176
	global_load_lds_dwordx4 v136, s[22:23]
	ds_read_b128 v[206:209], v150 offset:51200
	ds_read_b128 v[210:213], v150 offset:52224
	ds_read_b128 v[214:217], v150 offset:53248
	ds_read_b128 v[218:221], v150 offset:54272
	ds_read_b128 v[222:225], v150 offset:55296
	ds_read_b128 v[226:229], v150 offset:56320
	s_waitcnt vmcnt(6)
	s_waitcnt lgkmcnt(0)
	s_barrier
	v_mfma_f32_16x16x32_bf16 v[62:65], v[142:145], v[192:195], v[62:65]
	v_mfma_f32_16x16x32_bf16 v[62:65], v[154:157], v[202:205], v[62:65]
	v_mfma_f32_16x16x32_bf16 v[54:57], v[168:171], v[202:205], v[54:57]
	v_mfma_f32_16x16x32_bf16 v[54:57], v[158:161], v[192:195], v[54:57]
	v_mfma_f32_16x16x32_bf16 v[38:41], v[158:161], v[206:209], v[38:41]
	v_mfma_f32_16x16x32_bf16 v[38:41], v[168:171], v[210:213], v[38:41]
	v_mfma_f32_16x16x32_bf16 v[46:49], v[154:157], v[210:213], v[46:49]
	v_mfma_f32_16x16x32_bf16 v[46:49], v[142:145], v[206:209], v[46:49]
	v_mfma_f32_16x16x32_bf16 v[30:33], v[142:145], v[214:217], v[30:33]
	v_mfma_f32_16x16x32_bf16 v[30:33], v[154:157], v[218:221], v[30:33]
	v_mfma_f32_16x16x32_bf16 v[22:25], v[168:171], v[218:221], v[22:25]
	v_mfma_f32_16x16x32_bf16 v[22:25], v[158:161], v[214:217], v[22:25]
	v_mfma_f32_16x16x32_bf16 v[6:9], v[158:161], v[222:225], v[6:9]
	v_mfma_f32_16x16x32_bf16 v[6:9], v[168:171], v[226:229], v[6:9]
	v_mfma_f32_16x16x32_bf16 v[14:17], v[154:157], v[226:229], v[14:17]
	v_mfma_f32_16x16x32_bf16 v[14:17], v[142:145], v[222:225], v[14:17]
	v_mfma_f32_16x16x32_bf16 v[10:13], v[176:179], v[222:225], v[10:13]
	v_mfma_f32_16x16x32_bf16 v[10:13], v[180:183], v[226:229], v[10:13]
	v_mfma_f32_16x16x32_bf16 v[2:5], v[188:191], v[226:229], v[2:5]
	v_mfma_f32_16x16x32_bf16 v[2:5], v[184:187], v[222:225], v[2:5]
	v_mfma_f32_16x16x32_bf16 v[18:21], v[184:187], v[214:217], v[18:21]
	v_mfma_f32_16x16x32_bf16 v[18:21], v[188:191], v[218:221], v[18:21]
	v_mfma_f32_16x16x32_bf16 v[26:29], v[180:183], v[218:221], v[26:29]
	v_mfma_f32_16x16x32_bf16 v[26:29], v[176:179], v[214:217], v[26:29]
	v_mfma_f32_16x16x32_bf16 v[42:45], v[176:179], v[206:209], v[42:45]
	v_mfma_f32_16x16x32_bf16 v[42:45], v[180:183], v[210:213], v[42:45]
	v_mfma_f32_16x16x32_bf16 v[34:37], v[188:191], v[210:213], v[34:37]
	v_mfma_f32_16x16x32_bf16 v[34:37], v[184:187], v[206:209], v[34:37]
	v_mfma_f32_16x16x32_bf16 v[50:53], v[184:187], v[192:195], v[50:53]
	v_mfma_f32_16x16x32_bf16 v[50:53], v[188:191], v[202:205], v[50:53]
	v_mfma_f32_16x16x32_bf16 v[58:61], v[180:183], v[202:205], v[58:61]
	v_mfma_f32_16x16x32_bf16 v[58:61], v[176:179], v[192:195], v[58:61]
	s_barrier
	s_add_i32 s61, s61, 2
	s_add_u32 s20, s20, 0x100
	s_addc_u32 s21, s21, 0
	s_add_u32 s57, s57, 0x100
	s_addc_u32 s60, s60, 0
	s_cmp_gt_u32 s61, 61
	s_cbranch_scc0 .LBB0_1172
	s_and_b64 vcc, exec, s[16:17]
	s_cbranch_vccz .LBB0_1175
	s_barrier

.LBB0_1418:
	s_add_u32 s56, s22, 0xffd50000
	s_addc_u32 s57, s23, -1
	s_mov_b32 m0, s40
	ds_read_b128 v[142:145], v156
	global_load_lds_dwordx4 v130, s[56:57]
	s_mov_b32 m0, s41
	ds_read_b128 v[168:171], v156 offset:1024
	global_load_lds_dwordx4 v134, s[56:57]
	s_mov_b32 m0, s42
	ds_read_b128 v[176:179], v156 offset:2048
	global_load_lds_dwordx4 v138, s[22:23]
	s_mov_b32 m0, s43
	ds_read_b128 v[180:183], v156 offset:3072
	global_load_lds_dwordx4 v140, s[22:23]
	ds_read_b128 v[184:187], v157
	ds_read_b128 v[188:191], v157 offset:1024
	ds_read_b128 v[192:195], v157 offset:2048
	ds_read_b128 v[204:207], v157 offset:3072
	s_add_u32 s24, s22, 0xffd50080
	s_addc_u32 s25, s23, -1
	s_cmpk_eq_i32 s55, 0xa8
	s_cselect_b32 s27, s19, s25
	s_cselect_b32 s26, s18, s24
	s_cselect_b32 s25, s17, s54
	s_cselect_b32 s24, s16, s53
	ds_read_b128 v[208:211], v158
	ds_read_b128 v[212:215], v158 offset:1024
	ds_read_b128 v[216:219], v158 offset:2048
	ds_read_b128 v[220:223], v158 offset:3072
	ds_read_b128 v[224:227], v158 offset:4096
	ds_read_b128 v[228:231], v158 offset:5120
	ds_read_b128 v[232:235], v158 offset:6144
	ds_read_b128 v[236:239], v158 offset:7168
	s_waitcnt vmcnt(8)
	s_waitcnt lgkmcnt(0)
	s_barrier
	v_mfma_f32_16x16x32_bf16 v[126:129], v[142:145], v[208:211], v[126:129]
	v_mfma_f32_16x16x32_bf16 v[126:129], v[168:171], v[212:215], v[126:129]
	v_mfma_f32_16x16x32_bf16 v[122:125], v[180:183], v[212:215], v[122:125]
	v_mfma_f32_16x16x32_bf16 v[122:125], v[176:179], v[208:211], v[122:125]
	v_mfma_f32_16x16x32_bf16 v[106:109], v[176:179], v[216:219], v[106:109]
	v_mfma_f32_16x16x32_bf16 v[106:109], v[180:183], v[220:223], v[106:109]
	v_mfma_f32_16x16x32_bf16 v[110:113], v[168:171], v[220:223], v[110:113]
	v_mfma_f32_16x16x32_bf16 v[110:113], v[142:145], v[216:219], v[110:113]
	v_mfma_f32_16x16x32_bf16 v[94:97], v[142:145], v[224:227], v[94:97]
	v_mfma_f32_16x16x32_bf16 v[94:97], v[168:171], v[228:231], v[94:97]
	v_mfma_f32_16x16x32_bf16 v[90:93], v[180:183], v[228:231], v[90:93]
	v_mfma_f32_16x16x32_bf16 v[90:93], v[176:179], v[224:227], v[90:93]
	v_mfma_f32_16x16x32_bf16 v[74:77], v[176:179], v[232:235], v[74:77]
	v_mfma_f32_16x16x32_bf16 v[74:77], v[180:183], v[236:239], v[74:77]
	v_mfma_f32_16x16x32_bf16 v[78:81], v[168:171], v[236:239], v[78:81]
	v_mfma_f32_16x16x32_bf16 v[78:81], v[142:145], v[232:235], v[78:81]
	v_mfma_f32_16x16x32_bf16 v[70:73], v[184:187], v[232:235], v[70:73]
	v_mfma_f32_16x16x32_bf16 v[70:73], v[188:191], v[236:239], v[70:73]
	v_mfma_f32_16x16x32_bf16 v[66:69], v[204:207], v[236:239], v[66:69]
	v_mfma_f32_16x16x32_bf16 v[66:69], v[192:195], v[232:235], v[66:69]
	v_mfma_f32_16x16x32_bf16 v[82:85], v[192:195], v[224:227], v[82:85]
	v_mfma_f32_16x16x32_bf16 v[82:85], v[204:207], v[228:231], v[82:85]
	v_mfma_f32_16x16x32_bf16 v[86:89], v[188:191], v[228:231], v[86:89]
	v_mfma_f32_16x16x32_bf16 v[86:89], v[184:187], v[224:227], v[86:89]
	v_mfma_f32_16x16x32_bf16 v[102:105], v[184:187], v[216:219], v[102:105]
	v_mfma_f32_16x16x32_bf16 v[102:105], v[188:191], v[220:223], v[102:105]
	v_mfma_f32_16x16x32_bf16 v[98:101], v[204:207], v[220:223], v[98:101]
	v_mfma_f32_16x16x32_bf16 v[98:101], v[192:195], v[216:219], v[98:101]
	v_mfma_f32_16x16x32_bf16 v[114:117], v[192:195], v[208:211], v[114:117]
	v_mfma_f32_16x16x32_bf16 v[114:117], v[204:207], v[212:215], v[114:117]
	v_mfma_f32_16x16x32_bf16 v[118:121], v[188:191], v[212:215], v[118:121]
	v_mfma_f32_16x16x32_bf16 v[118:121], v[184:187], v[208:211], v[118:121]
	s_barrier
	s_mov_b32 m0, s44
	s_add_u32 s56, s24, 0x2b0000
	global_load_lds_dwordx4 v132, s[24:25]
	s_mov_b32 m0, s45
	s_addc_u32 s57, s25, 0
	global_load_lds_dwordx4 v136, s[24:25]
	s_mov_b32 m0, s46
	ds_read_b128 v[208:211], v158 offset:16384
	global_load_lds_dwordx4 v132, s[56:57]
	s_mov_b32 m0, s47
	ds_read_b128 v[212:215], v158 offset:17408
	global_load_lds_dwordx4 v136, s[56:57]
	ds_read_b128 v[216:219], v158 offset:18432
	ds_read_b128 v[220:223], v158 offset:19456
	ds_read_b128 v[224:227], v158 offset:20480
	ds_read_b128 v[228:231], v158 offset:21504
	ds_read_b128 v[232:235], v158 offset:22528
	ds_read_b128 v[236:239], v158 offset:23552
	s_waitcnt vmcnt(6)
	s_waitcnt lgkmcnt(0)
	s_barrier
	v_mfma_f32_16x16x32_bf16 v[62:65], v[142:145], v[208:211], v[62:65]
	v_mfma_f32_16x16x32_bf16 v[62:65], v[168:171], v[212:215], v[62:65]
	v_mfma_f32_16x16x32_bf16 v[58:61], v[180:183], v[212:215], v[58:61]
	v_mfma_f32_16x16x32_bf16 v[58:61], v[176:179], v[208:211], v[58:61]
	v_mfma_f32_16x16x32_bf16 v[42:45], v[176:179], v[216:219], v[42:45]
	v_mfma_f32_16x16x32_bf16 v[42:45], v[180:183], v[220:223], v[42:45]
	v_mfma_f32_16x16x32_bf16 v[46:49], v[168:171], v[220:223], v[46:49]
	v_mfma_f32_16x16x32_bf16 v[46:49], v[142:145], v[216:219], v[46:49]
	v_mfma_f32_16x16x32_bf16 v[30:33], v[142:145], v[224:227], v[30:33]
	v_mfma_f32_16x16x32_bf16 v[30:33], v[168:171], v[228:231], v[30:33]
	v_mfma_f32_16x16x32_bf16 v[26:29], v[180:183], v[228:231], v[26:29]
	v_mfma_f32_16x16x32_bf16 v[26:29], v[176:179], v[224:227], v[26:29]
	v_mfma_f32_16x16x32_bf16 v[10:13], v[176:179], v[232:235], v[10:13]
	v_mfma_f32_16x16x32_bf16 v[10:13], v[180:183], v[236:239], v[10:13]
	v_mfma_f32_16x16x32_bf16 v[14:17], v[168:171], v[236:239], v[14:17]
	v_mfma_f32_16x16x32_bf16 v[14:17], v[142:145], v[232:235], v[14:17]
	v_mfma_f32_16x16x32_bf16 v[6:9], v[184:187], v[232:235], v[6:9]
	v_mfma_f32_16x16x32_bf16 v[6:9], v[188:191], v[236:239], v[6:9]
	v_mfma_f32_16x16x32_bf16 v[2:5], v[204:207], v[236:239], v[2:5]
	v_mfma_f32_16x16x32_bf16 v[2:5], v[192:195], v[232:235], v[2:5]
	v_mfma_f32_16x16x32_bf16 v[18:21], v[192:195], v[224:227], v[18:21]
	v_mfma_f32_16x16x32_bf16 v[18:21], v[204:207], v[228:231], v[18:21]
	v_mfma_f32_16x16x32_bf16 v[22:25], v[188:191], v[228:231], v[22:25]
	v_mfma_f32_16x16x32_bf16 v[22:25], v[184:187], v[224:227], v[22:25]
	v_mfma_f32_16x16x32_bf16 v[38:41], v[184:187], v[216:219], v[38:41]
	v_mfma_f32_16x16x32_bf16 v[38:41], v[188:191], v[220:223], v[38:41]
	v_mfma_f32_16x16x32_bf16 v[34:37], v[204:207], v[220:223], v[34:37]
	v_mfma_f32_16x16x32_bf16 v[34:37], v[192:195], v[216:219], v[34:37]
	v_mfma_f32_16x16x32_bf16 v[50:53], v[192:195], v[208:211], v[50:53]
	v_mfma_f32_16x16x32_bf16 v[50:53], v[204:207], v[212:215], v[50:53]
	v_mfma_f32_16x16x32_bf16 v[54:57], v[188:191], v[212:215], v[54:57]
	v_mfma_f32_16x16x32_bf16 v[54:57], v[184:187], v[208:211], v[54:57]
	s_barrier
	s_mov_b32 m0, s35
	ds_read_b128 v[142:145], v159
	global_load_lds_dwordx4 v130, s[26:27]
	s_mov_b32 m0, s36
	ds_read_b128 v[168:171], v159 offset:1024
	global_load_lds_dwordx4 v134, s[26:27]
	s_add_u32 s26, s26, 0x2b0000
	s_addc_u32 s27, s27, 0
	s_mov_b32 m0, s37
	ds_read_b128 v[176:179], v159 offset:2048
	global_load_lds_dwordx4 v130, s[26:27]
	s_mov_b32 m0, s38
	ds_read_b128 v[180:183], v159 offset:3072
	global_load_lds_dwordx4 v134, s[26:27]
	ds_read_b128 v[184:187], v160
	ds_read_b128 v[188:191], v160 offset:1024
	ds_read_b128 v[192:195], v160 offset:2048
	ds_read_b128 v[204:207], v160 offset:3072
	ds_read_b128 v[208:211], v158 offset:32768
	ds_read_b128 v[212:215], v158 offset:33792
	ds_read_b128 v[216:219], v158 offset:34816
	ds_read_b128 v[220:223], v158 offset:35840
	ds_read_b128 v[224:227], v158 offset:36864
	ds_read_b128 v[228:231], v158 offset:37888
	ds_read_b128 v[232:235], v158 offset:38912
	ds_read_b128 v[236:239], v158 offset:39936
	s_waitcnt vmcnt(8)
	s_waitcnt lgkmcnt(0)
	s_barrier
	v_mfma_f32_16x16x32_bf16 v[126:129], v[142:145], v[208:211], v[126:129]
	v_mfma_f32_16x16x32_bf16 v[126:129], v[168:171], v[212:215], v[126:129]
	v_mfma_f32_16x16x32_bf16 v[122:125], v[180:183], v[212:215], v[122:125]
	v_mfma_f32_16x16x32_bf16 v[122:125], v[176:179], v[208:211], v[122:125]
	v_mfma_f32_16x16x32_bf16 v[106:109], v[176:179], v[216:219], v[106:109]
	v_mfma_f32_16x16x32_bf16 v[106:109], v[180:183], v[220:223], v[106:109]
	v_mfma_f32_16x16x32_bf16 v[110:113], v[168:171], v[220:223], v[110:113]
	v_mfma_f32_16x16x32_bf16 v[110:113], v[142:145], v[216:219], v[110:113]
	v_mfma_f32_16x16x32_bf16 v[94:97], v[142:145], v[224:227], v[94:97]
	v_mfma_f32_16x16x32_bf16 v[94:97], v[168:171], v[228:231], v[94:97]
	v_mfma_f32_16x16x32_bf16 v[90:93], v[180:183], v[228:231], v[90:93]
	v_mfma_f32_16x16x32_bf16 v[90:93], v[176:179], v[224:227], v[90:93]
	v_mfma_f32_16x16x32_bf16 v[74:77], v[176:179], v[232:235], v[74:77]
	v_mfma_f32_16x16x32_bf16 v[74:77], v[180:183], v[236:239], v[74:77]
	v_mfma_f32_16x16x32_bf16 v[78:81], v[168:171], v[236:239], v[78:81]
	v_mfma_f32_16x16x32_bf16 v[78:81], v[142:145], v[232:235], v[78:81]
	v_mfma_f32_16x16x32_bf16 v[70:73], v[184:187], v[232:235], v[70:73]
	v_mfma_f32_16x16x32_bf16 v[70:73], v[188:191], v[236:239], v[70:73]
	v_mfma_f32_16x16x32_bf16 v[66:69], v[204:207], v[236:239], v[66:69]
	v_mfma_f32_16x16x32_bf16 v[66:69], v[192:195], v[232:235], v[66:69]
	v_mfma_f32_16x16x32_bf16 v[82:85], v[192:195], v[224:227], v[82:85]
	v_mfma_f32_16x16x32_bf16 v[82:85], v[204:207], v[228:231], v[82:85]
	v_mfma_f32_16x16x32_bf16 v[86:89], v[188:191], v[228:231], v[86:89]
	v_mfma_f32_16x16x32_bf16 v[86:89], v[184:187], v[224:227], v[86:89]
	v_mfma_f32_16x16x32_bf16 v[102:105], v[184:187], v[216:219], v[102:105]
	v_mfma_f32_16x16x32_bf16 v[102:105], v[188:191], v[220:223], v[102:105]
	v_mfma_f32_16x16x32_bf16 v[98:101], v[204:207], v[220:223], v[98:101]
	v_mfma_f32_16x16x32_bf16 v[98:101], v[192:195], v[216:219], v[98:101]
	v_mfma_f32_16x16x32_bf16 v[114:117], v[192:195], v[208:211], v[114:117]
	v_mfma_f32_16x16x32_bf16 v[114:117], v[204:207], v[212:215], v[114:117]
	v_mfma_f32_16x16x32_bf16 v[118:121], v[188:191], v[212:215], v[118:121]
	v_mfma_f32_16x16x32_bf16 v[118:121], v[184:187], v[208:211], v[118:121]
	s_barrier
	s_mov_b32 m0, s48
	s_add_u32 s24, s24, 0x80
	s_addc_u32 s25, s25, 0
	global_load_lds_dwordx4 v132, s[24:25]
	s_mov_b32 m0, s49
	ds_read_b128 v[208:211], v158 offset:49152
	global_load_lds_dwordx4 v136, s[24:25]
	s_mov_b32 m0, s50
	s_add_u32 s24, s24, 0x2b0000
	s_addc_u32 s25, s25, 0
	global_load_lds_dwordx4 v132, s[24:25]
	s_add_i32 m0, s50, 0x2000
	ds_read_b128 v[212:215], v158 offset:50176
	global_load_lds_dwordx4 v136, s[24:25]
	ds_read_b128 v[216:219], v158 offset:51200
	ds_read_b128 v[220:223], v158 offset:52224
	ds_read_b128 v[224:227], v158 offset:53248
	ds_read_b128 v[228:231], v158 offset:54272
	ds_read_b128 v[232:235], v158 offset:55296
	ds_read_b128 v[236:239], v158 offset:56320
	s_waitcnt vmcnt(6)
	s_waitcnt lgkmcnt(0)
	s_barrier
	v_mfma_f32_16x16x32_bf16 v[62:65], v[142:145], v[208:211], v[62:65]
	v_mfma_f32_16x16x32_bf16 v[62:65], v[168:171], v[212:215], v[62:65]
	v_mfma_f32_16x16x32_bf16 v[58:61], v[180:183], v[212:215], v[58:61]
	v_mfma_f32_16x16x32_bf16 v[58:61], v[176:179], v[208:211], v[58:61]
	v_mfma_f32_16x16x32_bf16 v[42:45], v[176:179], v[216:219], v[42:45]
	v_mfma_f32_16x16x32_bf16 v[42:45], v[180:183], v[220:223], v[42:45]
	v_mfma_f32_16x16x32_bf16 v[46:49], v[168:171], v[220:223], v[46:49]
	v_mfma_f32_16x16x32_bf16 v[46:49], v[142:145], v[216:219], v[46:49]
	v_mfma_f32_16x16x32_bf16 v[30:33], v[142:145], v[224:227], v[30:33]
	v_mfma_f32_16x16x32_bf16 v[30:33], v[168:171], v[228:231], v[30:33]
	v_mfma_f32_16x16x32_bf16 v[26:29], v[180:183], v[228:231], v[26:29]
	v_mfma_f32_16x16x32_bf16 v[26:29], v[176:179], v[224:227], v[26:29]
	v_mfma_f32_16x16x32_bf16 v[10:13], v[176:179], v[232:235], v[10:13]
	v_mfma_f32_16x16x32_bf16 v[10:13], v[180:183], v[236:239], v[10:13]
	v_mfma_f32_16x16x32_bf16 v[14:17], v[168:171], v[236:239], v[14:17]
	v_mfma_f32_16x16x32_bf16 v[14:17], v[142:145], v[232:235], v[14:17]
	v_mfma_f32_16x16x32_bf16 v[6:9], v[184:187], v[232:235], v[6:9]
	v_mfma_f32_16x16x32_bf16 v[6:9], v[188:191], v[236:239], v[6:9]
	v_mfma_f32_16x16x32_bf16 v[2:5], v[204:207], v[236:239], v[2:5]
	v_mfma_f32_16x16x32_bf16 v[2:5], v[192:195], v[232:235], v[2:5]
	v_mfma_f32_16x16x32_bf16 v[18:21], v[192:195], v[224:227], v[18:21]
	v_mfma_f32_16x16x32_bf16 v[18:21], v[204:207], v[228:231], v[18:21]
	v_mfma_f32_16x16x32_bf16 v[22:25], v[188:191], v[228:231], v[22:25]
	v_mfma_f32_16x16x32_bf16 v[22:25], v[184:187], v[224:227], v[22:25]
	v_mfma_f32_16x16x32_bf16 v[38:41], v[184:187], v[216:219], v[38:41]
	v_mfma_f32_16x16x32_bf16 v[38:41], v[188:191], v[220:223], v[38:41]
	v_mfma_f32_16x16x32_bf16 v[34:37], v[204:207], v[220:223], v[34:37]
	v_mfma_f32_16x16x32_bf16 v[34:37], v[192:195], v[216:219], v[34:37]
	v_mfma_f32_16x16x32_bf16 v[50:53], v[192:195], v[208:211], v[50:53]
	v_mfma_f32_16x16x32_bf16 v[50:53], v[204:207], v[212:215], v[50:53]
	v_mfma_f32_16x16x32_bf16 v[54:57], v[188:191], v[212:215], v[54:57]
	v_mfma_f32_16x16x32_bf16 v[54:57], v[184:187], v[208:211], v[54:57]
	s_barrier
	s_add_i32 s55, s55, 2
	s_add_u32 s22, s22, 0x100
	s_addc_u32 s23, s23, 0
	s_add_u32 s53, s53, 0x100
	s_addc_u32 s54, s54, 0
	s_cmpk_gt_u32 s55, 0xa9
	s_cbranch_scc0 .LBB0_1418
	s_and_b64 vcc, exec, s[14:15]
	s_cbranch_vccz .LBB0_1421
	s_barrier

.LBB0_1432:
	ds_read_b128 v[150:153], v139
	ds_read_b128 v[154:157], v139 offset:1024
	ds_read_b128 v[158:161], v139 offset:2048
	ds_read_b128 v[168:171], v139 offset:3072
	ds_read_b128 v[176:179], v144
	ds_read_b128 v[180:183], v144 offset:1024
	ds_read_b128 v[184:187], v144 offset:2048
	ds_read_b128 v[188:191], v144 offset:3072
	s_add_i32 s42, s15, 2
	s_add_u32 s14, s12, 0xc2050080
	s_addc_u32 s16, s13, -1
	s_cmp_lg_u32 s30, s15
	s_cselect_b32 s14, s14, 0
	s_cselect_b32 s15, s16, 0
	s_add_u32 s16, s4, s14
	s_addc_u32 s17, s5, s15
	s_add_u32 s14, s8, s14
	s_addc_u32 s15, s9, s15
	s_mov_b32 m0, s31
	v_lshl_add_u64 v[172:173], v[140:141], 0, s[12:13]
	ds_read_b128 v[192:195], v145
	ds_read_b128 v[204:207], v145 offset:1024
	ds_read_b128 v[208:211], v145 offset:2048
	ds_read_b128 v[212:215], v145 offset:3072
	ds_read_b128 v[216:219], v145 offset:4096
	ds_read_b128 v[220:223], v145 offset:5120
	ds_read_b128 v[224:227], v145 offset:6144
	ds_read_b128 v[228:231], v145 offset:7168
	global_load_lds_dwordx4 v[172:173], off
	v_lshl_add_u64 v[172:173], v[142:143], 0, s[12:13]
	s_mov_b32 m0, s33
	s_nop 0
	global_load_lds_dwordx4 v[172:173], off
	s_waitcnt vmcnt(8)
	s_waitcnt lgkmcnt(0)
	s_barrier
	v_mfma_f32_16x16x32_bf16 v[126:129], v[150:153], v[192:195], v[126:129]
	v_mfma_f32_16x16x32_bf16 v[126:129], v[154:157], v[204:207], v[126:129]
	v_mfma_f32_16x16x32_bf16 v[122:125], v[168:171], v[204:207], v[122:125]
	v_mfma_f32_16x16x32_bf16 v[122:125], v[158:161], v[192:195], v[122:125]
	v_mfma_f32_16x16x32_bf16 v[114:117], v[158:161], v[208:211], v[114:117]
	v_mfma_f32_16x16x32_bf16 v[114:117], v[168:171], v[212:215], v[114:117]
	v_mfma_f32_16x16x32_bf16 v[118:121], v[154:157], v[212:215], v[118:121]
	v_mfma_f32_16x16x32_bf16 v[118:121], v[150:153], v[208:211], v[118:121]
	v_mfma_f32_16x16x32_bf16 v[102:105], v[150:153], v[216:219], v[102:105]
	v_mfma_f32_16x16x32_bf16 v[102:105], v[154:157], v[220:223], v[102:105]
	v_mfma_f32_16x16x32_bf16 v[98:101], v[168:171], v[220:223], v[98:101]
	v_mfma_f32_16x16x32_bf16 v[98:101], v[158:161], v[216:219], v[98:101]
	v_mfma_f32_16x16x32_bf16 v[82:85], v[158:161], v[224:227], v[82:85]
	v_mfma_f32_16x16x32_bf16 v[82:85], v[168:171], v[228:231], v[82:85]
	v_mfma_f32_16x16x32_bf16 v[86:89], v[154:157], v[228:231], v[86:89]
	v_mfma_f32_16x16x32_bf16 v[86:89], v[150:153], v[224:227], v[86:89]
	v_mfma_f32_16x16x32_bf16 v[70:73], v[176:179], v[224:227], v[70:73]
	v_mfma_f32_16x16x32_bf16 v[70:73], v[180:183], v[228:231], v[70:73]
	v_mfma_f32_16x16x32_bf16 v[66:69], v[188:191], v[228:231], v[66:69]
	v_mfma_f32_16x16x32_bf16 v[66:69], v[184:187], v[224:227], v[66:69]
	v_mfma_f32_16x16x32_bf16 v[74:77], v[184:187], v[216:219], v[74:77]
	v_mfma_f32_16x16x32_bf16 v[74:77], v[188:191], v[220:223], v[74:77]
	v_mfma_f32_16x16x32_bf16 v[78:81], v[180:183], v[220:223], v[78:81]
	v_mfma_f32_16x16x32_bf16 v[78:81], v[176:179], v[216:219], v[78:81]
	v_mfma_f32_16x16x32_bf16 v[94:97], v[176:179], v[208:211], v[94:97]
	v_mfma_f32_16x16x32_bf16 v[94:97], v[180:183], v[212:215], v[94:97]
	v_mfma_f32_16x16x32_bf16 v[90:93], v[188:191], v[212:215], v[90:93]
	v_mfma_f32_16x16x32_bf16 v[90:93], v[184:187], v[208:211], v[90:93]
	v_mfma_f32_16x16x32_bf16 v[106:109], v[184:187], v[192:195], v[106:109]
	v_mfma_f32_16x16x32_bf16 v[106:109], v[188:191], v[204:207], v[106:109]
	v_mfma_f32_16x16x32_bf16 v[110:113], v[180:183], v[204:207], v[110:113]
	v_mfma_f32_16x16x32_bf16 v[110:113], v[176:179], v[192:195], v[110:113]
	s_barrier
	s_mov_b32 m0, s34
	v_lshl_add_u64 v[172:173], s[14:15], 0, v[132:133]
	s_add_u32 s44, s14, 0x2b0000
	ds_read_b128 v[192:195], v145 offset:16384
	ds_read_b128 v[204:207], v145 offset:17408
	ds_read_b128 v[208:211], v145 offset:18432
	ds_read_b128 v[212:215], v145 offset:19456
	ds_read_b128 v[216:219], v145 offset:20480
	ds_read_b128 v[220:223], v145 offset:21504
	ds_read_b128 v[224:227], v145 offset:22528
	ds_read_b128 v[228:231], v145 offset:23552
	global_load_lds_dwordx4 v[172:173], off
	v_lshl_add_u64 v[196:197], s[14:15], 0, v[136:137]
	s_mov_b32 m0, s35
	s_addc_u32 s45, s15, 0
	global_load_lds_dwordx4 v[196:197], off
	v_lshl_add_u64 v[232:233], s[44:45], 0, v[132:133]
	s_mov_b32 m0, s36
	v_lshl_add_u64 v[234:235], s[16:17], 0, v[134:135]
	global_load_lds_dwordx4 v[232:233], off
	v_lshl_add_u64 v[232:233], s[44:45], 0, v[136:137]
	s_mov_b32 m0, s37
	s_nop 0
	global_load_lds_dwordx4 v[232:233], off
	v_lshl_add_u64 v[232:233], s[16:17], 0, v[130:131]
	s_mov_b32 m0, s21
	s_nop 0
	global_load_lds_dwordx4 v[232:233], off
	s_mov_b32 m0, s22
	s_nop 0
	global_load_lds_dwordx4 v[234:235], off
	s_waitcnt vmcnt(8)
	s_waitcnt lgkmcnt(0)
	s_barrier
	v_mfma_f32_16x16x32_bf16 v[62:65], v[150:153], v[192:195], v[62:65]
	v_mfma_f32_16x16x32_bf16 v[62:65], v[154:157], v[204:207], v[62:65]
	v_mfma_f32_16x16x32_bf16 v[58:61], v[168:171], v[204:207], v[58:61]
	v_mfma_f32_16x16x32_bf16 v[58:61], v[158:161], v[192:195], v[58:61]
	v_mfma_f32_16x16x32_bf16 v[50:53], v[158:161], v[208:211], v[50:53]
	v_mfma_f32_16x16x32_bf16 v[50:53], v[168:171], v[212:215], v[50:53]
	v_mfma_f32_16x16x32_bf16 v[54:57], v[154:157], v[212:215], v[54:57]
	v_mfma_f32_16x16x32_bf16 v[54:57], v[150:153], v[208:211], v[54:57]
	v_mfma_f32_16x16x32_bf16 v[38:41], v[150:153], v[216:219], v[38:41]
	v_mfma_f32_16x16x32_bf16 v[38:41], v[154:157], v[220:223], v[38:41]
	v_mfma_f32_16x16x32_bf16 v[34:37], v[168:171], v[220:223], v[34:37]
	v_mfma_f32_16x16x32_bf16 v[34:37], v[158:161], v[216:219], v[34:37]
	v_mfma_f32_16x16x32_bf16 v[18:21], v[158:161], v[224:227], v[18:21]
	v_mfma_f32_16x16x32_bf16 v[18:21], v[168:171], v[228:231], v[18:21]
	v_mfma_f32_16x16x32_bf16 v[22:25], v[154:157], v[228:231], v[22:25]
	v_mfma_f32_16x16x32_bf16 v[22:25], v[150:153], v[224:227], v[22:25]
	v_mfma_f32_16x16x32_bf16 v[6:9], v[176:179], v[224:227], v[6:9]
	v_mfma_f32_16x16x32_bf16 v[6:9], v[180:183], v[228:231], v[6:9]
	v_mfma_f32_16x16x32_bf16 v[2:5], v[188:191], v[228:231], v[2:5]
	v_mfma_f32_16x16x32_bf16 v[2:5], v[184:187], v[224:227], v[2:5]
	v_mfma_f32_16x16x32_bf16 v[10:13], v[184:187], v[216:219], v[10:13]
	v_mfma_f32_16x16x32_bf16 v[10:13], v[188:191], v[220:223], v[10:13]
	v_mfma_f32_16x16x32_bf16 v[14:17], v[180:183], v[220:223], v[14:17]
	v_mfma_f32_16x16x32_bf16 v[14:17], v[176:179], v[216:219], v[14:17]
	v_mfma_f32_16x16x32_bf16 v[30:33], v[176:179], v[208:211], v[30:33]
	v_mfma_f32_16x16x32_bf16 v[30:33], v[180:183], v[212:215], v[30:33]
	v_mfma_f32_16x16x32_bf16 v[26:29], v[188:191], v[212:215], v[26:29]
	v_mfma_f32_16x16x32_bf16 v[26:29], v[184:187], v[208:211], v[26:29]
	v_mfma_f32_16x16x32_bf16 v[42:45], v[184:187], v[192:195], v[42:45]
	v_mfma_f32_16x16x32_bf16 v[42:45], v[188:191], v[204:207], v[42:45]
	v_mfma_f32_16x16x32_bf16 v[46:49], v[180:183], v[204:207], v[46:49]
	v_mfma_f32_16x16x32_bf16 v[46:49], v[176:179], v[192:195], v[46:49]
	s_barrier
	ds_read_b128 v[150:153], v146
	ds_read_b128 v[154:157], v146 offset:1024
	ds_read_b128 v[158:161], v146 offset:2048
	ds_read_b128 v[168:171], v146 offset:3072
	ds_read_b128 v[176:179], v147
	ds_read_b128 v[180:183], v147 offset:1024
	ds_read_b128 v[184:187], v147 offset:2048
	ds_read_b128 v[188:191], v147 offset:3072
	s_add_u32 s16, s16, 0x2b0000
	s_addc_u32 s17, s17, 0
	s_mov_b32 m0, s23
	v_lshl_add_u64 v[236:237], s[16:17], 0, v[130:131]
	ds_read_b128 v[192:195], v145 offset:32768
	ds_read_b128 v[204:207], v145 offset:33792
	ds_read_b128 v[208:211], v145 offset:34816
	ds_read_b128 v[212:215], v145 offset:35840
	ds_read_b128 v[216:219], v145 offset:36864
	ds_read_b128 v[220:223], v145 offset:37888
	ds_read_b128 v[224:227], v145 offset:38912
	ds_read_b128 v[228:231], v145 offset:39936
	global_load_lds_dwordx4 v[236:237], off
	v_lshl_add_u64 v[236:237], s[16:17], 0, v[134:135]
	s_mov_b32 m0, s24
	s_nop 0
	global_load_lds_dwordx4 v[236:237], off
	s_waitcnt vmcnt(8)
	s_waitcnt lgkmcnt(0)
	s_barrier
	v_mfma_f32_16x16x32_bf16 v[126:129], v[150:153], v[192:195], v[126:129]
	v_mfma_f32_16x16x32_bf16 v[126:129], v[154:157], v[204:207], v[126:129]
	v_mfma_f32_16x16x32_bf16 v[122:125], v[168:171], v[204:207], v[122:125]
	v_mfma_f32_16x16x32_bf16 v[122:125], v[158:161], v[192:195], v[122:125]
	v_mfma_f32_16x16x32_bf16 v[114:117], v[158:161], v[208:211], v[114:117]
	v_mfma_f32_16x16x32_bf16 v[114:117], v[168:171], v[212:215], v[114:117]
	v_mfma_f32_16x16x32_bf16 v[118:121], v[154:157], v[212:215], v[118:121]
	v_mfma_f32_16x16x32_bf16 v[118:121], v[150:153], v[208:211], v[118:121]
	v_mfma_f32_16x16x32_bf16 v[102:105], v[150:153], v[216:219], v[102:105]
	v_mfma_f32_16x16x32_bf16 v[102:105], v[154:157], v[220:223], v[102:105]
	v_mfma_f32_16x16x32_bf16 v[98:101], v[168:171], v[220:223], v[98:101]
	v_mfma_f32_16x16x32_bf16 v[98:101], v[158:161], v[216:219], v[98:101]
	v_mfma_f32_16x16x32_bf16 v[82:85], v[158:161], v[224:227], v[82:85]
	v_mfma_f32_16x16x32_bf16 v[82:85], v[168:171], v[228:231], v[82:85]
	v_mfma_f32_16x16x32_bf16 v[86:89], v[154:157], v[228:231], v[86:89]
	v_mfma_f32_16x16x32_bf16 v[86:89], v[150:153], v[224:227], v[86:89]
	v_mfma_f32_16x16x32_bf16 v[70:73], v[176:179], v[224:227], v[70:73]
	v_mfma_f32_16x16x32_bf16 v[70:73], v[180:183], v[228:231], v[70:73]
	v_mfma_f32_16x16x32_bf16 v[66:69], v[188:191], v[228:231], v[66:69]
	v_mfma_f32_16x16x32_bf16 v[66:69], v[184:187], v[224:227], v[66:69]
	v_mfma_f32_16x16x32_bf16 v[74:77], v[184:187], v[216:219], v[74:77]
	v_mfma_f32_16x16x32_bf16 v[74:77], v[188:191], v[220:223], v[74:77]
	v_mfma_f32_16x16x32_bf16 v[78:81], v[180:183], v[220:223], v[78:81]
	v_mfma_f32_16x16x32_bf16 v[78:81], v[176:179], v[216:219], v[78:81]
	v_mfma_f32_16x16x32_bf16 v[94:97], v[176:179], v[208:211], v[94:97]
	v_mfma_f32_16x16x32_bf16 v[94:97], v[180:183], v[212:215], v[94:97]
	v_mfma_f32_16x16x32_bf16 v[90:93], v[188:191], v[212:215], v[90:93]
	v_mfma_f32_16x16x32_bf16 v[90:93], v[184:187], v[208:211], v[90:93]
	v_mfma_f32_16x16x32_bf16 v[106:109], v[184:187], v[192:195], v[106:109]
	v_mfma_f32_16x16x32_bf16 v[106:109], v[188:191], v[204:207], v[106:109]
	v_mfma_f32_16x16x32_bf16 v[110:113], v[180:183], v[204:207], v[110:113]
	v_mfma_f32_16x16x32_bf16 v[110:113], v[176:179], v[192:195], v[110:113]
	s_barrier
	s_mov_b32 m0, s38
	v_lshl_add_u64 v[172:173], v[172:173], 0, s[10:11]
	s_add_u32 s14, s14, 0x2b0080
	ds_read_b128 v[192:195], v145 offset:49152
	ds_read_b128 v[204:207], v145 offset:50176
	ds_read_b128 v[208:211], v145 offset:51200
	ds_read_b128 v[212:215], v145 offset:52224
	ds_read_b128 v[216:219], v145 offset:53248
	ds_read_b128 v[220:223], v145 offset:54272
	ds_read_b128 v[224:227], v145 offset:55296
	ds_read_b128 v[228:231], v145 offset:56320
	global_load_lds_dwordx4 v[172:173], off
	v_lshl_add_u64 v[172:173], v[196:197], 0, s[10:11]
	s_mov_b32 m0, s39
	s_addc_u32 s15, s15, 0
	global_load_lds_dwordx4 v[172:173], off
	v_lshl_add_u64 v[172:173], s[14:15], 0, v[132:133]
	s_mov_b32 m0, s40
	s_nop 0
	global_load_lds_dwordx4 v[172:173], off
	v_lshl_add_u64 v[172:173], s[14:15], 0, v[136:137]
	s_mov_b32 m0, s41
	s_nop 0
	global_load_lds_dwordx4 v[172:173], off
	v_lshl_add_u64 v[172:173], v[232:233], 0, s[10:11]
	s_mov_b32 m0, s26
	s_nop 0
	global_load_lds_dwordx4 v[172:173], off
	v_lshl_add_u64 v[172:173], v[234:235], 0, s[10:11]
	s_mov_b32 m0, s27
	s_nop 0
	global_load_lds_dwordx4 v[172:173], off
	s_waitcnt vmcnt(8)
	s_waitcnt lgkmcnt(0)
	s_barrier
	v_mfma_f32_16x16x32_bf16 v[62:65], v[150:153], v[192:195], v[62:65]
	v_mfma_f32_16x16x32_bf16 v[62:65], v[154:157], v[204:207], v[62:65]
	v_mfma_f32_16x16x32_bf16 v[58:61], v[168:171], v[204:207], v[58:61]
	v_mfma_f32_16x16x32_bf16 v[58:61], v[158:161], v[192:195], v[58:61]
	v_mfma_f32_16x16x32_bf16 v[50:53], v[158:161], v[208:211], v[50:53]
	v_mfma_f32_16x16x32_bf16 v[50:53], v[168:171], v[212:215], v[50:53]
	v_mfma_f32_16x16x32_bf16 v[54:57], v[154:157], v[212:215], v[54:57]
	v_mfma_f32_16x16x32_bf16 v[54:57], v[150:153], v[208:211], v[54:57]
	v_mfma_f32_16x16x32_bf16 v[38:41], v[150:153], v[216:219], v[38:41]
	v_mfma_f32_16x16x32_bf16 v[38:41], v[154:157], v[220:223], v[38:41]
	v_mfma_f32_16x16x32_bf16 v[34:37], v[168:171], v[220:223], v[34:37]
	v_mfma_f32_16x16x32_bf16 v[34:37], v[158:161], v[216:219], v[34:37]
	v_mfma_f32_16x16x32_bf16 v[18:21], v[158:161], v[224:227], v[18:21]
	v_mfma_f32_16x16x32_bf16 v[18:21], v[168:171], v[228:231], v[18:21]
	v_mfma_f32_16x16x32_bf16 v[22:25], v[154:157], v[228:231], v[22:25]
	v_mfma_f32_16x16x32_bf16 v[22:25], v[150:153], v[224:227], v[22:25]
	v_mfma_f32_16x16x32_bf16 v[6:9], v[176:179], v[224:227], v[6:9]
	v_mfma_f32_16x16x32_bf16 v[6:9], v[180:183], v[228:231], v[6:9]
	v_mfma_f32_16x16x32_bf16 v[2:5], v[188:191], v[228:231], v[2:5]
	v_mfma_f32_16x16x32_bf16 v[2:5], v[184:187], v[224:227], v[2:5]
	v_mfma_f32_16x16x32_bf16 v[10:13], v[184:187], v[216:219], v[10:13]
	v_mfma_f32_16x16x32_bf16 v[10:13], v[188:191], v[220:223], v[10:13]
	v_mfma_f32_16x16x32_bf16 v[14:17], v[180:183], v[220:223], v[14:17]
	v_mfma_f32_16x16x32_bf16 v[14:17], v[176:179], v[216:219], v[14:17]
	v_mfma_f32_16x16x32_bf16 v[30:33], v[176:179], v[208:211], v[30:33]
	v_mfma_f32_16x16x32_bf16 v[30:33], v[180:183], v[212:215], v[30:33]
	v_mfma_f32_16x16x32_bf16 v[26:29], v[188:191], v[212:215], v[26:29]
	v_mfma_f32_16x16x32_bf16 v[26:29], v[184:187], v[208:211], v[26:29]
	v_mfma_f32_16x16x32_bf16 v[42:45], v[184:187], v[192:195], v[42:45]
	v_mfma_f32_16x16x32_bf16 v[42:45], v[188:191], v[204:207], v[42:45]
	v_mfma_f32_16x16x32_bf16 v[46:49], v[180:183], v[204:207], v[46:49]
	v_mfma_f32_16x16x32_bf16 v[46:49], v[176:179], v[192:195], v[46:49]
	s_barrier
	s_add_u32 s12, s12, 0x100
	s_addc_u32 s13, s13, 0
	s_cmp_ge_u32 s42, s19
	s_mov_b32 s15, s42
	s_cbranch_scc0 .LBB0_1432
	s_lshl_b32 s4, s18, 21
	v_readlane_b32 s0, v249, 29
	v_lshl_or_b32 v130, s20, 8, v148
	v_mov_b32_e32 v139, 0
	s_add_u32 s4, s0, s4
	v_readlane_b32 s0, v249, 31
	v_or_b32_e32 v130, s25, v130
	v_cvt_pk_bf16_f32 v70, v70, v71
	v_cvt_pk_bf16_f32 v71, v72, v73
	v_cvt_pk_bf16_f32 v72, v66, v67
	v_add_u32_e32 v66, 0x80, v138
	v_mov_b32_e32 v67, v139
	s_addc_u32 s5, s0, 0
	v_ashrrev_i32_e32 v131, 31, v130
	v_lshlrev_b64 v[132:133], 13, v[138:139]
	v_cvt_pk_bf16_f32 v110, v110, v111
	v_cvt_pk_bf16_f32 v111, v112, v113
	v_cvt_pk_bf16_f32 v112, v106, v107
	v_or_b32_e32 v106, 16, v138
	v_mov_b32_e32 v107, v139
	v_lshlrev_b64 v[66:67], 13, v[66:67]
	v_cvt_pk_bf16_f32 v46, v46, v47
	v_cvt_pk_bf16_f32 v47, v48, v49
	v_cvt_pk_bf16_f32 v48, v42, v43
	v_add_u32_e32 v42, 0x90, v138
	v_mov_b32_e32 v43, v139
	v_lshl_add_u64 v[132:133], s[4:5], 0, v[132:133]
	v_lshlrev_b64 v[130:131], 1, v[130:131]
	v_lshlrev_b64 v[106:107], 13, v[106:107]
	v_cvt_pk_bf16_f32 v94, v94, v95
	v_cvt_pk_bf16_f32 v95, v96, v97
	v_cvt_pk_bf16_f32 v96, v90, v91
	v_or_b32_e32 v90, 32, v138
	v_mov_b32_e32 v91, v139
	v_lshl_add_u64 v[66:67], s[4:5], 0, v[66:67]
	v_lshlrev_b64 v[42:43], 13, v[42:43]
	v_cvt_pk_bf16_f32 v30, v30, v31
	v_cvt_pk_bf16_f32 v31, v32, v33
	v_cvt_pk_bf16_f32 v32, v26, v27
	v_add_u32_e32 v26, 0xa0, v138
	v_mov_b32_e32 v27, v139
	v_lshl_add_u64 v[132:133], v[132:133], 0, v[130:131]
	v_cvt_pk_bf16_f32 v113, v108, v109
	v_lshl_add_u64 v[106:107], s[4:5], 0, v[106:107]
	v_lshlrev_b64 v[90:91], 13, v[90:91]
	v_cvt_pk_bf16_f32 v78, v78, v79
	v_cvt_pk_bf16_f32 v79, v80, v81
	v_cvt_pk_bf16_f32 v80, v74, v75
	v_or_b32_e32 v74, 48, v138
	v_mov_b32_e32 v75, v139
	v_lshl_add_u64 v[66:67], v[66:67], 0, v[130:131]
	v_cvt_pk_bf16_f32 v49, v44, v45
	v_lshl_add_u64 v[42:43], s[4:5], 0, v[42:43]
	v_lshlrev_b64 v[26:27], 13, v[26:27]
	v_add_u32_e32 v138, 0xb0, v138
	global_store_dwordx4 v[132:133], v[110:113], off offset:256
	v_cvt_pk_bf16_f32 v97, v92, v93
	v_lshl_add_u64 v[90:91], s[4:5], 0, v[90:91]
	v_lshl_add_u64 v[110:111], v[106:107], 0, v[130:131]
	v_lshlrev_b64 v[74:75], 13, v[74:75]
	global_store_dwordx4 v[66:67], v[46:49], off offset:256
	v_cvt_pk_bf16_f32 v33, v28, v29
	v_lshl_add_u64 v[26:27], s[4:5], 0, v[26:27]
	v_lshl_add_u64 v[46:47], v[42:43], 0, v[130:131]
	v_cvt_pk_bf16_f32 v14, v14, v15
	v_cvt_pk_bf16_f32 v15, v16, v17
	v_cvt_pk_bf16_f32 v16, v10, v11
	v_lshlrev_b64 v[10:11], 13, v[138:139]
	global_store_dwordx4 v[110:111], v[94:97], off offset:256
	v_cvt_pk_bf16_f32 v81, v76, v77
	v_lshl_add_u64 v[74:75], s[4:5], 0, v[74:75]
	v_lshl_add_u64 v[94:95], v[90:91], 0, v[130:131]
	global_store_dwordx4 v[46:47], v[30:33], off offset:256
	v_cvt_pk_bf16_f32 v17, v12, v13
	v_lshl_add_u64 v[10:11], s[4:5], 0, v[10:11]
	v_lshl_add_u64 v[30:31], v[26:27], 0, v[130:131]
	v_cvt_pk_bf16_f32 v126, v126, v127
	v_cvt_pk_bf16_f32 v127, v128, v129
	v_cvt_pk_bf16_f32 v128, v122, v123
	v_cvt_pk_bf16_f32 v129, v124, v125
	v_cvt_pk_bf16_f32 v106, v118, v119
	v_cvt_pk_bf16_f32 v107, v120, v121
	v_cvt_pk_bf16_f32 v108, v114, v115
	v_cvt_pk_bf16_f32 v109, v116, v117
	v_cvt_pk_bf16_f32 v90, v102, v103
	v_cvt_pk_bf16_f32 v91, v104, v105
	v_cvt_pk_bf16_f32 v92, v98, v99
	v_cvt_pk_bf16_f32 v93, v100, v101
	global_store_dwordx4 v[94:95], v[78:81], off offset:256
	v_cvt_pk_bf16_f32 v76, v82, v83
	v_cvt_pk_bf16_f32 v77, v84, v85
	v_lshl_add_u64 v[78:79], v[74:75], 0, v[130:131]
	v_cvt_pk_bf16_f32 v74, v86, v87
	v_cvt_pk_bf16_f32 v75, v88, v89
	v_cvt_pk_bf16_f32 v73, v68, v69
	v_cvt_pk_bf16_f32 v62, v62, v63
	v_cvt_pk_bf16_f32 v63, v64, v65
	v_cvt_pk_bf16_f32 v64, v58, v59
	v_cvt_pk_bf16_f32 v65, v60, v61
	v_cvt_pk_bf16_f32 v42, v54, v55
	v_cvt_pk_bf16_f32 v43, v56, v57
	v_cvt_pk_bf16_f32 v44, v50, v51
	v_cvt_pk_bf16_f32 v45, v52, v53
	v_cvt_pk_bf16_f32 v26, v38, v39
	v_cvt_pk_bf16_f32 v27, v40, v41
	v_cvt_pk_bf16_f32 v28, v34, v35
	v_cvt_pk_bf16_f32 v29, v36, v37
	global_store_dwordx4 v[30:31], v[14:17], off offset:256
	v_cvt_pk_bf16_f32 v12, v18, v19
	v_cvt_pk_bf16_f32 v13, v20, v21
	v_lshl_add_u64 v[14:15], v[10:11], 0, v[130:131]
	v_cvt_pk_bf16_f32 v10, v22, v23
	v_cvt_pk_bf16_f32 v11, v24, v25
	v_cvt_pk_bf16_f32 v6, v6, v7
	v_cvt_pk_bf16_f32 v7, v8, v9
	v_cvt_pk_bf16_f32 v8, v2, v3
	v_cvt_pk_bf16_f32 v9, v4, v5
	global_store_dwordx4 v[132:133], v[126:129], off
	global_store_dwordx4 v[110:111], v[106:109], off
	global_store_dwordx4 v[94:95], v[90:93], off
	global_store_dwordx4 v[78:79], v[74:77], off
	global_store_dwordx4 v[78:79], v[70:73], off offset:256
	global_store_dwordx4 v[66:67], v[62:65], off
	global_store_dwordx4 v[46:47], v[42:45], off
	global_store_dwordx4 v[30:31], v[26:29], off
	global_store_dwordx4 v[14:15], v[10:13], off
	global_store_dwordx4 v[14:15], v[6:9], off offset:256
	s_waitcnt vmcnt(0)
	s_cmpk_lt_u32 s3, 0x100
	s_cbranch_scc0 .LBB0_1435
	s_barrier

.LBB0_1565:
	ds_read_b128 v[130:133], v204
	ds_read_b128 v[134:137], v204 offset:1024
	ds_read_b128 v[138:141], v204 offset:2048
	ds_read_b128 v[142:145], v204 offset:3072
	ds_read_b128 v[146:149], v205
	ds_read_b128 v[150:153], v205 offset:1024
	ds_read_b128 v[154:157], v205 offset:2048
	ds_read_b128 v[158:161], v205 offset:3072
	s_add_u32 s8, s6, 0xfff00080
	s_addc_u32 s9, s7, -1
	s_cmp_eq_u32 s66, 60
	s_cselect_b32 s73, s41, s9
	s_cselect_b32 s72, s50, s8
	s_cselect_b32 s9, s13, s57
	s_cselect_b32 s8, s51, s56
	s_add_i32 m0, s42, 0xc000
	ds_read_b128 v[184:187], v206
	ds_read_b128 v[188:191], v206 offset:1024
	ds_read_b128 v[192:195], v206 offset:2048
	ds_read_b128 v[210:213], v206 offset:3072
	ds_read_b128 v[214:217], v206 offset:4096
	ds_read_b128 v[218:221], v206 offset:5120
	ds_read_b128 v[222:225], v206 offset:6144
	ds_read_b128 v[226:229], v206 offset:7168
	global_load_lds_dwordx4 v180, s[6:7]
	s_add_i32 m0, s42, 0xe000
	s_nop 0
	global_load_lds_dwordx4 v182, s[6:7]
	s_waitcnt vmcnt(8)
	s_waitcnt lgkmcnt(0)
	s_barrier
	v_mfma_f32_16x16x32_bf16 v[126:129], v[130:133], v[184:187], v[126:129]
	v_mfma_f32_16x16x32_bf16 v[126:129], v[134:137], v[188:191], v[126:129]
	v_mfma_f32_16x16x32_bf16 v[122:125], v[142:145], v[188:191], v[122:125]
	v_mfma_f32_16x16x32_bf16 v[122:125], v[138:141], v[184:187], v[122:125]
	v_mfma_f32_16x16x32_bf16 v[106:109], v[138:141], v[192:195], v[106:109]
	v_mfma_f32_16x16x32_bf16 v[106:109], v[142:145], v[210:213], v[106:109]
	v_mfma_f32_16x16x32_bf16 v[110:113], v[134:137], v[210:213], v[110:113]
	v_mfma_f32_16x16x32_bf16 v[110:113], v[130:133], v[192:195], v[110:113]
	v_mfma_f32_16x16x32_bf16 v[94:97], v[130:133], v[214:217], v[94:97]
	v_mfma_f32_16x16x32_bf16 v[94:97], v[134:137], v[218:221], v[94:97]
	v_mfma_f32_16x16x32_bf16 v[90:93], v[142:145], v[218:221], v[90:93]
	v_mfma_f32_16x16x32_bf16 v[90:93], v[138:141], v[214:217], v[90:93]
	v_mfma_f32_16x16x32_bf16 v[74:77], v[138:141], v[222:225], v[74:77]
	v_mfma_f32_16x16x32_bf16 v[74:77], v[142:145], v[226:229], v[74:77]
	v_mfma_f32_16x16x32_bf16 v[78:81], v[134:137], v[226:229], v[78:81]
	v_mfma_f32_16x16x32_bf16 v[78:81], v[130:133], v[222:225], v[78:81]
	v_mfma_f32_16x16x32_bf16 v[70:73], v[146:149], v[222:225], v[70:73]
	v_mfma_f32_16x16x32_bf16 v[70:73], v[150:153], v[226:229], v[70:73]
	v_mfma_f32_16x16x32_bf16 v[66:69], v[158:161], v[226:229], v[66:69]
	v_mfma_f32_16x16x32_bf16 v[66:69], v[154:157], v[222:225], v[66:69]
	v_mfma_f32_16x16x32_bf16 v[82:85], v[154:157], v[214:217], v[82:85]
	v_mfma_f32_16x16x32_bf16 v[82:85], v[158:161], v[218:221], v[82:85]
	v_mfma_f32_16x16x32_bf16 v[86:89], v[150:153], v[218:221], v[86:89]
	v_mfma_f32_16x16x32_bf16 v[86:89], v[146:149], v[214:217], v[86:89]
	v_mfma_f32_16x16x32_bf16 v[102:105], v[146:149], v[192:195], v[102:105]
	v_mfma_f32_16x16x32_bf16 v[102:105], v[150:153], v[210:213], v[102:105]
	v_mfma_f32_16x16x32_bf16 v[98:101], v[158:161], v[210:213], v[98:101]
	v_mfma_f32_16x16x32_bf16 v[98:101], v[154:157], v[192:195], v[98:101]
	v_mfma_f32_16x16x32_bf16 v[114:117], v[154:157], v[184:187], v[114:117]
	v_mfma_f32_16x16x32_bf16 v[114:117], v[158:161], v[188:191], v[114:117]
	v_mfma_f32_16x16x32_bf16 v[118:121], v[150:153], v[188:191], v[118:121]
	v_mfma_f32_16x16x32_bf16 v[118:121], v[146:149], v[184:187], v[118:121]
	s_barrier
	s_add_i32 s67, s54, s35
	s_mov_b32 m0, s67
	ds_read_b128 v[184:187], v206 offset:16384
	ds_read_b128 v[188:191], v206 offset:17408
	ds_read_b128 v[192:195], v206 offset:18432
	ds_read_b128 v[210:213], v206 offset:19456
	ds_read_b128 v[214:217], v206 offset:20480
	ds_read_b128 v[218:221], v206 offset:21504
	ds_read_b128 v[222:225], v206 offset:22528
	ds_read_b128 v[226:229], v206 offset:23552
	global_load_lds_dwordx4 v168, s[8:9]
	s_add_i32 m0, s67, 0x2000
	s_add_u32 s68, s8, 0x100000
	s_addc_u32 s69, s9, 0
	s_add_i32 s67, s55, s35
	global_load_lds_dwordx4 v170, s[8:9]
	s_mov_b32 m0, s67
	s_nop 0
	global_load_lds_dwordx4 v168, s[68:69]
	s_add_i32 m0, s67, 0x2000
	s_nop 0
	global_load_lds_dwordx4 v170, s[68:69]
	s_mov_b32 m0, s42
	s_nop 0
	global_load_lds_dwordx4 v168, s[72:73]
	s_mov_b32 m0, s43
	s_nop 0
	global_load_lds_dwordx4 v170, s[72:73]
	s_waitcnt vmcnt(8)
	s_waitcnt lgkmcnt(0)
	s_barrier
	v_mfma_f32_16x16x32_bf16 v[62:65], v[130:133], v[184:187], v[62:65]
	v_mfma_f32_16x16x32_bf16 v[62:65], v[134:137], v[188:191], v[62:65]
	v_mfma_f32_16x16x32_bf16 v[58:61], v[142:145], v[188:191], v[58:61]
	v_mfma_f32_16x16x32_bf16 v[58:61], v[138:141], v[184:187], v[58:61]
	v_mfma_f32_16x16x32_bf16 v[42:45], v[138:141], v[192:195], v[42:45]
	v_mfma_f32_16x16x32_bf16 v[42:45], v[142:145], v[210:213], v[42:45]
	v_mfma_f32_16x16x32_bf16 v[46:49], v[134:137], v[210:213], v[46:49]
	v_mfma_f32_16x16x32_bf16 v[46:49], v[130:133], v[192:195], v[46:49]
	v_mfma_f32_16x16x32_bf16 v[30:33], v[130:133], v[214:217], v[30:33]
	v_mfma_f32_16x16x32_bf16 v[30:33], v[134:137], v[218:221], v[30:33]
	v_mfma_f32_16x16x32_bf16 v[26:29], v[142:145], v[218:221], v[26:29]
	v_mfma_f32_16x16x32_bf16 v[26:29], v[138:141], v[214:217], v[26:29]
	v_mfma_f32_16x16x32_bf16 v[10:13], v[138:141], v[222:225], v[10:13]
	v_mfma_f32_16x16x32_bf16 v[10:13], v[142:145], v[226:229], v[10:13]
	v_mfma_f32_16x16x32_bf16 v[14:17], v[134:137], v[226:229], v[14:17]
	v_mfma_f32_16x16x32_bf16 v[14:17], v[130:133], v[222:225], v[14:17]
	v_mfma_f32_16x16x32_bf16 v[6:9], v[146:149], v[222:225], v[6:9]
	v_mfma_f32_16x16x32_bf16 v[6:9], v[150:153], v[226:229], v[6:9]
	v_mfma_f32_16x16x32_bf16 v[2:5], v[158:161], v[226:229], v[2:5]
	v_mfma_f32_16x16x32_bf16 v[2:5], v[154:157], v[222:225], v[2:5]
	v_mfma_f32_16x16x32_bf16 v[18:21], v[154:157], v[214:217], v[18:21]
	v_mfma_f32_16x16x32_bf16 v[18:21], v[158:161], v[218:221], v[18:21]
	v_mfma_f32_16x16x32_bf16 v[22:25], v[150:153], v[218:221], v[22:25]
	v_mfma_f32_16x16x32_bf16 v[22:25], v[146:149], v[214:217], v[22:25]
	v_mfma_f32_16x16x32_bf16 v[38:41], v[146:149], v[192:195], v[38:41]
	v_mfma_f32_16x16x32_bf16 v[38:41], v[150:153], v[210:213], v[38:41]
	v_mfma_f32_16x16x32_bf16 v[34:37], v[158:161], v[210:213], v[34:37]
	v_mfma_f32_16x16x32_bf16 v[34:37], v[154:157], v[192:195], v[34:37]
	v_mfma_f32_16x16x32_bf16 v[50:53], v[154:157], v[184:187], v[50:53]
	v_mfma_f32_16x16x32_bf16 v[50:53], v[158:161], v[188:191], v[50:53]
	v_mfma_f32_16x16x32_bf16 v[54:57], v[150:153], v[188:191], v[54:57]
	v_mfma_f32_16x16x32_bf16 v[54:57], v[146:149], v[184:187], v[54:57]
	s_barrier
	s_add_i32 s67, 0, 0x18000
	s_add_i32 s70, 0, 0x1c000
	v_add_u32_e32 v142, s67, v203
	v_add_u32_e32 v158, s70, v203
	ds_read_b128 v[130:133], v142
	ds_read_b128 v[134:137], v142 offset:1024
	ds_read_b128 v[138:141], v142 offset:2048
	ds_read_b128 v[142:145], v142 offset:3072
	ds_read_b128 v[146:149], v158
	ds_read_b128 v[150:153], v158 offset:1024
	ds_read_b128 v[154:157], v158 offset:2048
	ds_read_b128 v[158:161], v158 offset:3072
	s_add_u32 s68, s72, 0x100000
	s_addc_u32 s69, s73, 0
	s_mov_b32 m0, s44
	ds_read_b128 v[184:187], v206 offset:32768
	ds_read_b128 v[188:191], v206 offset:33792
	ds_read_b128 v[192:195], v206 offset:34816
	ds_read_b128 v[210:213], v206 offset:35840
	ds_read_b128 v[214:217], v206 offset:36864
	ds_read_b128 v[218:221], v206 offset:37888
	ds_read_b128 v[222:225], v206 offset:38912
	ds_read_b128 v[226:229], v206 offset:39936
	global_load_lds_dwordx4 v168, s[68:69]
	s_mov_b32 m0, s45
	s_nop 0
	global_load_lds_dwordx4 v170, s[68:69]
	s_waitcnt vmcnt(8)
	s_waitcnt lgkmcnt(0)
	s_barrier
	v_mfma_f32_16x16x32_bf16 v[126:129], v[130:133], v[184:187], v[126:129]
	v_mfma_f32_16x16x32_bf16 v[126:129], v[134:137], v[188:191], v[126:129]
	v_mfma_f32_16x16x32_bf16 v[122:125], v[142:145], v[188:191], v[122:125]
	v_mfma_f32_16x16x32_bf16 v[122:125], v[138:141], v[184:187], v[122:125]
	v_mfma_f32_16x16x32_bf16 v[106:109], v[138:141], v[192:195], v[106:109]
	v_mfma_f32_16x16x32_bf16 v[106:109], v[142:145], v[210:213], v[106:109]
	v_mfma_f32_16x16x32_bf16 v[110:113], v[134:137], v[210:213], v[110:113]
	v_mfma_f32_16x16x32_bf16 v[110:113], v[130:133], v[192:195], v[110:113]
	v_mfma_f32_16x16x32_bf16 v[94:97], v[130:133], v[214:217], v[94:97]
	v_mfma_f32_16x16x32_bf16 v[94:97], v[134:137], v[218:221], v[94:97]
	v_mfma_f32_16x16x32_bf16 v[90:93], v[142:145], v[218:221], v[90:93]
	v_mfma_f32_16x16x32_bf16 v[90:93], v[138:141], v[214:217], v[90:93]
	v_mfma_f32_16x16x32_bf16 v[74:77], v[138:141], v[222:225], v[74:77]
	v_mfma_f32_16x16x32_bf16 v[74:77], v[142:145], v[226:229], v[74:77]
	v_mfma_f32_16x16x32_bf16 v[78:81], v[134:137], v[226:229], v[78:81]
	v_mfma_f32_16x16x32_bf16 v[78:81], v[130:133], v[222:225], v[78:81]
	v_mfma_f32_16x16x32_bf16 v[70:73], v[146:149], v[222:225], v[70:73]
	v_mfma_f32_16x16x32_bf16 v[70:73], v[150:153], v[226:229], v[70:73]
	v_mfma_f32_16x16x32_bf16 v[66:69], v[158:161], v[226:229], v[66:69]
	v_mfma_f32_16x16x32_bf16 v[66:69], v[154:157], v[222:225], v[66:69]
	v_mfma_f32_16x16x32_bf16 v[82:85], v[154:157], v[214:217], v[82:85]
	v_mfma_f32_16x16x32_bf16 v[82:85], v[158:161], v[218:221], v[82:85]
	v_mfma_f32_16x16x32_bf16 v[86:89], v[150:153], v[218:221], v[86:89]
	v_mfma_f32_16x16x32_bf16 v[86:89], v[146:149], v[214:217], v[86:89]
	v_mfma_f32_16x16x32_bf16 v[102:105], v[146:149], v[192:195], v[102:105]
	v_mfma_f32_16x16x32_bf16 v[102:105], v[150:153], v[210:213], v[102:105]
	v_mfma_f32_16x16x32_bf16 v[98:101], v[158:161], v[210:213], v[98:101]
	v_mfma_f32_16x16x32_bf16 v[98:101], v[154:157], v[192:195], v[98:101]
	v_mfma_f32_16x16x32_bf16 v[114:117], v[154:157], v[184:187], v[114:117]
	v_mfma_f32_16x16x32_bf16 v[114:117], v[158:161], v[188:191], v[114:117]
	v_mfma_f32_16x16x32_bf16 v[118:121], v[150:153], v[188:191], v[118:121]
	v_mfma_f32_16x16x32_bf16 v[118:121], v[146:149], v[184:187], v[118:121]
	s_barrier
	s_add_u32 s68, s72, 0x80
	s_addc_u32 s69, s73, 0
	s_add_u32 s8, s8, 0x80
	s_addc_u32 s9, s9, 0
	s_add_i32 s67, s67, s35
	s_mov_b32 m0, s67
	ds_read_b128 v[184:187], v206 offset:49152
	ds_read_b128 v[188:191], v206 offset:50176
	ds_read_b128 v[192:195], v206 offset:51200
	ds_read_b128 v[210:213], v206 offset:52224
	ds_read_b128 v[214:217], v206 offset:53248
	ds_read_b128 v[218:221], v206 offset:54272
	ds_read_b128 v[222:225], v206 offset:55296
	ds_read_b128 v[226:229], v206 offset:56320
	global_load_lds_dwordx4 v168, s[8:9]
	s_add_i32 m0, s67, 0x2000
	s_add_i32 s67, s70, s35
	global_load_lds_dwordx4 v170, s[8:9]
	s_add_u32 s8, s8, 0x100000
	s_addc_u32 s9, s9, 0
	s_mov_b32 m0, s67
	s_nop 0
	global_load_lds_dwordx4 v168, s[8:9]
	s_add_i32 m0, s67, 0x2000
	s_nop 0
	global_load_lds_dwordx4 v170, s[8:9]
	s_mov_b32 m0, s48
	s_nop 0
	global_load_lds_dwordx4 v168, s[68:69]
	s_mov_b32 m0, s49
	s_nop 0
	global_load_lds_dwordx4 v170, s[68:69]
	s_waitcnt vmcnt(8)
	s_waitcnt lgkmcnt(0)
	s_barrier
	v_mfma_f32_16x16x32_bf16 v[62:65], v[130:133], v[184:187], v[62:65]
	v_mfma_f32_16x16x32_bf16 v[62:65], v[134:137], v[188:191], v[62:65]
	v_mfma_f32_16x16x32_bf16 v[58:61], v[142:145], v[188:191], v[58:61]
	v_mfma_f32_16x16x32_bf16 v[58:61], v[138:141], v[184:187], v[58:61]
	v_mfma_f32_16x16x32_bf16 v[42:45], v[138:141], v[192:195], v[42:45]
	v_mfma_f32_16x16x32_bf16 v[42:45], v[142:145], v[210:213], v[42:45]
	v_mfma_f32_16x16x32_bf16 v[46:49], v[134:137], v[210:213], v[46:49]
	v_mfma_f32_16x16x32_bf16 v[46:49], v[130:133], v[192:195], v[46:49]
	v_mfma_f32_16x16x32_bf16 v[30:33], v[130:133], v[214:217], v[30:33]
	v_mfma_f32_16x16x32_bf16 v[30:33], v[134:137], v[218:221], v[30:33]
	v_mfma_f32_16x16x32_bf16 v[26:29], v[142:145], v[218:221], v[26:29]
	v_mfma_f32_16x16x32_bf16 v[26:29], v[138:141], v[214:217], v[26:29]
	v_mfma_f32_16x16x32_bf16 v[10:13], v[138:141], v[222:225], v[10:13]
	v_mfma_f32_16x16x32_bf16 v[10:13], v[142:145], v[226:229], v[10:13]
	v_mfma_f32_16x16x32_bf16 v[14:17], v[134:137], v[226:229], v[14:17]
	v_mfma_f32_16x16x32_bf16 v[14:17], v[130:133], v[222:225], v[14:17]
	v_mfma_f32_16x16x32_bf16 v[6:9], v[146:149], v[222:225], v[6:9]
	v_mfma_f32_16x16x32_bf16 v[6:9], v[150:153], v[226:229], v[6:9]
	v_mfma_f32_16x16x32_bf16 v[2:5], v[158:161], v[226:229], v[2:5]
	v_mfma_f32_16x16x32_bf16 v[2:5], v[154:157], v[222:225], v[2:5]
	v_mfma_f32_16x16x32_bf16 v[18:21], v[154:157], v[214:217], v[18:21]
	v_mfma_f32_16x16x32_bf16 v[18:21], v[158:161], v[218:221], v[18:21]
	v_mfma_f32_16x16x32_bf16 v[22:25], v[150:153], v[218:221], v[22:25]
	v_mfma_f32_16x16x32_bf16 v[22:25], v[146:149], v[214:217], v[22:25]
	v_mfma_f32_16x16x32_bf16 v[38:41], v[146:149], v[192:195], v[38:41]
	v_mfma_f32_16x16x32_bf16 v[38:41], v[150:153], v[210:213], v[38:41]
	v_mfma_f32_16x16x32_bf16 v[34:37], v[158:161], v[210:213], v[34:37]
	v_mfma_f32_16x16x32_bf16 v[34:37], v[154:157], v[192:195], v[34:37]
	v_mfma_f32_16x16x32_bf16 v[50:53], v[154:157], v[184:187], v[50:53]
	v_mfma_f32_16x16x32_bf16 v[50:53], v[158:161], v[188:191], v[50:53]
	v_mfma_f32_16x16x32_bf16 v[54:57], v[150:153], v[188:191], v[54:57]
	v_mfma_f32_16x16x32_bf16 v[54:57], v[146:149], v[184:187], v[54:57]
	s_barrier
	s_add_i32 s66, s66, 2
	s_add_u32 s6, s6, 0x100
	s_addc_u32 s7, s7, 0
	s_add_u32 s56, s56, 0x100
	s_addc_u32 s57, s57, 0
	s_cmp_gt_u32 s66, 61
	s_cbranch_scc0 .LBB0_1565
	s_and_b64 vcc, exec, s[24:25]
	s_cbranch_vccz .LBB0_1568
	s_barrier

.LBB0_2230:
	ds_read_b128 v[142:145], v154
	ds_read_b128 v[158:161], v154 offset:1024
	ds_read_b128 v[168:171], v154 offset:2048
	ds_read_b128 v[176:179], v154 offset:3072
	ds_read_b128 v[180:183], v155
	ds_read_b128 v[184:187], v155 offset:1024
	ds_read_b128 v[188:191], v155 offset:2048
	ds_read_b128 v[192:195], v155 offset:3072
	s_add_u32 s24, s22, 0xfff00080
	s_addc_u32 s25, s23, -1
	s_cmp_eq_u32 s48, 60
	s_cselect_b32 s27, s19, s25
	s_cselect_b32 s26, s44, s24
	s_cselect_b32 s25, s7, s47
	s_cselect_b32 s24, s45, s46
	s_mov_b32 m0, s40
	ds_read_b128 v[204:207], v156
	ds_read_b128 v[208:211], v156 offset:1024
	ds_read_b128 v[212:215], v156 offset:2048
	ds_read_b128 v[216:219], v156 offset:3072
	ds_read_b128 v[220:223], v156 offset:4096
	ds_read_b128 v[224:227], v156 offset:5120
	ds_read_b128 v[228:231], v156 offset:6144
	ds_read_b128 v[232:235], v156 offset:7168
	global_load_lds_dwordx4 v138, s[22:23]
	s_mov_b32 m0, s41
	s_nop 0
	global_load_lds_dwordx4 v140, s[22:23]
	s_waitcnt vmcnt(8)
	s_waitcnt lgkmcnt(0)
	s_barrier
	v_mfma_f32_16x16x32_bf16 v[126:129], v[142:145], v[204:207], v[126:129]
	v_mfma_f32_16x16x32_bf16 v[126:129], v[158:161], v[208:211], v[126:129]
	v_mfma_f32_16x16x32_bf16 v[122:125], v[176:179], v[208:211], v[122:125]
	v_mfma_f32_16x16x32_bf16 v[122:125], v[168:171], v[204:207], v[122:125]
	v_mfma_f32_16x16x32_bf16 v[106:109], v[168:171], v[212:215], v[106:109]
	v_mfma_f32_16x16x32_bf16 v[106:109], v[176:179], v[216:219], v[106:109]
	v_mfma_f32_16x16x32_bf16 v[110:113], v[158:161], v[216:219], v[110:113]
	v_mfma_f32_16x16x32_bf16 v[110:113], v[142:145], v[212:215], v[110:113]
	v_mfma_f32_16x16x32_bf16 v[94:97], v[142:145], v[220:223], v[94:97]
	v_mfma_f32_16x16x32_bf16 v[94:97], v[158:161], v[224:227], v[94:97]
	v_mfma_f32_16x16x32_bf16 v[90:93], v[176:179], v[224:227], v[90:93]
	v_mfma_f32_16x16x32_bf16 v[90:93], v[168:171], v[220:223], v[90:93]
	v_mfma_f32_16x16x32_bf16 v[74:77], v[168:171], v[228:231], v[74:77]
	v_mfma_f32_16x16x32_bf16 v[74:77], v[176:179], v[232:235], v[74:77]
	v_mfma_f32_16x16x32_bf16 v[78:81], v[158:161], v[232:235], v[78:81]
	v_mfma_f32_16x16x32_bf16 v[78:81], v[142:145], v[228:231], v[78:81]
	v_mfma_f32_16x16x32_bf16 v[70:73], v[180:183], v[228:231], v[70:73]
	v_mfma_f32_16x16x32_bf16 v[70:73], v[184:187], v[232:235], v[70:73]
	v_mfma_f32_16x16x32_bf16 v[66:69], v[192:195], v[232:235], v[66:69]
	v_mfma_f32_16x16x32_bf16 v[66:69], v[188:191], v[228:231], v[66:69]
	v_mfma_f32_16x16x32_bf16 v[82:85], v[188:191], v[220:223], v[82:85]
	v_mfma_f32_16x16x32_bf16 v[82:85], v[192:195], v[224:227], v[82:85]
	v_mfma_f32_16x16x32_bf16 v[86:89], v[184:187], v[224:227], v[86:89]
	v_mfma_f32_16x16x32_bf16 v[86:89], v[180:183], v[220:223], v[86:89]
	v_mfma_f32_16x16x32_bf16 v[102:105], v[180:183], v[212:215], v[102:105]
	v_mfma_f32_16x16x32_bf16 v[102:105], v[184:187], v[216:219], v[102:105]
	v_mfma_f32_16x16x32_bf16 v[98:101], v[192:195], v[216:219], v[98:101]
	v_mfma_f32_16x16x32_bf16 v[98:101], v[188:191], v[212:215], v[98:101]
	v_mfma_f32_16x16x32_bf16 v[114:117], v[188:191], v[204:207], v[114:117]
	v_mfma_f32_16x16x32_bf16 v[114:117], v[192:195], v[208:211], v[114:117]
	v_mfma_f32_16x16x32_bf16 v[118:121], v[184:187], v[208:211], v[118:121]
	v_mfma_f32_16x16x32_bf16 v[118:121], v[180:183], v[204:207], v[118:121]
	s_barrier
	s_add_i32 s49, s38, s28
	s_mov_b32 m0, s49
	ds_read_b128 v[204:207], v156 offset:16384
	ds_read_b128 v[208:211], v156 offset:17408
	ds_read_b128 v[212:215], v156 offset:18432
	ds_read_b128 v[216:219], v156 offset:19456
	ds_read_b128 v[220:223], v156 offset:20480
	ds_read_b128 v[224:227], v156 offset:21504
	ds_read_b128 v[228:231], v156 offset:22528
	ds_read_b128 v[232:235], v156 offset:23552
	global_load_lds_dwordx4 v132, s[24:25]
	s_add_i32 m0, s49, 0x2000
	s_add_u32 s50, s24, 0x100000
	s_addc_u32 s51, s25, 0
	s_add_i32 s49, s39, s28
	global_load_lds_dwordx4 v136, s[24:25]
	s_mov_b32 m0, s49
	s_nop 0
	global_load_lds_dwordx4 v132, s[50:51]
	s_add_i32 m0, s49, 0x2000
	s_nop 0
	global_load_lds_dwordx4 v136, s[50:51]
	s_mov_b32 m0, s30
	s_nop 0
	global_load_lds_dwordx4 v130, s[26:27]
	s_mov_b32 m0, s31
	s_nop 0
	global_load_lds_dwordx4 v134, s[26:27]
	s_waitcnt vmcnt(8)
	s_waitcnt lgkmcnt(0)
	s_barrier
	v_mfma_f32_16x16x32_bf16 v[62:65], v[142:145], v[204:207], v[62:65]
	v_mfma_f32_16x16x32_bf16 v[62:65], v[158:161], v[208:211], v[62:65]
	v_mfma_f32_16x16x32_bf16 v[58:61], v[176:179], v[208:211], v[58:61]
	v_mfma_f32_16x16x32_bf16 v[58:61], v[168:171], v[204:207], v[58:61]
	v_mfma_f32_16x16x32_bf16 v[42:45], v[168:171], v[212:215], v[42:45]
	v_mfma_f32_16x16x32_bf16 v[42:45], v[176:179], v[216:219], v[42:45]
	v_mfma_f32_16x16x32_bf16 v[46:49], v[158:161], v[216:219], v[46:49]
	v_mfma_f32_16x16x32_bf16 v[46:49], v[142:145], v[212:215], v[46:49]
	v_mfma_f32_16x16x32_bf16 v[30:33], v[142:145], v[220:223], v[30:33]
	v_mfma_f32_16x16x32_bf16 v[30:33], v[158:161], v[224:227], v[30:33]
	v_mfma_f32_16x16x32_bf16 v[26:29], v[176:179], v[224:227], v[26:29]
	v_mfma_f32_16x16x32_bf16 v[26:29], v[168:171], v[220:223], v[26:29]
	v_mfma_f32_16x16x32_bf16 v[10:13], v[168:171], v[228:231], v[10:13]
	v_mfma_f32_16x16x32_bf16 v[10:13], v[176:179], v[232:235], v[10:13]
	v_mfma_f32_16x16x32_bf16 v[14:17], v[158:161], v[232:235], v[14:17]
	v_mfma_f32_16x16x32_bf16 v[14:17], v[142:145], v[228:231], v[14:17]
	v_mfma_f32_16x16x32_bf16 v[6:9], v[180:183], v[228:231], v[6:9]
	v_mfma_f32_16x16x32_bf16 v[6:9], v[184:187], v[232:235], v[6:9]
	v_mfma_f32_16x16x32_bf16 v[2:5], v[192:195], v[232:235], v[2:5]
	v_mfma_f32_16x16x32_bf16 v[2:5], v[188:191], v[228:231], v[2:5]
	v_mfma_f32_16x16x32_bf16 v[18:21], v[188:191], v[220:223], v[18:21]
	v_mfma_f32_16x16x32_bf16 v[18:21], v[192:195], v[224:227], v[18:21]
	v_mfma_f32_16x16x32_bf16 v[22:25], v[184:187], v[224:227], v[22:25]
	v_mfma_f32_16x16x32_bf16 v[22:25], v[180:183], v[220:223], v[22:25]
	v_mfma_f32_16x16x32_bf16 v[38:41], v[180:183], v[212:215], v[38:41]
	v_mfma_f32_16x16x32_bf16 v[38:41], v[184:187], v[216:219], v[38:41]
	v_mfma_f32_16x16x32_bf16 v[34:37], v[192:195], v[216:219], v[34:37]
	v_mfma_f32_16x16x32_bf16 v[34:37], v[188:191], v[212:215], v[34:37]
	v_mfma_f32_16x16x32_bf16 v[50:53], v[188:191], v[204:207], v[50:53]
	v_mfma_f32_16x16x32_bf16 v[50:53], v[192:195], v[208:211], v[50:53]
	v_mfma_f32_16x16x32_bf16 v[54:57], v[184:187], v[208:211], v[54:57]
	v_mfma_f32_16x16x32_bf16 v[54:57], v[180:183], v[204:207], v[54:57]
	s_barrier
	s_add_i32 s49, 0, 0x18000
	v_add_u32_e32 v157, s49, v152
	s_add_i32 s50, 0, 0x1c000
	ds_read_b128 v[142:145], v157
	ds_read_b128 v[158:161], v157 offset:1024
	ds_read_b128 v[168:171], v157 offset:2048
	ds_read_b128 v[176:179], v157 offset:3072
	v_add_u32_e32 v157, s50, v152
	ds_read_b128 v[180:183], v157
	ds_read_b128 v[184:187], v157 offset:1024
	ds_read_b128 v[188:191], v157 offset:2048
	ds_read_b128 v[192:195], v157 offset:3072
	s_add_u32 s26, s26, 0x100000
	s_addc_u32 s27, s27, 0
	s_mov_b32 m0, s33
	ds_read_b128 v[204:207], v156 offset:32768
	ds_read_b128 v[208:211], v156 offset:33792
	ds_read_b128 v[212:215], v156 offset:34816
	ds_read_b128 v[216:219], v156 offset:35840
	ds_read_b128 v[220:223], v156 offset:36864
	ds_read_b128 v[224:227], v156 offset:37888
	ds_read_b128 v[228:231], v156 offset:38912
	ds_read_b128 v[232:235], v156 offset:39936
	global_load_lds_dwordx4 v130, s[26:27]
	s_mov_b32 m0, s34
	s_nop 0
	global_load_lds_dwordx4 v134, s[26:27]
	s_waitcnt vmcnt(8)
	s_waitcnt lgkmcnt(0)
	s_barrier
	v_mfma_f32_16x16x32_bf16 v[126:129], v[142:145], v[204:207], v[126:129]
	v_mfma_f32_16x16x32_bf16 v[126:129], v[158:161], v[208:211], v[126:129]
	v_mfma_f32_16x16x32_bf16 v[122:125], v[176:179], v[208:211], v[122:125]
	v_mfma_f32_16x16x32_bf16 v[122:125], v[168:171], v[204:207], v[122:125]
	v_mfma_f32_16x16x32_bf16 v[106:109], v[168:171], v[212:215], v[106:109]
	v_mfma_f32_16x16x32_bf16 v[106:109], v[176:179], v[216:219], v[106:109]
	v_mfma_f32_16x16x32_bf16 v[110:113], v[158:161], v[216:219], v[110:113]
	v_mfma_f32_16x16x32_bf16 v[110:113], v[142:145], v[212:215], v[110:113]
	v_mfma_f32_16x16x32_bf16 v[94:97], v[142:145], v[220:223], v[94:97]
	v_mfma_f32_16x16x32_bf16 v[94:97], v[158:161], v[224:227], v[94:97]
	v_mfma_f32_16x16x32_bf16 v[90:93], v[176:179], v[224:227], v[90:93]
	v_mfma_f32_16x16x32_bf16 v[90:93], v[168:171], v[220:223], v[90:93]
	v_mfma_f32_16x16x32_bf16 v[74:77], v[168:171], v[228:231], v[74:77]
	v_mfma_f32_16x16x32_bf16 v[74:77], v[176:179], v[232:235], v[74:77]
	v_mfma_f32_16x16x32_bf16 v[78:81], v[158:161], v[232:235], v[78:81]
	v_mfma_f32_16x16x32_bf16 v[78:81], v[142:145], v[228:231], v[78:81]
	v_mfma_f32_16x16x32_bf16 v[70:73], v[180:183], v[228:231], v[70:73]
	v_mfma_f32_16x16x32_bf16 v[70:73], v[184:187], v[232:235], v[70:73]
	v_mfma_f32_16x16x32_bf16 v[66:69], v[192:195], v[232:235], v[66:69]
	v_mfma_f32_16x16x32_bf16 v[66:69], v[188:191], v[228:231], v[66:69]
	v_mfma_f32_16x16x32_bf16 v[82:85], v[188:191], v[220:223], v[82:85]
	v_mfma_f32_16x16x32_bf16 v[82:85], v[192:195], v[224:227], v[82:85]
	v_mfma_f32_16x16x32_bf16 v[86:89], v[184:187], v[224:227], v[86:89]
	v_mfma_f32_16x16x32_bf16 v[86:89], v[180:183], v[220:223], v[86:89]
	v_mfma_f32_16x16x32_bf16 v[102:105], v[180:183], v[212:215], v[102:105]
	v_mfma_f32_16x16x32_bf16 v[102:105], v[184:187], v[216:219], v[102:105]
	v_mfma_f32_16x16x32_bf16 v[98:101], v[192:195], v[216:219], v[98:101]
	v_mfma_f32_16x16x32_bf16 v[98:101], v[188:191], v[212:215], v[98:101]
	v_mfma_f32_16x16x32_bf16 v[114:117], v[188:191], v[204:207], v[114:117]
	v_mfma_f32_16x16x32_bf16 v[114:117], v[192:195], v[208:211], v[114:117]
	v_mfma_f32_16x16x32_bf16 v[118:121], v[184:187], v[208:211], v[118:121]
	v_mfma_f32_16x16x32_bf16 v[118:121], v[180:183], v[204:207], v[118:121]
	s_barrier
	s_add_u32 s98, s26, 0xfff00080
	s_addc_u32 s99, s27, -1
	s_add_u32 s24, s24, 0x80
	s_addc_u32 s25, s25, 0
	s_add_i32 s26, s49, s28
	s_mov_b32 m0, s26
	ds_read_b128 v[204:207], v156 offset:49152
	ds_read_b128 v[208:211], v156 offset:50176
	ds_read_b128 v[212:215], v156 offset:51200
	ds_read_b128 v[216:219], v156 offset:52224
	ds_read_b128 v[220:223], v156 offset:53248
	ds_read_b128 v[224:227], v156 offset:54272
	ds_read_b128 v[228:231], v156 offset:55296
	ds_read_b128 v[232:235], v156 offset:56320
	global_load_lds_dwordx4 v132, s[24:25]
	s_add_i32 m0, s26, 0x2000
	s_add_i32 s26, s50, s28
	global_load_lds_dwordx4 v136, s[24:25]
	s_add_u32 s24, s24, 0x100000
	s_addc_u32 s25, s25, 0
	s_mov_b32 m0, s26
	s_nop 0
	global_load_lds_dwordx4 v132, s[24:25]
	s_add_i32 m0, s26, 0x2000
	s_nop 0
	global_load_lds_dwordx4 v136, s[24:25]
	s_mov_b32 m0, s36
	s_nop 0
	global_load_lds_dwordx4 v130, s[98:99]
	s_mov_b32 m0, s37
	s_nop 0
	global_load_lds_dwordx4 v134, s[98:99]
	s_waitcnt vmcnt(8)
	s_waitcnt lgkmcnt(0)
	s_barrier
	v_mfma_f32_16x16x32_bf16 v[62:65], v[142:145], v[204:207], v[62:65]
	v_mfma_f32_16x16x32_bf16 v[62:65], v[158:161], v[208:211], v[62:65]
	v_mfma_f32_16x16x32_bf16 v[58:61], v[176:179], v[208:211], v[58:61]
	v_mfma_f32_16x16x32_bf16 v[58:61], v[168:171], v[204:207], v[58:61]
	v_mfma_f32_16x16x32_bf16 v[42:45], v[168:171], v[212:215], v[42:45]
	v_mfma_f32_16x16x32_bf16 v[42:45], v[176:179], v[216:219], v[42:45]
	v_mfma_f32_16x16x32_bf16 v[46:49], v[158:161], v[216:219], v[46:49]
	v_mfma_f32_16x16x32_bf16 v[46:49], v[142:145], v[212:215], v[46:49]
	v_mfma_f32_16x16x32_bf16 v[30:33], v[142:145], v[220:223], v[30:33]
	v_mfma_f32_16x16x32_bf16 v[30:33], v[158:161], v[224:227], v[30:33]
	v_mfma_f32_16x16x32_bf16 v[26:29], v[176:179], v[224:227], v[26:29]
	v_mfma_f32_16x16x32_bf16 v[26:29], v[168:171], v[220:223], v[26:29]
	v_mfma_f32_16x16x32_bf16 v[10:13], v[168:171], v[228:231], v[10:13]
	v_mfma_f32_16x16x32_bf16 v[10:13], v[176:179], v[232:235], v[10:13]
	v_mfma_f32_16x16x32_bf16 v[14:17], v[158:161], v[232:235], v[14:17]
	v_mfma_f32_16x16x32_bf16 v[14:17], v[142:145], v[228:231], v[14:17]
	v_mfma_f32_16x16x32_bf16 v[6:9], v[180:183], v[228:231], v[6:9]
	v_mfma_f32_16x16x32_bf16 v[6:9], v[184:187], v[232:235], v[6:9]
	v_mfma_f32_16x16x32_bf16 v[2:5], v[192:195], v[232:235], v[2:5]
	v_mfma_f32_16x16x32_bf16 v[2:5], v[188:191], v[228:231], v[2:5]
	v_mfma_f32_16x16x32_bf16 v[18:21], v[188:191], v[220:223], v[18:21]
	v_mfma_f32_16x16x32_bf16 v[18:21], v[192:195], v[224:227], v[18:21]
	v_mfma_f32_16x16x32_bf16 v[22:25], v[184:187], v[224:227], v[22:25]
	v_mfma_f32_16x16x32_bf16 v[22:25], v[180:183], v[220:223], v[22:25]
	v_mfma_f32_16x16x32_bf16 v[38:41], v[180:183], v[212:215], v[38:41]
	v_mfma_f32_16x16x32_bf16 v[38:41], v[184:187], v[216:219], v[38:41]
	v_mfma_f32_16x16x32_bf16 v[34:37], v[192:195], v[216:219], v[34:37]
	v_mfma_f32_16x16x32_bf16 v[34:37], v[188:191], v[212:215], v[34:37]
	v_mfma_f32_16x16x32_bf16 v[50:53], v[188:191], v[204:207], v[50:53]
	v_mfma_f32_16x16x32_bf16 v[50:53], v[192:195], v[208:211], v[50:53]
	v_mfma_f32_16x16x32_bf16 v[54:57], v[184:187], v[208:211], v[54:57]
	v_mfma_f32_16x16x32_bf16 v[54:57], v[180:183], v[204:207], v[54:57]
	s_barrier
	s_add_i32 s48, s48, 2
	s_add_u32 s22, s22, 0x100
	s_addc_u32 s23, s23, 0
	s_add_u32 s46, s46, 0x100
	s_addc_u32 s47, s47, 0
	s_cmp_gt_u32 s48, 61
	s_cbranch_scc0 .LBB0_2230
	s_and_b64 vcc, exec, s[16:17]
	s_cbranch_vccz .LBB0_2233
	s_barrier

.LBB0_2240:
	s_add_i32 s20, s24, 0x100
	s_and_b64 s[18:19], s[18:19], exec
	s_cselect_b32 s19, 0, s20
	s_cselect_b32 s18, 0, 0
	s_add_u32 s20, s8, s19
	ds_read_b128 v[144:147], v139
	ds_read_b128 v[150:153], v139 offset:1024
	ds_read_b128 v[154:157], v139 offset:2048
	ds_read_b128 v[158:161], v139 offset:3072
	ds_read_b128 v[168:171], v140
	ds_read_b128 v[176:179], v140 offset:1024
	ds_read_b128 v[180:183], v140 offset:2048
	ds_read_b128 v[184:187], v140 offset:3072
	s_addc_u32 s21, s9, s18
	s_add_u32 s22, s10, s19
	s_addc_u32 s23, s11, s18
	s_add_u32 s28, s12, s24
	s_addc_u32 s29, s13, 0
	s_add_u32 s24, s22, 0x100000
	s_addc_u32 s25, s23, 0
	s_add_u32 s18, s20, 0x100000
	s_addc_u32 s19, s21, 0
	s_add_u32 s26, s22, 0x100080
	s_addc_u32 s27, s23, 0
	v_lshl_add_u64 v[172:173], s[28:29], 0, v[130:131]
	s_mov_b32 m0, s38
	v_lshl_add_u64 v[172:173], v[172:173], 0, s[14:15]
	ds_read_b128 v[188:191], v141
	ds_read_b128 v[192:195], v141 offset:1024
	ds_read_b128 v[204:207], v141 offset:2048
	ds_read_b128 v[208:211], v141 offset:3072
	ds_read_b128 v[212:215], v141 offset:4096
	ds_read_b128 v[216:219], v141 offset:5120
	ds_read_b128 v[220:223], v141 offset:6144
	ds_read_b128 v[224:227], v141 offset:7168
	global_load_lds_dwordx4 v[172:173], off
	v_lshl_add_u64 v[172:173], s[28:29], 0, v[134:135]
	v_lshl_add_u64 v[172:173], v[172:173], 0, s[14:15]
	s_mov_b32 m0, s39
	s_nop 0
	global_load_lds_dwordx4 v[172:173], off
	s_waitcnt vmcnt(8)
	s_waitcnt lgkmcnt(0)
	s_barrier
	v_mfma_f32_16x16x32_bf16 v[126:129], v[144:147], v[188:191], v[126:129]
	v_mfma_f32_16x16x32_bf16 v[126:129], v[150:153], v[192:195], v[126:129]
	v_mfma_f32_16x16x32_bf16 v[122:125], v[158:161], v[192:195], v[122:125]
	v_mfma_f32_16x16x32_bf16 v[122:125], v[154:157], v[188:191], v[122:125]
	v_mfma_f32_16x16x32_bf16 v[114:117], v[154:157], v[204:207], v[114:117]
	v_mfma_f32_16x16x32_bf16 v[114:117], v[158:161], v[208:211], v[114:117]
	v_mfma_f32_16x16x32_bf16 v[118:121], v[150:153], v[208:211], v[118:121]
	v_mfma_f32_16x16x32_bf16 v[118:121], v[144:147], v[204:207], v[118:121]
	v_mfma_f32_16x16x32_bf16 v[102:105], v[144:147], v[212:215], v[102:105]
	v_mfma_f32_16x16x32_bf16 v[102:105], v[150:153], v[216:219], v[102:105]
	v_mfma_f32_16x16x32_bf16 v[98:101], v[158:161], v[216:219], v[98:101]
	v_mfma_f32_16x16x32_bf16 v[98:101], v[154:157], v[212:215], v[98:101]
	v_mfma_f32_16x16x32_bf16 v[82:85], v[154:157], v[220:223], v[82:85]
	v_mfma_f32_16x16x32_bf16 v[82:85], v[158:161], v[224:227], v[82:85]
	v_mfma_f32_16x16x32_bf16 v[86:89], v[150:153], v[224:227], v[86:89]
	v_mfma_f32_16x16x32_bf16 v[86:89], v[144:147], v[220:223], v[86:89]
	v_mfma_f32_16x16x32_bf16 v[70:73], v[168:171], v[220:223], v[70:73]
	v_mfma_f32_16x16x32_bf16 v[70:73], v[176:179], v[224:227], v[70:73]
	v_mfma_f32_16x16x32_bf16 v[66:69], v[184:187], v[224:227], v[66:69]
	v_mfma_f32_16x16x32_bf16 v[66:69], v[180:183], v[220:223], v[66:69]
	v_mfma_f32_16x16x32_bf16 v[74:77], v[180:183], v[212:215], v[74:77]
	v_mfma_f32_16x16x32_bf16 v[74:77], v[184:187], v[216:219], v[74:77]
	v_mfma_f32_16x16x32_bf16 v[78:81], v[176:179], v[216:219], v[78:81]
	v_mfma_f32_16x16x32_bf16 v[78:81], v[168:171], v[212:215], v[78:81]
	v_mfma_f32_16x16x32_bf16 v[94:97], v[168:171], v[204:207], v[94:97]
	v_mfma_f32_16x16x32_bf16 v[94:97], v[176:179], v[208:211], v[94:97]
	v_mfma_f32_16x16x32_bf16 v[90:93], v[184:187], v[208:211], v[90:93]
	v_mfma_f32_16x16x32_bf16 v[90:93], v[180:183], v[204:207], v[90:93]
	v_mfma_f32_16x16x32_bf16 v[106:109], v[180:183], v[188:191], v[106:109]
	v_mfma_f32_16x16x32_bf16 v[106:109], v[184:187], v[192:195], v[106:109]
	v_mfma_f32_16x16x32_bf16 v[110:113], v[176:179], v[192:195], v[110:113]
	v_mfma_f32_16x16x32_bf16 v[110:113], v[168:171], v[188:191], v[110:113]
	s_barrier
	s_mov_b32 m0, s40
	v_lshl_add_u64 v[172:173], s[22:23], 0, v[132:133]
	ds_read_b128 v[188:191], v141 offset:16384
	ds_read_b128 v[192:195], v141 offset:17408
	ds_read_b128 v[204:207], v141 offset:18432
	ds_read_b128 v[208:211], v141 offset:19456
	ds_read_b128 v[212:215], v141 offset:20480
	ds_read_b128 v[216:219], v141 offset:21504
	ds_read_b128 v[220:223], v141 offset:22528
	ds_read_b128 v[224:227], v141 offset:23552
	global_load_lds_dwordx4 v[172:173], off
	v_lshl_add_u64 v[196:197], s[22:23], 0, v[136:137]
	s_mov_b32 m0, s41
	v_lshl_add_u64 v[228:229], s[24:25], 0, v[132:133]
	global_load_lds_dwordx4 v[196:197], off
	s_mov_b32 m0, s42
	v_lshl_add_u64 v[230:231], s[20:21], 0, v[134:135]
	global_load_lds_dwordx4 v[228:229], off
	v_lshl_add_u64 v[228:229], s[24:25], 0, v[136:137]
	s_mov_b32 m0, s43
	s_nop 0
	global_load_lds_dwordx4 v[228:229], off
	v_lshl_add_u64 v[228:229], s[20:21], 0, v[130:131]
	s_mov_b32 m0, s7
	s_nop 0
	global_load_lds_dwordx4 v[228:229], off
	s_mov_b32 m0, s31
	s_nop 0
	global_load_lds_dwordx4 v[230:231], off
	s_waitcnt vmcnt(8)
	s_waitcnt lgkmcnt(0)
	s_barrier
	v_mfma_f32_16x16x32_bf16 v[62:65], v[144:147], v[188:191], v[62:65]
	v_mfma_f32_16x16x32_bf16 v[62:65], v[150:153], v[192:195], v[62:65]
	v_mfma_f32_16x16x32_bf16 v[58:61], v[158:161], v[192:195], v[58:61]
	v_mfma_f32_16x16x32_bf16 v[58:61], v[154:157], v[188:191], v[58:61]
	v_mfma_f32_16x16x32_bf16 v[50:53], v[154:157], v[204:207], v[50:53]
	v_mfma_f32_16x16x32_bf16 v[50:53], v[158:161], v[208:211], v[50:53]
	v_mfma_f32_16x16x32_bf16 v[54:57], v[150:153], v[208:211], v[54:57]
	v_mfma_f32_16x16x32_bf16 v[54:57], v[144:147], v[204:207], v[54:57]
	v_mfma_f32_16x16x32_bf16 v[38:41], v[144:147], v[212:215], v[38:41]
	v_mfma_f32_16x16x32_bf16 v[38:41], v[150:153], v[216:219], v[38:41]
	v_mfma_f32_16x16x32_bf16 v[34:37], v[158:161], v[216:219], v[34:37]
	v_mfma_f32_16x16x32_bf16 v[34:37], v[154:157], v[212:215], v[34:37]
	v_mfma_f32_16x16x32_bf16 v[18:21], v[154:157], v[220:223], v[18:21]
	v_mfma_f32_16x16x32_bf16 v[18:21], v[158:161], v[224:227], v[18:21]
	v_mfma_f32_16x16x32_bf16 v[22:25], v[150:153], v[224:227], v[22:25]
	v_mfma_f32_16x16x32_bf16 v[22:25], v[144:147], v[220:223], v[22:25]
	v_mfma_f32_16x16x32_bf16 v[6:9], v[168:171], v[220:223], v[6:9]
	v_mfma_f32_16x16x32_bf16 v[6:9], v[176:179], v[224:227], v[6:9]
	v_mfma_f32_16x16x32_bf16 v[2:5], v[184:187], v[224:227], v[2:5]
	v_mfma_f32_16x16x32_bf16 v[2:5], v[180:183], v[220:223], v[2:5]
	v_mfma_f32_16x16x32_bf16 v[10:13], v[180:183], v[212:215], v[10:13]
	v_mfma_f32_16x16x32_bf16 v[10:13], v[184:187], v[216:219], v[10:13]
	v_mfma_f32_16x16x32_bf16 v[14:17], v[176:179], v[216:219], v[14:17]
	v_mfma_f32_16x16x32_bf16 v[14:17], v[168:171], v[212:215], v[14:17]
	v_mfma_f32_16x16x32_bf16 v[30:33], v[168:171], v[204:207], v[30:33]
	v_mfma_f32_16x16x32_bf16 v[30:33], v[176:179], v[208:211], v[30:33]
	v_mfma_f32_16x16x32_bf16 v[26:29], v[184:187], v[208:211], v[26:29]
	v_mfma_f32_16x16x32_bf16 v[26:29], v[180:183], v[204:207], v[26:29]
	v_mfma_f32_16x16x32_bf16 v[42:45], v[180:183], v[188:191], v[42:45]
	v_mfma_f32_16x16x32_bf16 v[42:45], v[184:187], v[192:195], v[42:45]
	v_mfma_f32_16x16x32_bf16 v[46:49], v[176:179], v[192:195], v[46:49]
	v_mfma_f32_16x16x32_bf16 v[46:49], v[168:171], v[188:191], v[46:49]
	s_barrier
	ds_read_b128 v[144:147], v142
	ds_read_b128 v[150:153], v142 offset:1024
	ds_read_b128 v[154:157], v142 offset:2048
	ds_read_b128 v[158:161], v142 offset:3072
	ds_read_b128 v[168:171], v143
	ds_read_b128 v[176:179], v143 offset:1024
	ds_read_b128 v[180:183], v143 offset:2048
	ds_read_b128 v[184:187], v143 offset:3072
	s_mov_b32 m0, s33
	v_lshl_add_u64 v[232:233], s[18:19], 0, v[130:131]
	ds_read_b128 v[188:191], v141 offset:32768
	ds_read_b128 v[192:195], v141 offset:33792
	ds_read_b128 v[204:207], v141 offset:34816
	ds_read_b128 v[208:211], v141 offset:35840
	ds_read_b128 v[212:215], v141 offset:36864
	ds_read_b128 v[216:219], v141 offset:37888
	ds_read_b128 v[220:223], v141 offset:38912
	ds_read_b128 v[224:227], v141 offset:39936
	global_load_lds_dwordx4 v[232:233], off
	v_lshl_add_u64 v[232:233], s[18:19], 0, v[134:135]
	s_mov_b32 m0, s34
	s_nop 0
	global_load_lds_dwordx4 v[232:233], off
	s_waitcnt vmcnt(8)
	s_waitcnt lgkmcnt(0)
	s_barrier
	v_mfma_f32_16x16x32_bf16 v[126:129], v[144:147], v[188:191], v[126:129]
	v_mfma_f32_16x16x32_bf16 v[126:129], v[150:153], v[192:195], v[126:129]
	v_mfma_f32_16x16x32_bf16 v[122:125], v[158:161], v[192:195], v[122:125]
	v_mfma_f32_16x16x32_bf16 v[122:125], v[154:157], v[188:191], v[122:125]
	v_mfma_f32_16x16x32_bf16 v[114:117], v[154:157], v[204:207], v[114:117]
	v_mfma_f32_16x16x32_bf16 v[114:117], v[158:161], v[208:211], v[114:117]
	v_mfma_f32_16x16x32_bf16 v[118:121], v[150:153], v[208:211], v[118:121]
	v_mfma_f32_16x16x32_bf16 v[118:121], v[144:147], v[204:207], v[118:121]
	v_mfma_f32_16x16x32_bf16 v[102:105], v[144:147], v[212:215], v[102:105]
	v_mfma_f32_16x16x32_bf16 v[102:105], v[150:153], v[216:219], v[102:105]
	v_mfma_f32_16x16x32_bf16 v[98:101], v[158:161], v[216:219], v[98:101]
	v_mfma_f32_16x16x32_bf16 v[98:101], v[154:157], v[212:215], v[98:101]
	v_mfma_f32_16x16x32_bf16 v[82:85], v[154:157], v[220:223], v[82:85]
	v_mfma_f32_16x16x32_bf16 v[82:85], v[158:161], v[224:227], v[82:85]
	v_mfma_f32_16x16x32_bf16 v[86:89], v[150:153], v[224:227], v[86:89]
	v_mfma_f32_16x16x32_bf16 v[86:89], v[144:147], v[220:223], v[86:89]
	v_mfma_f32_16x16x32_bf16 v[70:73], v[168:171], v[220:223], v[70:73]
	v_mfma_f32_16x16x32_bf16 v[70:73], v[176:179], v[224:227], v[70:73]
	v_mfma_f32_16x16x32_bf16 v[66:69], v[184:187], v[224:227], v[66:69]
	v_mfma_f32_16x16x32_bf16 v[66:69], v[180:183], v[220:223], v[66:69]
	v_mfma_f32_16x16x32_bf16 v[74:77], v[180:183], v[212:215], v[74:77]
	v_mfma_f32_16x16x32_bf16 v[74:77], v[184:187], v[216:219], v[74:77]
	v_mfma_f32_16x16x32_bf16 v[78:81], v[176:179], v[216:219], v[78:81]
	v_mfma_f32_16x16x32_bf16 v[78:81], v[168:171], v[212:215], v[78:81]
	v_mfma_f32_16x16x32_bf16 v[94:97], v[168:171], v[204:207], v[94:97]
	v_mfma_f32_16x16x32_bf16 v[94:97], v[176:179], v[208:211], v[94:97]
	v_mfma_f32_16x16x32_bf16 v[90:93], v[184:187], v[208:211], v[90:93]
	v_mfma_f32_16x16x32_bf16 v[90:93], v[180:183], v[204:207], v[90:93]
	v_mfma_f32_16x16x32_bf16 v[106:109], v[180:183], v[188:191], v[106:109]
	v_mfma_f32_16x16x32_bf16 v[106:109], v[184:187], v[192:195], v[106:109]
	v_mfma_f32_16x16x32_bf16 v[110:113], v[176:179], v[192:195], v[110:113]
	v_mfma_f32_16x16x32_bf16 v[110:113], v[168:171], v[188:191], v[110:113]
	s_barrier
	s_mov_b32 m0, s44
	v_lshl_add_u64 v[172:173], v[172:173], 0, s[14:15]
	ds_read_b128 v[188:191], v141 offset:49152
	ds_read_b128 v[192:195], v141 offset:50176
	ds_read_b128 v[204:207], v141 offset:51200
	ds_read_b128 v[208:211], v141 offset:52224
	ds_read_b128 v[212:215], v141 offset:53248
	ds_read_b128 v[216:219], v141 offset:54272
	ds_read_b128 v[220:223], v141 offset:55296
	ds_read_b128 v[224:227], v141 offset:56320
	global_load_lds_dwordx4 v[172:173], off
	v_lshl_add_u64 v[172:173], v[196:197], 0, s[14:15]
	s_mov_b32 m0, s45
	s_nop 0
	global_load_lds_dwordx4 v[172:173], off
	v_lshl_add_u64 v[172:173], s[26:27], 0, v[132:133]
	s_mov_b32 m0, s46
	s_nop 0
	global_load_lds_dwordx4 v[172:173], off
	v_lshl_add_u64 v[172:173], s[26:27], 0, v[136:137]
	s_mov_b32 m0, s47
	s_nop 0
	global_load_lds_dwordx4 v[172:173], off
	v_lshl_add_u64 v[172:173], v[228:229], 0, s[14:15]
	s_mov_b32 m0, s36
	s_nop 0
	global_load_lds_dwordx4 v[172:173], off
	v_lshl_add_u64 v[172:173], v[230:231], 0, s[14:15]
	s_mov_b32 m0, s37
	s_nop 0
	global_load_lds_dwordx4 v[172:173], off
	s_waitcnt vmcnt(8)
	s_waitcnt lgkmcnt(0)
	s_barrier
	v_mfma_f32_16x16x32_bf16 v[62:65], v[144:147], v[188:191], v[62:65]
	v_mfma_f32_16x16x32_bf16 v[62:65], v[150:153], v[192:195], v[62:65]
	v_mfma_f32_16x16x32_bf16 v[58:61], v[158:161], v[192:195], v[58:61]
	v_mfma_f32_16x16x32_bf16 v[58:61], v[154:157], v[188:191], v[58:61]
	v_mfma_f32_16x16x32_bf16 v[50:53], v[154:157], v[204:207], v[50:53]
	v_mfma_f32_16x16x32_bf16 v[50:53], v[158:161], v[208:211], v[50:53]
	v_mfma_f32_16x16x32_bf16 v[54:57], v[150:153], v[208:211], v[54:57]
	v_mfma_f32_16x16x32_bf16 v[54:57], v[144:147], v[204:207], v[54:57]
	v_mfma_f32_16x16x32_bf16 v[38:41], v[144:147], v[212:215], v[38:41]
	v_mfma_f32_16x16x32_bf16 v[38:41], v[150:153], v[216:219], v[38:41]
	v_mfma_f32_16x16x32_bf16 v[34:37], v[158:161], v[216:219], v[34:37]
	v_mfma_f32_16x16x32_bf16 v[34:37], v[154:157], v[212:215], v[34:37]
	v_mfma_f32_16x16x32_bf16 v[18:21], v[154:157], v[220:223], v[18:21]
	v_mfma_f32_16x16x32_bf16 v[18:21], v[158:161], v[224:227], v[18:21]
	v_mfma_f32_16x16x32_bf16 v[22:25], v[150:153], v[224:227], v[22:25]
	v_mfma_f32_16x16x32_bf16 v[22:25], v[144:147], v[220:223], v[22:25]
	v_mfma_f32_16x16x32_bf16 v[6:9], v[168:171], v[220:223], v[6:9]
	v_mfma_f32_16x16x32_bf16 v[6:9], v[176:179], v[224:227], v[6:9]
	v_mfma_f32_16x16x32_bf16 v[2:5], v[184:187], v[224:227], v[2:5]
	v_mfma_f32_16x16x32_bf16 v[2:5], v[180:183], v[220:223], v[2:5]
	v_mfma_f32_16x16x32_bf16 v[10:13], v[180:183], v[212:215], v[10:13]
	v_mfma_f32_16x16x32_bf16 v[10:13], v[184:187], v[216:219], v[10:13]
	v_mfma_f32_16x16x32_bf16 v[14:17], v[176:179], v[216:219], v[14:17]
	v_mfma_f32_16x16x32_bf16 v[14:17], v[168:171], v[212:215], v[14:17]
	v_mfma_f32_16x16x32_bf16 v[30:33], v[168:171], v[204:207], v[30:33]
	v_mfma_f32_16x16x32_bf16 v[30:33], v[176:179], v[208:211], v[30:33]
	v_mfma_f32_16x16x32_bf16 v[26:29], v[184:187], v[208:211], v[26:29]
	v_mfma_f32_16x16x32_bf16 v[26:29], v[180:183], v[204:207], v[26:29]
	v_mfma_f32_16x16x32_bf16 v[42:45], v[180:183], v[188:191], v[42:45]
	v_mfma_f32_16x16x32_bf16 v[42:45], v[184:187], v[192:195], v[42:45]
	v_mfma_f32_16x16x32_bf16 v[46:49], v[176:179], v[192:195], v[46:49]
	v_mfma_f32_16x16x32_bf16 v[46:49], v[168:171], v[188:191], v[46:49]
	s_barrier
	s_andn2_b64 vcc, exec, s[16:17]
	s_mov_b64 s[18:19], -1
	s_mov_b64 s[16:17], 0
	s_movk_i32 s24, 0x100
	s_cbranch_vccz .LBB0_2240
	s_lshl_b32 s7, s30, 21
	v_readlane_b32 s0, v249, 29
	v_lshl_or_b32 v130, s6, 8, v148
	v_mov_b32_e32 v139, 0
	s_add_u32 s8, s0, s7
	v_readlane_b32 s0, v249, 31
	v_or_b32_e32 v130, s35, v130
	v_cvt_pk_bf16_f32 v70, v70, v71
	v_cvt_pk_bf16_f32 v71, v72, v73
	v_cvt_pk_bf16_f32 v72, v66, v67
	v_add_u32_e32 v66, 0x80, v138
	v_mov_b32_e32 v67, v139
	s_addc_u32 s9, s0, 0
	v_ashrrev_i32_e32 v131, 31, v130
	v_lshlrev_b64 v[132:133], 13, v[138:139]
	v_cvt_pk_bf16_f32 v110, v110, v111
	v_cvt_pk_bf16_f32 v111, v112, v113
	v_cvt_pk_bf16_f32 v112, v106, v107
	v_or_b32_e32 v106, 16, v138
	v_mov_b32_e32 v107, v139
	v_lshlrev_b64 v[66:67], 13, v[66:67]
	v_cvt_pk_bf16_f32 v46, v46, v47
	v_cvt_pk_bf16_f32 v47, v48, v49
	v_cvt_pk_bf16_f32 v48, v42, v43
	v_add_u32_e32 v42, 0x90, v138
	v_mov_b32_e32 v43, v139
	v_lshl_add_u64 v[132:133], s[8:9], 0, v[132:133]
	v_lshlrev_b64 v[130:131], 1, v[130:131]
	v_lshlrev_b64 v[106:107], 13, v[106:107]
	v_cvt_pk_bf16_f32 v94, v94, v95
	v_cvt_pk_bf16_f32 v95, v96, v97
	v_cvt_pk_bf16_f32 v96, v90, v91
	v_or_b32_e32 v90, 32, v138
	v_mov_b32_e32 v91, v139
	v_lshl_add_u64 v[66:67], s[8:9], 0, v[66:67]
	v_lshlrev_b64 v[42:43], 13, v[42:43]
	v_cvt_pk_bf16_f32 v30, v30, v31
	v_cvt_pk_bf16_f32 v31, v32, v33
	v_cvt_pk_bf16_f32 v32, v26, v27
	v_add_u32_e32 v26, 0xa0, v138
	v_mov_b32_e32 v27, v139
	v_lshl_add_u64 v[132:133], v[132:133], 0, v[130:131]
	v_cvt_pk_bf16_f32 v113, v108, v109
	v_lshl_add_u64 v[106:107], s[8:9], 0, v[106:107]
	v_lshlrev_b64 v[90:91], 13, v[90:91]
	v_cvt_pk_bf16_f32 v78, v78, v79
	v_cvt_pk_bf16_f32 v79, v80, v81
	v_cvt_pk_bf16_f32 v80, v74, v75
	v_or_b32_e32 v74, 48, v138
	v_mov_b32_e32 v75, v139
	v_lshl_add_u64 v[66:67], v[66:67], 0, v[130:131]
	v_cvt_pk_bf16_f32 v49, v44, v45
	v_lshl_add_u64 v[42:43], s[8:9], 0, v[42:43]
	v_lshlrev_b64 v[26:27], 13, v[26:27]
	v_add_u32_e32 v138, 0xb0, v138
	global_store_dwordx4 v[132:133], v[110:113], off offset:256
	v_cvt_pk_bf16_f32 v97, v92, v93
	v_lshl_add_u64 v[90:91], s[8:9], 0, v[90:91]
	v_lshl_add_u64 v[110:111], v[106:107], 0, v[130:131]
	v_lshlrev_b64 v[74:75], 13, v[74:75]
	global_store_dwordx4 v[66:67], v[46:49], off offset:256
	v_cvt_pk_bf16_f32 v33, v28, v29
	v_lshl_add_u64 v[26:27], s[8:9], 0, v[26:27]
	v_lshl_add_u64 v[46:47], v[42:43], 0, v[130:131]
	v_cvt_pk_bf16_f32 v14, v14, v15
	v_cvt_pk_bf16_f32 v15, v16, v17
	v_cvt_pk_bf16_f32 v16, v10, v11
	v_lshlrev_b64 v[10:11], 13, v[138:139]
	global_store_dwordx4 v[110:111], v[94:97], off offset:256
	v_cvt_pk_bf16_f32 v81, v76, v77
	v_lshl_add_u64 v[74:75], s[8:9], 0, v[74:75]
	v_lshl_add_u64 v[94:95], v[90:91], 0, v[130:131]
	global_store_dwordx4 v[46:47], v[30:33], off offset:256
	v_cvt_pk_bf16_f32 v17, v12, v13
	v_lshl_add_u64 v[10:11], s[8:9], 0, v[10:11]
	v_lshl_add_u64 v[30:31], v[26:27], 0, v[130:131]
	v_cvt_pk_bf16_f32 v126, v126, v127
	v_cvt_pk_bf16_f32 v127, v128, v129
	v_cvt_pk_bf16_f32 v128, v122, v123
	v_cvt_pk_bf16_f32 v129, v124, v125
	v_cvt_pk_bf16_f32 v106, v118, v119
	v_cvt_pk_bf16_f32 v107, v120, v121
	v_cvt_pk_bf16_f32 v108, v114, v115
	v_cvt_pk_bf16_f32 v109, v116, v117
	v_cvt_pk_bf16_f32 v90, v102, v103
	v_cvt_pk_bf16_f32 v91, v104, v105
	v_cvt_pk_bf16_f32 v92, v98, v99
	v_cvt_pk_bf16_f32 v93, v100, v101
	global_store_dwordx4 v[94:95], v[78:81], off offset:256
	v_cvt_pk_bf16_f32 v76, v82, v83
	v_cvt_pk_bf16_f32 v77, v84, v85
	v_lshl_add_u64 v[78:79], v[74:75], 0, v[130:131]
	v_cvt_pk_bf16_f32 v74, v86, v87
	v_cvt_pk_bf16_f32 v75, v88, v89
	v_cvt_pk_bf16_f32 v73, v68, v69
	v_cvt_pk_bf16_f32 v62, v62, v63
	v_cvt_pk_bf16_f32 v63, v64, v65
	v_cvt_pk_bf16_f32 v64, v58, v59
	v_cvt_pk_bf16_f32 v65, v60, v61
	v_cvt_pk_bf16_f32 v42, v54, v55
	v_cvt_pk_bf16_f32 v43, v56, v57
	v_cvt_pk_bf16_f32 v44, v50, v51
	v_cvt_pk_bf16_f32 v45, v52, v53
	v_cvt_pk_bf16_f32 v26, v38, v39
	v_cvt_pk_bf16_f32 v27, v40, v41
	v_cvt_pk_bf16_f32 v28, v34, v35
	v_cvt_pk_bf16_f32 v29, v36, v37
	global_store_dwordx4 v[30:31], v[14:17], off offset:256
	v_cvt_pk_bf16_f32 v12, v18, v19
	v_cvt_pk_bf16_f32 v13, v20, v21
	v_lshl_add_u64 v[14:15], v[10:11], 0, v[130:131]
	v_cvt_pk_bf16_f32 v10, v22, v23
	v_cvt_pk_bf16_f32 v11, v24, v25
	v_cvt_pk_bf16_f32 v6, v6, v7
	v_cvt_pk_bf16_f32 v7, v8, v9
	v_cvt_pk_bf16_f32 v8, v2, v3
	v_cvt_pk_bf16_f32 v9, v4, v5
	global_store_dwordx4 v[132:133], v[126:129], off
	global_store_dwordx4 v[110:111], v[106:109], off
	global_store_dwordx4 v[94:95], v[90:93], off
	global_store_dwordx4 v[78:79], v[74:77], off
	global_store_dwordx4 v[78:79], v[70:73], off offset:256
	global_store_dwordx4 v[66:67], v[62:65], off
	global_store_dwordx4 v[46:47], v[42:45], off
	global_store_dwordx4 v[30:31], v[26:29], off
	global_store_dwordx4 v[14:15], v[10:13], off
	global_store_dwordx4 v[14:15], v[6:9], off offset:256
	s_waitcnt vmcnt(0)
	s_cmpk_lt_u32 s3, 0x100
	s_cbranch_scc0 .LBB0_2243
	s_barrier

.LBB0_2373:
	s_add_u32 s60, s20, 0xfff00000
	s_addc_u32 s61, s21, -1
	s_mov_b32 m0, s35
	ds_read_b128 v[142:145], v148
	global_load_lds_dwordx4 v130, s[60:61]
	s_mov_b32 m0, s36
	ds_read_b128 v[154:157], v148 offset:1024
	global_load_lds_dwordx4 v134, s[60:61]
	s_mov_b32 m0, s40
	ds_read_b128 v[158:161], v148 offset:2048
	global_load_lds_dwordx4 v138, s[20:21]
	s_mov_b32 m0, s41
	ds_read_b128 v[168:171], v148 offset:3072
	global_load_lds_dwordx4 v140, s[20:21]
	ds_read_b128 v[176:179], v149
	ds_read_b128 v[180:183], v149 offset:1024
	ds_read_b128 v[184:187], v149 offset:2048
	ds_read_b128 v[188:191], v149 offset:3072
	s_add_u32 s22, s20, 0xfff00080
	s_addc_u32 s23, s21, -1
	s_cmp_eq_u32 s57, 60
	s_cselect_b32 s25, s52, s23
	s_cselect_b32 s24, s53, s22
	s_cselect_b32 s23, s7, s56
	s_cselect_b32 s22, s54, s55
	ds_read_b128 v[192:195], v150
	ds_read_b128 v[204:207], v150 offset:1024
	ds_read_b128 v[208:211], v150 offset:2048
	ds_read_b128 v[212:215], v150 offset:3072
	ds_read_b128 v[216:219], v150 offset:4096
	ds_read_b128 v[220:223], v150 offset:5120
	ds_read_b128 v[224:227], v150 offset:6144
	ds_read_b128 v[228:231], v150 offset:7168
	s_waitcnt vmcnt(8)
	s_waitcnt lgkmcnt(0)
	s_barrier
	v_mfma_f32_16x16x32_bf16 v[126:129], v[142:145], v[192:195], v[126:129]
	v_mfma_f32_16x16x32_bf16 v[126:129], v[154:157], v[204:207], v[126:129]
	v_mfma_f32_16x16x32_bf16 v[122:125], v[168:171], v[204:207], v[122:125]
	v_mfma_f32_16x16x32_bf16 v[122:125], v[158:161], v[192:195], v[122:125]
	v_mfma_f32_16x16x32_bf16 v[106:109], v[158:161], v[208:211], v[106:109]
	v_mfma_f32_16x16x32_bf16 v[106:109], v[168:171], v[212:215], v[106:109]
	v_mfma_f32_16x16x32_bf16 v[110:113], v[154:157], v[212:215], v[110:113]
	v_mfma_f32_16x16x32_bf16 v[110:113], v[142:145], v[208:211], v[110:113]
	v_mfma_f32_16x16x32_bf16 v[94:97], v[142:145], v[216:219], v[94:97]
	v_mfma_f32_16x16x32_bf16 v[94:97], v[154:157], v[220:223], v[94:97]
	v_mfma_f32_16x16x32_bf16 v[90:93], v[168:171], v[220:223], v[90:93]
	v_mfma_f32_16x16x32_bf16 v[90:93], v[158:161], v[216:219], v[90:93]
	v_mfma_f32_16x16x32_bf16 v[74:77], v[158:161], v[224:227], v[74:77]
	v_mfma_f32_16x16x32_bf16 v[74:77], v[168:171], v[228:231], v[74:77]
	v_mfma_f32_16x16x32_bf16 v[78:81], v[154:157], v[228:231], v[78:81]
	v_mfma_f32_16x16x32_bf16 v[78:81], v[142:145], v[224:227], v[78:81]
	v_mfma_f32_16x16x32_bf16 v[70:73], v[176:179], v[224:227], v[70:73]
	v_mfma_f32_16x16x32_bf16 v[70:73], v[180:183], v[228:231], v[70:73]
	v_mfma_f32_16x16x32_bf16 v[66:69], v[188:191], v[228:231], v[66:69]
	v_mfma_f32_16x16x32_bf16 v[66:69], v[184:187], v[224:227], v[66:69]
	v_mfma_f32_16x16x32_bf16 v[82:85], v[184:187], v[216:219], v[82:85]
	v_mfma_f32_16x16x32_bf16 v[82:85], v[188:191], v[220:223], v[82:85]
	v_mfma_f32_16x16x32_bf16 v[86:89], v[180:183], v[220:223], v[86:89]
	v_mfma_f32_16x16x32_bf16 v[86:89], v[176:179], v[216:219], v[86:89]
	v_mfma_f32_16x16x32_bf16 v[102:105], v[176:179], v[208:211], v[102:105]
	v_mfma_f32_16x16x32_bf16 v[102:105], v[180:183], v[212:215], v[102:105]
	v_mfma_f32_16x16x32_bf16 v[98:101], v[188:191], v[212:215], v[98:101]
	v_mfma_f32_16x16x32_bf16 v[98:101], v[184:187], v[208:211], v[98:101]
	v_mfma_f32_16x16x32_bf16 v[114:117], v[184:187], v[192:195], v[114:117]
	v_mfma_f32_16x16x32_bf16 v[114:117], v[188:191], v[204:207], v[114:117]
	v_mfma_f32_16x16x32_bf16 v[118:121], v[180:183], v[204:207], v[118:121]
	v_mfma_f32_16x16x32_bf16 v[118:121], v[176:179], v[192:195], v[118:121]
	s_barrier
	s_mov_b32 m0, s42
	s_add_u32 s60, s22, 0x100000
	global_load_lds_dwordx4 v132, s[22:23]
	s_mov_b32 m0, s43
	s_addc_u32 s61, s23, 0
	global_load_lds_dwordx4 v136, s[22:23]
	s_mov_b32 m0, s44
	ds_read_b128 v[192:195], v150 offset:16384
	global_load_lds_dwordx4 v132, s[60:61]
	s_mov_b32 m0, s45
	ds_read_b128 v[204:207], v150 offset:17408
	global_load_lds_dwordx4 v136, s[60:61]
	ds_read_b128 v[208:211], v150 offset:18432
	ds_read_b128 v[212:215], v150 offset:19456
	ds_read_b128 v[216:219], v150 offset:20480
	ds_read_b128 v[220:223], v150 offset:21504
	ds_read_b128 v[224:227], v150 offset:22528
	ds_read_b128 v[228:231], v150 offset:23552
	s_waitcnt vmcnt(6)
	s_waitcnt lgkmcnt(0)
	s_barrier
	v_mfma_f32_16x16x32_bf16 v[62:65], v[142:145], v[192:195], v[62:65]
	v_mfma_f32_16x16x32_bf16 v[62:65], v[154:157], v[204:207], v[62:65]
	v_mfma_f32_16x16x32_bf16 v[58:61], v[168:171], v[204:207], v[58:61]
	v_mfma_f32_16x16x32_bf16 v[58:61], v[158:161], v[192:195], v[58:61]
	v_mfma_f32_16x16x32_bf16 v[42:45], v[158:161], v[208:211], v[42:45]
	v_mfma_f32_16x16x32_bf16 v[42:45], v[168:171], v[212:215], v[42:45]
	v_mfma_f32_16x16x32_bf16 v[46:49], v[154:157], v[212:215], v[46:49]
	v_mfma_f32_16x16x32_bf16 v[46:49], v[142:145], v[208:211], v[46:49]
	v_mfma_f32_16x16x32_bf16 v[30:33], v[142:145], v[216:219], v[30:33]
	v_mfma_f32_16x16x32_bf16 v[30:33], v[154:157], v[220:223], v[30:33]
	v_mfma_f32_16x16x32_bf16 v[26:29], v[168:171], v[220:223], v[26:29]
	v_mfma_f32_16x16x32_bf16 v[26:29], v[158:161], v[216:219], v[26:29]
	v_mfma_f32_16x16x32_bf16 v[10:13], v[158:161], v[224:227], v[10:13]
	v_mfma_f32_16x16x32_bf16 v[10:13], v[168:171], v[228:231], v[10:13]
	v_mfma_f32_16x16x32_bf16 v[14:17], v[154:157], v[228:231], v[14:17]
	v_mfma_f32_16x16x32_bf16 v[14:17], v[142:145], v[224:227], v[14:17]
	v_mfma_f32_16x16x32_bf16 v[6:9], v[176:179], v[224:227], v[6:9]
	v_mfma_f32_16x16x32_bf16 v[6:9], v[180:183], v[228:231], v[6:9]
	v_mfma_f32_16x16x32_bf16 v[2:5], v[188:191], v[228:231], v[2:5]
	v_mfma_f32_16x16x32_bf16 v[2:5], v[184:187], v[224:227], v[2:5]
	v_mfma_f32_16x16x32_bf16 v[18:21], v[184:187], v[216:219], v[18:21]
	v_mfma_f32_16x16x32_bf16 v[18:21], v[188:191], v[220:223], v[18:21]
	v_mfma_f32_16x16x32_bf16 v[22:25], v[180:183], v[220:223], v[22:25]
	v_mfma_f32_16x16x32_bf16 v[22:25], v[176:179], v[216:219], v[22:25]
	v_mfma_f32_16x16x32_bf16 v[38:41], v[176:179], v[208:211], v[38:41]
	v_mfma_f32_16x16x32_bf16 v[38:41], v[180:183], v[212:215], v[38:41]
	v_mfma_f32_16x16x32_bf16 v[34:37], v[188:191], v[212:215], v[34:37]
	v_mfma_f32_16x16x32_bf16 v[34:37], v[184:187], v[208:211], v[34:37]
	v_mfma_f32_16x16x32_bf16 v[50:53], v[184:187], v[192:195], v[50:53]
	v_mfma_f32_16x16x32_bf16 v[50:53], v[188:191], v[204:207], v[50:53]
	v_mfma_f32_16x16x32_bf16 v[54:57], v[180:183], v[204:207], v[54:57]
	v_mfma_f32_16x16x32_bf16 v[54:57], v[176:179], v[192:195], v[54:57]
	s_barrier
	s_mov_b32 m0, s29
	ds_read_b128 v[142:145], v151
	global_load_lds_dwordx4 v130, s[24:25]
	s_mov_b32 m0, s30
	ds_read_b128 v[154:157], v151 offset:1024
	global_load_lds_dwordx4 v134, s[24:25]
	s_add_u32 s24, s24, 0x100000
	s_addc_u32 s25, s25, 0
	s_mov_b32 m0, s31
	ds_read_b128 v[158:161], v151 offset:2048
	global_load_lds_dwordx4 v130, s[24:25]
	s_mov_b32 m0, s33
	ds_read_b128 v[168:171], v151 offset:3072
	global_load_lds_dwordx4 v134, s[24:25]
	ds_read_b128 v[176:179], v152
	ds_read_b128 v[180:183], v152 offset:1024
	ds_read_b128 v[184:187], v152 offset:2048
	ds_read_b128 v[188:191], v152 offset:3072
	ds_read_b128 v[192:195], v150 offset:32768
	ds_read_b128 v[204:207], v150 offset:33792
	ds_read_b128 v[208:211], v150 offset:34816
	ds_read_b128 v[212:215], v150 offset:35840
	ds_read_b128 v[216:219], v150 offset:36864
	ds_read_b128 v[220:223], v150 offset:37888
	ds_read_b128 v[224:227], v150 offset:38912
	ds_read_b128 v[228:231], v150 offset:39936
	s_waitcnt vmcnt(8)
	s_waitcnt lgkmcnt(0)
	s_barrier
	v_mfma_f32_16x16x32_bf16 v[126:129], v[142:145], v[192:195], v[126:129]
	v_mfma_f32_16x16x32_bf16 v[126:129], v[154:157], v[204:207], v[126:129]
	v_mfma_f32_16x16x32_bf16 v[122:125], v[168:171], v[204:207], v[122:125]
	v_mfma_f32_16x16x32_bf16 v[122:125], v[158:161], v[192:195], v[122:125]
	v_mfma_f32_16x16x32_bf16 v[106:109], v[158:161], v[208:211], v[106:109]
	v_mfma_f32_16x16x32_bf16 v[106:109], v[168:171], v[212:215], v[106:109]
	v_mfma_f32_16x16x32_bf16 v[110:113], v[154:157], v[212:215], v[110:113]
	v_mfma_f32_16x16x32_bf16 v[110:113], v[142:145], v[208:211], v[110:113]
	v_mfma_f32_16x16x32_bf16 v[94:97], v[142:145], v[216:219], v[94:97]
	v_mfma_f32_16x16x32_bf16 v[94:97], v[154:157], v[220:223], v[94:97]
	v_mfma_f32_16x16x32_bf16 v[90:93], v[168:171], v[220:223], v[90:93]
	v_mfma_f32_16x16x32_bf16 v[90:93], v[158:161], v[216:219], v[90:93]
	v_mfma_f32_16x16x32_bf16 v[74:77], v[158:161], v[224:227], v[74:77]
	v_mfma_f32_16x16x32_bf16 v[74:77], v[168:171], v[228:231], v[74:77]
	v_mfma_f32_16x16x32_bf16 v[78:81], v[154:157], v[228:231], v[78:81]
	v_mfma_f32_16x16x32_bf16 v[78:81], v[142:145], v[224:227], v[78:81]
	v_mfma_f32_16x16x32_bf16 v[70:73], v[176:179], v[224:227], v[70:73]
	v_mfma_f32_16x16x32_bf16 v[70:73], v[180:183], v[228:231], v[70:73]
	v_mfma_f32_16x16x32_bf16 v[66:69], v[188:191], v[228:231], v[66:69]
	v_mfma_f32_16x16x32_bf16 v[66:69], v[184:187], v[224:227], v[66:69]
	v_mfma_f32_16x16x32_bf16 v[82:85], v[184:187], v[216:219], v[82:85]
	v_mfma_f32_16x16x32_bf16 v[82:85], v[188:191], v[220:223], v[82:85]
	v_mfma_f32_16x16x32_bf16 v[86:89], v[180:183], v[220:223], v[86:89]
	v_mfma_f32_16x16x32_bf16 v[86:89], v[176:179], v[216:219], v[86:89]
	v_mfma_f32_16x16x32_bf16 v[102:105], v[176:179], v[208:211], v[102:105]
	v_mfma_f32_16x16x32_bf16 v[102:105], v[180:183], v[212:215], v[102:105]
	v_mfma_f32_16x16x32_bf16 v[98:101], v[188:191], v[212:215], v[98:101]
	v_mfma_f32_16x16x32_bf16 v[98:101], v[184:187], v[208:211], v[98:101]
	v_mfma_f32_16x16x32_bf16 v[114:117], v[184:187], v[192:195], v[114:117]
	v_mfma_f32_16x16x32_bf16 v[114:117], v[188:191], v[204:207], v[114:117]
	v_mfma_f32_16x16x32_bf16 v[118:121], v[180:183], v[204:207], v[118:121]
	v_mfma_f32_16x16x32_bf16 v[118:121], v[176:179], v[192:195], v[118:121]
	s_barrier
	s_mov_b32 m0, s46
	s_add_u32 s22, s22, 0x80
	s_addc_u32 s23, s23, 0
	global_load_lds_dwordx4 v132, s[22:23]
	s_mov_b32 m0, s47
	ds_read_b128 v[192:195], v150 offset:49152
	global_load_lds_dwordx4 v136, s[22:23]
	s_mov_b32 m0, s48
	s_add_u32 s22, s22, 0x100000
	s_addc_u32 s23, s23, 0
	global_load_lds_dwordx4 v132, s[22:23]
	s_mov_b32 m0, s49
	ds_read_b128 v[204:207], v150 offset:50176
	global_load_lds_dwordx4 v136, s[22:23]
	ds_read_b128 v[208:211], v150 offset:51200
	ds_read_b128 v[212:215], v150 offset:52224
	ds_read_b128 v[216:219], v150 offset:53248
	ds_read_b128 v[220:223], v150 offset:54272
	ds_read_b128 v[224:227], v150 offset:55296
	ds_read_b128 v[228:231], v150 offset:56320
	s_waitcnt vmcnt(6)
	s_waitcnt lgkmcnt(0)
	s_barrier
	v_mfma_f32_16x16x32_bf16 v[62:65], v[142:145], v[192:195], v[62:65]
	v_mfma_f32_16x16x32_bf16 v[62:65], v[154:157], v[204:207], v[62:65]
	v_mfma_f32_16x16x32_bf16 v[58:61], v[168:171], v[204:207], v[58:61]
	v_mfma_f32_16x16x32_bf16 v[58:61], v[158:161], v[192:195], v[58:61]
	v_mfma_f32_16x16x32_bf16 v[42:45], v[158:161], v[208:211], v[42:45]
	v_mfma_f32_16x16x32_bf16 v[42:45], v[168:171], v[212:215], v[42:45]
	v_mfma_f32_16x16x32_bf16 v[46:49], v[154:157], v[212:215], v[46:49]
	v_mfma_f32_16x16x32_bf16 v[46:49], v[142:145], v[208:211], v[46:49]
	v_mfma_f32_16x16x32_bf16 v[30:33], v[142:145], v[216:219], v[30:33]
	v_mfma_f32_16x16x32_bf16 v[30:33], v[154:157], v[220:223], v[30:33]
	v_mfma_f32_16x16x32_bf16 v[26:29], v[168:171], v[220:223], v[26:29]
	v_mfma_f32_16x16x32_bf16 v[26:29], v[158:161], v[216:219], v[26:29]
	v_mfma_f32_16x16x32_bf16 v[10:13], v[158:161], v[224:227], v[10:13]
	v_mfma_f32_16x16x32_bf16 v[10:13], v[168:171], v[228:231], v[10:13]
	v_mfma_f32_16x16x32_bf16 v[14:17], v[154:157], v[228:231], v[14:17]
	v_mfma_f32_16x16x32_bf16 v[14:17], v[142:145], v[224:227], v[14:17]
	v_mfma_f32_16x16x32_bf16 v[6:9], v[176:179], v[224:227], v[6:9]
	v_mfma_f32_16x16x32_bf16 v[6:9], v[180:183], v[228:231], v[6:9]
	v_mfma_f32_16x16x32_bf16 v[2:5], v[188:191], v[228:231], v[2:5]
	v_mfma_f32_16x16x32_bf16 v[2:5], v[184:187], v[224:227], v[2:5]
	v_mfma_f32_16x16x32_bf16 v[18:21], v[184:187], v[216:219], v[18:21]
	v_mfma_f32_16x16x32_bf16 v[18:21], v[188:191], v[220:223], v[18:21]
	v_mfma_f32_16x16x32_bf16 v[22:25], v[180:183], v[220:223], v[22:25]
	v_mfma_f32_16x16x32_bf16 v[22:25], v[176:179], v[216:219], v[22:25]
	v_mfma_f32_16x16x32_bf16 v[38:41], v[176:179], v[208:211], v[38:41]
	v_mfma_f32_16x16x32_bf16 v[38:41], v[180:183], v[212:215], v[38:41]
	v_mfma_f32_16x16x32_bf16 v[34:37], v[188:191], v[212:215], v[34:37]
	v_mfma_f32_16x16x32_bf16 v[34:37], v[184:187], v[208:211], v[34:37]
	v_mfma_f32_16x16x32_bf16 v[50:53], v[184:187], v[192:195], v[50:53]
	v_mfma_f32_16x16x32_bf16 v[50:53], v[188:191], v[204:207], v[50:53]
	v_mfma_f32_16x16x32_bf16 v[54:57], v[180:183], v[204:207], v[54:57]
	v_mfma_f32_16x16x32_bf16 v[54:57], v[176:179], v[192:195], v[54:57]
	s_barrier
	s_add_i32 s57, s57, 2
	s_add_u32 s20, s20, 0x100
	s_addc_u32 s21, s21, 0
	s_add_u32 s55, s55, 0x100
	s_addc_u32 s56, s56, 0
	s_cmp_gt_u32 s57, 61
	s_cbranch_scc0 .LBB0_2373
	s_and_b64 vcc, exec, s[16:17]
	s_cbranch_vccz .LBB0_2376
	s_barrier

.LBB0_2618:
	s_add_u32 s64, s28, 0xffd50000
	s_addc_u32 s65, s29, -1
	s_mov_b32 m0, s44
	ds_read_b128 v[142:145], v156
	global_load_lds_dwordx4 v130, s[64:65]
	s_mov_b32 m0, s45
	ds_read_b128 v[168:171], v156 offset:1024
	global_load_lds_dwordx4 v134, s[64:65]
	s_mov_b32 m0, s46
	ds_read_b128 v[172:175], v156 offset:2048
	global_load_lds_dwordx4 v138, s[28:29]
	s_mov_b32 m0, s47
	ds_read_b128 v[176:179], v156 offset:3072
	global_load_lds_dwordx4 v140, s[28:29]
	ds_read_b128 v[180:183], v157
	ds_read_b128 v[184:187], v157 offset:1024
	ds_read_b128 v[188:191], v157 offset:2048
	ds_read_b128 v[192:195], v157 offset:3072
	s_add_u32 s30, s28, 0xffd50080
	s_addc_u32 s31, s29, -1
	s_cmpk_eq_i32 s62, 0xa8
	s_cselect_b32 s35, s25, s31
	s_cselect_b32 s34, s24, s30
	s_cselect_b32 s31, s23, s61
	s_cselect_b32 s30, s22, s60
	ds_read_b128 v[196:199], v158
	ds_read_b128 v[200:203], v158 offset:1024
	ds_read_b128 v[204:207], v158 offset:2048
	ds_read_b128 v[208:211], v158 offset:3072
	ds_read_b128 v[212:215], v158 offset:4096
	ds_read_b128 v[216:219], v158 offset:5120
	ds_read_b128 v[220:223], v158 offset:6144
	ds_read_b128 v[224:227], v158 offset:7168
	s_waitcnt vmcnt(8)
	s_waitcnt lgkmcnt(0)
	s_barrier
	v_mfma_f32_16x16x32_bf16 v[126:129], v[142:145], v[196:199], v[126:129]
	v_mfma_f32_16x16x32_bf16 v[126:129], v[168:171], v[200:203], v[126:129]
	v_mfma_f32_16x16x32_bf16 v[122:125], v[176:179], v[200:203], v[122:125]
	v_mfma_f32_16x16x32_bf16 v[122:125], v[172:175], v[196:199], v[122:125]
	v_mfma_f32_16x16x32_bf16 v[106:109], v[172:175], v[204:207], v[106:109]
	v_mfma_f32_16x16x32_bf16 v[106:109], v[176:179], v[208:211], v[106:109]
	v_mfma_f32_16x16x32_bf16 v[110:113], v[168:171], v[208:211], v[110:113]
	v_mfma_f32_16x16x32_bf16 v[110:113], v[142:145], v[204:207], v[110:113]
	v_mfma_f32_16x16x32_bf16 v[94:97], v[142:145], v[212:215], v[94:97]
	v_mfma_f32_16x16x32_bf16 v[94:97], v[168:171], v[216:219], v[94:97]
	v_mfma_f32_16x16x32_bf16 v[90:93], v[176:179], v[216:219], v[90:93]
	v_mfma_f32_16x16x32_bf16 v[90:93], v[172:175], v[212:215], v[90:93]
	v_mfma_f32_16x16x32_bf16 v[74:77], v[172:175], v[220:223], v[74:77]
	v_mfma_f32_16x16x32_bf16 v[74:77], v[176:179], v[224:227], v[74:77]
	v_mfma_f32_16x16x32_bf16 v[78:81], v[168:171], v[224:227], v[78:81]
	v_mfma_f32_16x16x32_bf16 v[78:81], v[142:145], v[220:223], v[78:81]
	v_mfma_f32_16x16x32_bf16 v[70:73], v[180:183], v[220:223], v[70:73]
	v_mfma_f32_16x16x32_bf16 v[70:73], v[184:187], v[224:227], v[70:73]
	v_mfma_f32_16x16x32_bf16 v[66:69], v[192:195], v[224:227], v[66:69]
	v_mfma_f32_16x16x32_bf16 v[66:69], v[188:191], v[220:223], v[66:69]
	v_mfma_f32_16x16x32_bf16 v[82:85], v[188:191], v[212:215], v[82:85]
	v_mfma_f32_16x16x32_bf16 v[82:85], v[192:195], v[216:219], v[82:85]
	v_mfma_f32_16x16x32_bf16 v[86:89], v[184:187], v[216:219], v[86:89]
	v_mfma_f32_16x16x32_bf16 v[86:89], v[180:183], v[212:215], v[86:89]
	v_mfma_f32_16x16x32_bf16 v[102:105], v[180:183], v[204:207], v[102:105]
	v_mfma_f32_16x16x32_bf16 v[102:105], v[184:187], v[208:211], v[102:105]
	v_mfma_f32_16x16x32_bf16 v[98:101], v[192:195], v[208:211], v[98:101]
	v_mfma_f32_16x16x32_bf16 v[98:101], v[188:191], v[204:207], v[98:101]
	v_mfma_f32_16x16x32_bf16 v[114:117], v[188:191], v[196:199], v[114:117]
	v_mfma_f32_16x16x32_bf16 v[114:117], v[192:195], v[200:203], v[114:117]
	v_mfma_f32_16x16x32_bf16 v[118:121], v[184:187], v[200:203], v[118:121]
	v_mfma_f32_16x16x32_bf16 v[118:121], v[180:183], v[196:199], v[118:121]
	s_barrier
	s_mov_b32 m0, s48
	s_add_u32 s64, s30, 0x2b0000
	global_load_lds_dwordx4 v132, s[30:31]
	s_mov_b32 m0, s49
	s_addc_u32 s65, s31, 0
	global_load_lds_dwordx4 v136, s[30:31]
	s_mov_b32 m0, s50
	ds_read_b128 v[196:199], v158 offset:16384
	global_load_lds_dwordx4 v132, s[64:65]
	s_mov_b32 m0, s51
	ds_read_b128 v[200:203], v158 offset:17408
	global_load_lds_dwordx4 v136, s[64:65]
	ds_read_b128 v[204:207], v158 offset:18432
	ds_read_b128 v[208:211], v158 offset:19456
	ds_read_b128 v[212:215], v158 offset:20480
	ds_read_b128 v[216:219], v158 offset:21504
	ds_read_b128 v[220:223], v158 offset:22528
	ds_read_b128 v[224:227], v158 offset:23552
	s_waitcnt vmcnt(6)
	s_waitcnt lgkmcnt(0)
	s_barrier
	v_mfma_f32_16x16x32_bf16 v[62:65], v[142:145], v[196:199], v[62:65]
	v_mfma_f32_16x16x32_bf16 v[62:65], v[168:171], v[200:203], v[62:65]
	v_mfma_f32_16x16x32_bf16 v[58:61], v[176:179], v[200:203], v[58:61]
	v_mfma_f32_16x16x32_bf16 v[58:61], v[172:175], v[196:199], v[58:61]
	v_mfma_f32_16x16x32_bf16 v[42:45], v[172:175], v[204:207], v[42:45]
	v_mfma_f32_16x16x32_bf16 v[42:45], v[176:179], v[208:211], v[42:45]
	v_mfma_f32_16x16x32_bf16 v[46:49], v[168:171], v[208:211], v[46:49]
	v_mfma_f32_16x16x32_bf16 v[46:49], v[142:145], v[204:207], v[46:49]
	v_mfma_f32_16x16x32_bf16 v[30:33], v[142:145], v[212:215], v[30:33]
	v_mfma_f32_16x16x32_bf16 v[30:33], v[168:171], v[216:219], v[30:33]
	v_mfma_f32_16x16x32_bf16 v[26:29], v[176:179], v[216:219], v[26:29]
	v_mfma_f32_16x16x32_bf16 v[26:29], v[172:175], v[212:215], v[26:29]
	v_mfma_f32_16x16x32_bf16 v[10:13], v[172:175], v[220:223], v[10:13]
	v_mfma_f32_16x16x32_bf16 v[10:13], v[176:179], v[224:227], v[10:13]
	v_mfma_f32_16x16x32_bf16 v[14:17], v[168:171], v[224:227], v[14:17]
	v_mfma_f32_16x16x32_bf16 v[14:17], v[142:145], v[220:223], v[14:17]
	v_mfma_f32_16x16x32_bf16 v[6:9], v[180:183], v[220:223], v[6:9]
	v_mfma_f32_16x16x32_bf16 v[6:9], v[184:187], v[224:227], v[6:9]
	v_mfma_f32_16x16x32_bf16 v[2:5], v[192:195], v[224:227], v[2:5]
	v_mfma_f32_16x16x32_bf16 v[2:5], v[188:191], v[220:223], v[2:5]
	v_mfma_f32_16x16x32_bf16 v[18:21], v[188:191], v[212:215], v[18:21]
	v_mfma_f32_16x16x32_bf16 v[18:21], v[192:195], v[216:219], v[18:21]
	v_mfma_f32_16x16x32_bf16 v[22:25], v[184:187], v[216:219], v[22:25]
	v_mfma_f32_16x16x32_bf16 v[22:25], v[180:183], v[212:215], v[22:25]
	v_mfma_f32_16x16x32_bf16 v[38:41], v[180:183], v[204:207], v[38:41]
	v_mfma_f32_16x16x32_bf16 v[38:41], v[184:187], v[208:211], v[38:41]
	v_mfma_f32_16x16x32_bf16 v[34:37], v[192:195], v[208:211], v[34:37]
	v_mfma_f32_16x16x32_bf16 v[34:37], v[188:191], v[204:207], v[34:37]
	v_mfma_f32_16x16x32_bf16 v[50:53], v[188:191], v[196:199], v[50:53]
	v_mfma_f32_16x16x32_bf16 v[50:53], v[192:195], v[200:203], v[50:53]
	v_mfma_f32_16x16x32_bf16 v[54:57], v[184:187], v[200:203], v[54:57]
	v_mfma_f32_16x16x32_bf16 v[54:57], v[180:183], v[196:199], v[54:57]
	s_barrier
	s_mov_b32 m0, s39
	ds_read_b128 v[142:145], v159
	global_load_lds_dwordx4 v130, s[34:35]
	s_mov_b32 m0, s40
	ds_read_b128 v[168:171], v159 offset:1024
	global_load_lds_dwordx4 v134, s[34:35]
	s_add_u32 s34, s34, 0x2b0000
	s_addc_u32 s35, s35, 0
	s_mov_b32 m0, s41
	ds_read_b128 v[172:175], v159 offset:2048
	global_load_lds_dwordx4 v130, s[34:35]
	s_mov_b32 m0, s42
	ds_read_b128 v[176:179], v159 offset:3072
	global_load_lds_dwordx4 v134, s[34:35]
	ds_read_b128 v[180:183], v160
	ds_read_b128 v[184:187], v160 offset:1024
	ds_read_b128 v[188:191], v160 offset:2048
	ds_read_b128 v[192:195], v160 offset:3072
	ds_read_b128 v[196:199], v158 offset:32768
	ds_read_b128 v[200:203], v158 offset:33792
	ds_read_b128 v[204:207], v158 offset:34816
	ds_read_b128 v[208:211], v158 offset:35840
	ds_read_b128 v[212:215], v158 offset:36864
	ds_read_b128 v[216:219], v158 offset:37888
	ds_read_b128 v[220:223], v158 offset:38912
	ds_read_b128 v[224:227], v158 offset:39936
	s_waitcnt vmcnt(8)
	s_waitcnt lgkmcnt(0)
	s_barrier
	v_mfma_f32_16x16x32_bf16 v[126:129], v[142:145], v[196:199], v[126:129]
	v_mfma_f32_16x16x32_bf16 v[126:129], v[168:171], v[200:203], v[126:129]
	v_mfma_f32_16x16x32_bf16 v[122:125], v[176:179], v[200:203], v[122:125]
	v_mfma_f32_16x16x32_bf16 v[122:125], v[172:175], v[196:199], v[122:125]
	v_mfma_f32_16x16x32_bf16 v[106:109], v[172:175], v[204:207], v[106:109]
	v_mfma_f32_16x16x32_bf16 v[106:109], v[176:179], v[208:211], v[106:109]
	v_mfma_f32_16x16x32_bf16 v[110:113], v[168:171], v[208:211], v[110:113]
	v_mfma_f32_16x16x32_bf16 v[110:113], v[142:145], v[204:207], v[110:113]
	v_mfma_f32_16x16x32_bf16 v[94:97], v[142:145], v[212:215], v[94:97]
	v_mfma_f32_16x16x32_bf16 v[94:97], v[168:171], v[216:219], v[94:97]
	v_mfma_f32_16x16x32_bf16 v[90:93], v[176:179], v[216:219], v[90:93]
	v_mfma_f32_16x16x32_bf16 v[90:93], v[172:175], v[212:215], v[90:93]
	v_mfma_f32_16x16x32_bf16 v[74:77], v[172:175], v[220:223], v[74:77]
	v_mfma_f32_16x16x32_bf16 v[74:77], v[176:179], v[224:227], v[74:77]
	v_mfma_f32_16x16x32_bf16 v[78:81], v[168:171], v[224:227], v[78:81]
	v_mfma_f32_16x16x32_bf16 v[78:81], v[142:145], v[220:223], v[78:81]
	v_mfma_f32_16x16x32_bf16 v[70:73], v[180:183], v[220:223], v[70:73]
	v_mfma_f32_16x16x32_bf16 v[70:73], v[184:187], v[224:227], v[70:73]
	v_mfma_f32_16x16x32_bf16 v[66:69], v[192:195], v[224:227], v[66:69]
	v_mfma_f32_16x16x32_bf16 v[66:69], v[188:191], v[220:223], v[66:69]
	v_mfma_f32_16x16x32_bf16 v[82:85], v[188:191], v[212:215], v[82:85]
	v_mfma_f32_16x16x32_bf16 v[82:85], v[192:195], v[216:219], v[82:85]
	v_mfma_f32_16x16x32_bf16 v[86:89], v[184:187], v[216:219], v[86:89]
	v_mfma_f32_16x16x32_bf16 v[86:89], v[180:183], v[212:215], v[86:89]
	v_mfma_f32_16x16x32_bf16 v[102:105], v[180:183], v[204:207], v[102:105]
	v_mfma_f32_16x16x32_bf16 v[102:105], v[184:187], v[208:211], v[102:105]
	v_mfma_f32_16x16x32_bf16 v[98:101], v[192:195], v[208:211], v[98:101]
	v_mfma_f32_16x16x32_bf16 v[98:101], v[188:191], v[204:207], v[98:101]
	v_mfma_f32_16x16x32_bf16 v[114:117], v[188:191], v[196:199], v[114:117]
	v_mfma_f32_16x16x32_bf16 v[114:117], v[192:195], v[200:203], v[114:117]
	v_mfma_f32_16x16x32_bf16 v[118:121], v[184:187], v[200:203], v[118:121]
	v_mfma_f32_16x16x32_bf16 v[118:121], v[180:183], v[196:199], v[118:121]
	s_barrier
	s_mov_b32 m0, s52
	s_add_u32 s30, s30, 0x80
	s_addc_u32 s31, s31, 0
	global_load_lds_dwordx4 v132, s[30:31]
	s_mov_b32 m0, s53
	ds_read_b128 v[196:199], v158 offset:49152
	global_load_lds_dwordx4 v136, s[30:31]
	s_mov_b32 m0, s54
	s_add_u32 s30, s30, 0x2b0000
	s_addc_u32 s31, s31, 0
	global_load_lds_dwordx4 v132, s[30:31]
	s_mov_b32 m0, s55
	ds_read_b128 v[200:203], v158 offset:50176
	global_load_lds_dwordx4 v136, s[30:31]
	ds_read_b128 v[204:207], v158 offset:51200
	ds_read_b128 v[208:211], v158 offset:52224
	ds_read_b128 v[212:215], v158 offset:53248
	ds_read_b128 v[216:219], v158 offset:54272
	ds_read_b128 v[220:223], v158 offset:55296
	ds_read_b128 v[224:227], v158 offset:56320
	s_waitcnt vmcnt(6)
	s_waitcnt lgkmcnt(0)
	s_barrier
	v_mfma_f32_16x16x32_bf16 v[62:65], v[142:145], v[196:199], v[62:65]
	v_mfma_f32_16x16x32_bf16 v[62:65], v[168:171], v[200:203], v[62:65]
	v_mfma_f32_16x16x32_bf16 v[58:61], v[176:179], v[200:203], v[58:61]
	v_mfma_f32_16x16x32_bf16 v[58:61], v[172:175], v[196:199], v[58:61]
	v_mfma_f32_16x16x32_bf16 v[42:45], v[172:175], v[204:207], v[42:45]
	v_mfma_f32_16x16x32_bf16 v[42:45], v[176:179], v[208:211], v[42:45]
	v_mfma_f32_16x16x32_bf16 v[46:49], v[168:171], v[208:211], v[46:49]
	v_mfma_f32_16x16x32_bf16 v[46:49], v[142:145], v[204:207], v[46:49]
	v_mfma_f32_16x16x32_bf16 v[30:33], v[142:145], v[212:215], v[30:33]
	v_mfma_f32_16x16x32_bf16 v[30:33], v[168:171], v[216:219], v[30:33]
	v_mfma_f32_16x16x32_bf16 v[26:29], v[176:179], v[216:219], v[26:29]
	v_mfma_f32_16x16x32_bf16 v[26:29], v[172:175], v[212:215], v[26:29]
	v_mfma_f32_16x16x32_bf16 v[10:13], v[172:175], v[220:223], v[10:13]
	v_mfma_f32_16x16x32_bf16 v[10:13], v[176:179], v[224:227], v[10:13]
	v_mfma_f32_16x16x32_bf16 v[14:17], v[168:171], v[224:227], v[14:17]
	v_mfma_f32_16x16x32_bf16 v[14:17], v[142:145], v[220:223], v[14:17]
	v_mfma_f32_16x16x32_bf16 v[6:9], v[180:183], v[220:223], v[6:9]
	v_mfma_f32_16x16x32_bf16 v[6:9], v[184:187], v[224:227], v[6:9]
	v_mfma_f32_16x16x32_bf16 v[2:5], v[192:195], v[224:227], v[2:5]
	v_mfma_f32_16x16x32_bf16 v[2:5], v[188:191], v[220:223], v[2:5]
	v_mfma_f32_16x16x32_bf16 v[18:21], v[188:191], v[212:215], v[18:21]
	v_mfma_f32_16x16x32_bf16 v[18:21], v[192:195], v[216:219], v[18:21]
	v_mfma_f32_16x16x32_bf16 v[22:25], v[184:187], v[216:219], v[22:25]
	v_mfma_f32_16x16x32_bf16 v[22:25], v[180:183], v[212:215], v[22:25]
	v_mfma_f32_16x16x32_bf16 v[38:41], v[180:183], v[204:207], v[38:41]
	v_mfma_f32_16x16x32_bf16 v[38:41], v[184:187], v[208:211], v[38:41]
	v_mfma_f32_16x16x32_bf16 v[34:37], v[192:195], v[208:211], v[34:37]
	v_mfma_f32_16x16x32_bf16 v[34:37], v[188:191], v[204:207], v[34:37]
	v_mfma_f32_16x16x32_bf16 v[50:53], v[188:191], v[196:199], v[50:53]
	v_mfma_f32_16x16x32_bf16 v[50:53], v[192:195], v[200:203], v[50:53]
	v_mfma_f32_16x16x32_bf16 v[54:57], v[184:187], v[200:203], v[54:57]
	v_mfma_f32_16x16x32_bf16 v[54:57], v[180:183], v[196:199], v[54:57]
	s_barrier
	s_add_i32 s62, s62, 2
	s_add_u32 s28, s28, 0x100
	s_addc_u32 s29, s29, 0
	s_add_u32 s60, s60, 0x100
	s_addc_u32 s61, s61, 0
	s_cmpk_gt_u32 s62, 0xa9
	s_cbranch_scc0 .LBB0_2618
	s_and_b64 vcc, exec, s[12:13]
	s_cbranch_vccz .LBB0_2621
	s_barrier

.LBB0_2632:
	ds_read_b128 v[150:153], v1
	ds_read_b128 v[154:157], v1 offset:1024
	ds_read_b128 v[158:161], v1 offset:2048
	ds_read_b128 v[166:169], v1 offset:3072
	ds_read_b128 v[170:173], v139
	ds_read_b128 v[174:177], v139 offset:1024
	ds_read_b128 v[178:181], v139 offset:2048
	ds_read_b128 v[182:185], v139 offset:3072
	s_add_i32 s38, s13, 2
	s_add_u32 s12, s10, 0xc2050080
	s_addc_u32 s14, s11, -1
	s_cmp_lg_u32 s26, s13
	s_cselect_b32 s12, s12, 0
	s_cselect_b32 s13, s14, 0
	s_add_u32 s14, s4, s12
	s_addc_u32 s15, s5, s13
	s_add_u32 s12, s6, s12
	s_addc_u32 s13, s7, s13
	s_mov_b32 m0, s27
	v_lshl_add_u64 v[162:163], v[140:141], 0, s[10:11]
	ds_read_b128 v[186:189], v144
	ds_read_b128 v[190:193], v144 offset:1024
	ds_read_b128 v[194:197], v144 offset:2048
	ds_read_b128 v[198:201], v144 offset:3072
	ds_read_b128 v[202:205], v144 offset:4096
	ds_read_b128 v[206:209], v144 offset:5120
	ds_read_b128 v[210:213], v144 offset:6144
	ds_read_b128 v[214:217], v144 offset:7168
	global_load_lds_dwordx4 v[162:163], off
	v_lshl_add_u64 v[162:163], v[142:143], 0, s[10:11]
	s_mov_b32 m0, s28
	s_nop 0
	global_load_lds_dwordx4 v[162:163], off
	s_waitcnt vmcnt(8)
	s_waitcnt lgkmcnt(0)
	s_barrier
	v_mfma_f32_16x16x32_bf16 v[126:129], v[150:153], v[186:189], v[126:129]
	v_mfma_f32_16x16x32_bf16 v[126:129], v[154:157], v[190:193], v[126:129]
	v_mfma_f32_16x16x32_bf16 v[122:125], v[166:169], v[190:193], v[122:125]
	v_mfma_f32_16x16x32_bf16 v[122:125], v[158:161], v[186:189], v[122:125]
	v_mfma_f32_16x16x32_bf16 v[114:117], v[158:161], v[194:197], v[114:117]
	v_mfma_f32_16x16x32_bf16 v[114:117], v[166:169], v[198:201], v[114:117]
	v_mfma_f32_16x16x32_bf16 v[118:121], v[154:157], v[198:201], v[118:121]
	v_mfma_f32_16x16x32_bf16 v[118:121], v[150:153], v[194:197], v[118:121]
	v_mfma_f32_16x16x32_bf16 v[102:105], v[150:153], v[202:205], v[102:105]
	v_mfma_f32_16x16x32_bf16 v[102:105], v[154:157], v[206:209], v[102:105]
	v_mfma_f32_16x16x32_bf16 v[98:101], v[166:169], v[206:209], v[98:101]
	v_mfma_f32_16x16x32_bf16 v[98:101], v[158:161], v[202:205], v[98:101]
	v_mfma_f32_16x16x32_bf16 v[82:85], v[158:161], v[210:213], v[82:85]
	v_mfma_f32_16x16x32_bf16 v[82:85], v[166:169], v[214:217], v[82:85]
	v_mfma_f32_16x16x32_bf16 v[86:89], v[154:157], v[214:217], v[86:89]
	v_mfma_f32_16x16x32_bf16 v[86:89], v[150:153], v[210:213], v[86:89]
	v_mfma_f32_16x16x32_bf16 v[70:73], v[170:173], v[210:213], v[70:73]
	v_mfma_f32_16x16x32_bf16 v[70:73], v[174:177], v[214:217], v[70:73]
	v_mfma_f32_16x16x32_bf16 v[66:69], v[182:185], v[214:217], v[66:69]
	v_mfma_f32_16x16x32_bf16 v[66:69], v[178:181], v[210:213], v[66:69]
	v_mfma_f32_16x16x32_bf16 v[74:77], v[178:181], v[202:205], v[74:77]
	v_mfma_f32_16x16x32_bf16 v[74:77], v[182:185], v[206:209], v[74:77]
	v_mfma_f32_16x16x32_bf16 v[78:81], v[174:177], v[206:209], v[78:81]
	v_mfma_f32_16x16x32_bf16 v[78:81], v[170:173], v[202:205], v[78:81]
	v_mfma_f32_16x16x32_bf16 v[94:97], v[170:173], v[194:197], v[94:97]
	v_mfma_f32_16x16x32_bf16 v[94:97], v[174:177], v[198:201], v[94:97]
	v_mfma_f32_16x16x32_bf16 v[90:93], v[182:185], v[198:201], v[90:93]
	v_mfma_f32_16x16x32_bf16 v[90:93], v[178:181], v[194:197], v[90:93]
	v_mfma_f32_16x16x32_bf16 v[106:109], v[178:181], v[186:189], v[106:109]
	v_mfma_f32_16x16x32_bf16 v[106:109], v[182:185], v[190:193], v[106:109]
	v_mfma_f32_16x16x32_bf16 v[110:113], v[174:177], v[190:193], v[110:113]
	v_mfma_f32_16x16x32_bf16 v[110:113], v[170:173], v[186:189], v[110:113]
	s_barrier
	s_mov_b32 m0, s29
	v_lshl_add_u64 v[162:163], s[12:13], 0, v[132:133]
	s_add_u32 s40, s12, 0x2b0000
	ds_read_b128 v[186:189], v144 offset:16384
	ds_read_b128 v[190:193], v144 offset:17408
	ds_read_b128 v[194:197], v144 offset:18432
	ds_read_b128 v[198:201], v144 offset:19456
	ds_read_b128 v[202:205], v144 offset:20480
	ds_read_b128 v[206:209], v144 offset:21504
	ds_read_b128 v[210:213], v144 offset:22528
	ds_read_b128 v[214:217], v144 offset:23552
	global_load_lds_dwordx4 v[162:163], off
	v_lshl_add_u64 v[218:219], s[12:13], 0, v[136:137]
	s_mov_b32 m0, s30
	s_addc_u32 s41, s13, 0
	global_load_lds_dwordx4 v[218:219], off
	v_lshl_add_u64 v[220:221], s[40:41], 0, v[132:133]
	s_mov_b32 m0, s31
	v_lshl_add_u64 v[222:223], s[14:15], 0, v[134:135]
	global_load_lds_dwordx4 v[220:221], off
	v_lshl_add_u64 v[220:221], s[40:41], 0, v[136:137]
	s_mov_b32 m0, s33
	s_nop 0
	global_load_lds_dwordx4 v[220:221], off
	v_lshl_add_u64 v[220:221], s[14:15], 0, v[130:131]
	s_mov_b32 m0, s19
	s_nop 0
	global_load_lds_dwordx4 v[220:221], off
	s_mov_b32 m0, s20
	s_nop 0
	global_load_lds_dwordx4 v[222:223], off
	s_waitcnt vmcnt(8)
	s_waitcnt lgkmcnt(0)
	s_barrier
	v_mfma_f32_16x16x32_bf16 v[62:65], v[150:153], v[186:189], v[62:65]
	v_mfma_f32_16x16x32_bf16 v[62:65], v[154:157], v[190:193], v[62:65]
	v_mfma_f32_16x16x32_bf16 v[58:61], v[166:169], v[190:193], v[58:61]
	v_mfma_f32_16x16x32_bf16 v[58:61], v[158:161], v[186:189], v[58:61]
	v_mfma_f32_16x16x32_bf16 v[50:53], v[158:161], v[194:197], v[50:53]
	v_mfma_f32_16x16x32_bf16 v[50:53], v[166:169], v[198:201], v[50:53]
	v_mfma_f32_16x16x32_bf16 v[54:57], v[154:157], v[198:201], v[54:57]
	v_mfma_f32_16x16x32_bf16 v[54:57], v[150:153], v[194:197], v[54:57]
	v_mfma_f32_16x16x32_bf16 v[38:41], v[150:153], v[202:205], v[38:41]
	v_mfma_f32_16x16x32_bf16 v[38:41], v[154:157], v[206:209], v[38:41]
	v_mfma_f32_16x16x32_bf16 v[34:37], v[166:169], v[206:209], v[34:37]
	v_mfma_f32_16x16x32_bf16 v[34:37], v[158:161], v[202:205], v[34:37]
	v_mfma_f32_16x16x32_bf16 v[18:21], v[158:161], v[210:213], v[18:21]
	v_mfma_f32_16x16x32_bf16 v[18:21], v[166:169], v[214:217], v[18:21]
	v_mfma_f32_16x16x32_bf16 v[22:25], v[154:157], v[214:217], v[22:25]
	v_mfma_f32_16x16x32_bf16 v[22:25], v[150:153], v[210:213], v[22:25]
	v_mfma_f32_16x16x32_bf16 v[6:9], v[170:173], v[210:213], v[6:9]
	v_mfma_f32_16x16x32_bf16 v[6:9], v[174:177], v[214:217], v[6:9]
	v_mfma_f32_16x16x32_bf16 v[2:5], v[182:185], v[214:217], v[2:5]
	v_mfma_f32_16x16x32_bf16 v[2:5], v[178:181], v[210:213], v[2:5]
	v_mfma_f32_16x16x32_bf16 v[10:13], v[178:181], v[202:205], v[10:13]
	v_mfma_f32_16x16x32_bf16 v[10:13], v[182:185], v[206:209], v[10:13]
	v_mfma_f32_16x16x32_bf16 v[14:17], v[174:177], v[206:209], v[14:17]
	v_mfma_f32_16x16x32_bf16 v[14:17], v[170:173], v[202:205], v[14:17]
	v_mfma_f32_16x16x32_bf16 v[30:33], v[170:173], v[194:197], v[30:33]
	v_mfma_f32_16x16x32_bf16 v[30:33], v[174:177], v[198:201], v[30:33]
	v_mfma_f32_16x16x32_bf16 v[26:29], v[182:185], v[198:201], v[26:29]
	v_mfma_f32_16x16x32_bf16 v[26:29], v[178:181], v[194:197], v[26:29]
	v_mfma_f32_16x16x32_bf16 v[42:45], v[178:181], v[186:189], v[42:45]
	v_mfma_f32_16x16x32_bf16 v[42:45], v[182:185], v[190:193], v[42:45]
	v_mfma_f32_16x16x32_bf16 v[46:49], v[174:177], v[190:193], v[46:49]
	v_mfma_f32_16x16x32_bf16 v[46:49], v[170:173], v[186:189], v[46:49]
	s_barrier
	ds_read_b128 v[150:153], v145
	ds_read_b128 v[154:157], v145 offset:1024
	ds_read_b128 v[158:161], v145 offset:2048
	ds_read_b128 v[166:169], v145 offset:3072
	ds_read_b128 v[170:173], v146
	ds_read_b128 v[174:177], v146 offset:1024
	ds_read_b128 v[178:181], v146 offset:2048
	ds_read_b128 v[182:185], v146 offset:3072
	s_add_u32 s14, s14, 0x2b0000
	s_addc_u32 s15, s15, 0
	s_mov_b32 m0, s21
	v_lshl_add_u64 v[224:225], s[14:15], 0, v[130:131]
	ds_read_b128 v[186:189], v144 offset:32768
	ds_read_b128 v[190:193], v144 offset:33792
	ds_read_b128 v[194:197], v144 offset:34816
	ds_read_b128 v[198:201], v144 offset:35840
	ds_read_b128 v[202:205], v144 offset:36864
	ds_read_b128 v[206:209], v144 offset:37888
	ds_read_b128 v[210:213], v144 offset:38912
	ds_read_b128 v[214:217], v144 offset:39936
	global_load_lds_dwordx4 v[224:225], off
	v_lshl_add_u64 v[224:225], s[14:15], 0, v[134:135]
	s_mov_b32 m0, s22
	s_nop 0
	global_load_lds_dwordx4 v[224:225], off
	s_waitcnt vmcnt(8)
	s_waitcnt lgkmcnt(0)
	s_barrier
	v_mfma_f32_16x16x32_bf16 v[126:129], v[150:153], v[186:189], v[126:129]
	v_mfma_f32_16x16x32_bf16 v[126:129], v[154:157], v[190:193], v[126:129]
	v_mfma_f32_16x16x32_bf16 v[122:125], v[166:169], v[190:193], v[122:125]
	v_mfma_f32_16x16x32_bf16 v[122:125], v[158:161], v[186:189], v[122:125]
	v_mfma_f32_16x16x32_bf16 v[114:117], v[158:161], v[194:197], v[114:117]
	v_mfma_f32_16x16x32_bf16 v[114:117], v[166:169], v[198:201], v[114:117]
	v_mfma_f32_16x16x32_bf16 v[118:121], v[154:157], v[198:201], v[118:121]
	v_mfma_f32_16x16x32_bf16 v[118:121], v[150:153], v[194:197], v[118:121]
	v_mfma_f32_16x16x32_bf16 v[102:105], v[150:153], v[202:205], v[102:105]
	v_mfma_f32_16x16x32_bf16 v[102:105], v[154:157], v[206:209], v[102:105]
	v_mfma_f32_16x16x32_bf16 v[98:101], v[166:169], v[206:209], v[98:101]
	v_mfma_f32_16x16x32_bf16 v[98:101], v[158:161], v[202:205], v[98:101]
	v_mfma_f32_16x16x32_bf16 v[82:85], v[158:161], v[210:213], v[82:85]
	v_mfma_f32_16x16x32_bf16 v[82:85], v[166:169], v[214:217], v[82:85]
	v_mfma_f32_16x16x32_bf16 v[86:89], v[154:157], v[214:217], v[86:89]
	v_mfma_f32_16x16x32_bf16 v[86:89], v[150:153], v[210:213], v[86:89]
	v_mfma_f32_16x16x32_bf16 v[70:73], v[170:173], v[210:213], v[70:73]
	v_mfma_f32_16x16x32_bf16 v[70:73], v[174:177], v[214:217], v[70:73]
	v_mfma_f32_16x16x32_bf16 v[66:69], v[182:185], v[214:217], v[66:69]
	v_mfma_f32_16x16x32_bf16 v[66:69], v[178:181], v[210:213], v[66:69]
	v_mfma_f32_16x16x32_bf16 v[74:77], v[178:181], v[202:205], v[74:77]
	v_mfma_f32_16x16x32_bf16 v[74:77], v[182:185], v[206:209], v[74:77]
	v_mfma_f32_16x16x32_bf16 v[78:81], v[174:177], v[206:209], v[78:81]
	v_mfma_f32_16x16x32_bf16 v[78:81], v[170:173], v[202:205], v[78:81]
	v_mfma_f32_16x16x32_bf16 v[94:97], v[170:173], v[194:197], v[94:97]
	v_mfma_f32_16x16x32_bf16 v[94:97], v[174:177], v[198:201], v[94:97]
	v_mfma_f32_16x16x32_bf16 v[90:93], v[182:185], v[198:201], v[90:93]
	v_mfma_f32_16x16x32_bf16 v[90:93], v[178:181], v[194:197], v[90:93]
	v_mfma_f32_16x16x32_bf16 v[106:109], v[178:181], v[186:189], v[106:109]
	v_mfma_f32_16x16x32_bf16 v[106:109], v[182:185], v[190:193], v[106:109]
	v_mfma_f32_16x16x32_bf16 v[110:113], v[174:177], v[190:193], v[110:113]
	v_mfma_f32_16x16x32_bf16 v[110:113], v[170:173], v[186:189], v[110:113]
	s_barrier
	s_mov_b32 m0, s34
	v_lshl_add_u64 v[162:163], v[162:163], 0, s[8:9]
	s_add_u32 s12, s12, 0x2b0080
	ds_read_b128 v[186:189], v144 offset:49152
	ds_read_b128 v[190:193], v144 offset:50176
	ds_read_b128 v[194:197], v144 offset:51200
	ds_read_b128 v[198:201], v144 offset:52224
	ds_read_b128 v[202:205], v144 offset:53248
	ds_read_b128 v[206:209], v144 offset:54272
	ds_read_b128 v[210:213], v144 offset:55296
	ds_read_b128 v[214:217], v144 offset:56320
	global_load_lds_dwordx4 v[162:163], off
	v_lshl_add_u64 v[162:163], v[218:219], 0, s[8:9]
	s_mov_b32 m0, s35
	s_addc_u32 s13, s13, 0
	global_load_lds_dwordx4 v[162:163], off
	v_lshl_add_u64 v[162:163], s[12:13], 0, v[132:133]
	s_mov_b32 m0, s36
	s_nop 0
	global_load_lds_dwordx4 v[162:163], off
	v_lshl_add_u64 v[162:163], s[12:13], 0, v[136:137]
	s_mov_b32 m0, s37
	s_nop 0
	global_load_lds_dwordx4 v[162:163], off
	v_lshl_add_u64 v[162:163], v[220:221], 0, s[8:9]
	s_mov_b32 m0, s24
	s_nop 0
	global_load_lds_dwordx4 v[162:163], off
	v_lshl_add_u64 v[162:163], v[222:223], 0, s[8:9]
	s_mov_b32 m0, s25
	s_nop 0
	global_load_lds_dwordx4 v[162:163], off
	s_waitcnt vmcnt(8)
	s_waitcnt lgkmcnt(0)
	s_barrier
	v_mfma_f32_16x16x32_bf16 v[62:65], v[150:153], v[186:189], v[62:65]
	v_mfma_f32_16x16x32_bf16 v[62:65], v[154:157], v[190:193], v[62:65]
	v_mfma_f32_16x16x32_bf16 v[58:61], v[166:169], v[190:193], v[58:61]
	v_mfma_f32_16x16x32_bf16 v[58:61], v[158:161], v[186:189], v[58:61]
	v_mfma_f32_16x16x32_bf16 v[50:53], v[158:161], v[194:197], v[50:53]
	v_mfma_f32_16x16x32_bf16 v[50:53], v[166:169], v[198:201], v[50:53]
	v_mfma_f32_16x16x32_bf16 v[54:57], v[154:157], v[198:201], v[54:57]
	v_mfma_f32_16x16x32_bf16 v[54:57], v[150:153], v[194:197], v[54:57]
	v_mfma_f32_16x16x32_bf16 v[38:41], v[150:153], v[202:205], v[38:41]
	v_mfma_f32_16x16x32_bf16 v[38:41], v[154:157], v[206:209], v[38:41]
	v_mfma_f32_16x16x32_bf16 v[34:37], v[166:169], v[206:209], v[34:37]
	v_mfma_f32_16x16x32_bf16 v[34:37], v[158:161], v[202:205], v[34:37]
	v_mfma_f32_16x16x32_bf16 v[18:21], v[158:161], v[210:213], v[18:21]
	v_mfma_f32_16x16x32_bf16 v[18:21], v[166:169], v[214:217], v[18:21]
	v_mfma_f32_16x16x32_bf16 v[22:25], v[154:157], v[214:217], v[22:25]
	v_mfma_f32_16x16x32_bf16 v[22:25], v[150:153], v[210:213], v[22:25]
	v_mfma_f32_16x16x32_bf16 v[6:9], v[170:173], v[210:213], v[6:9]
	v_mfma_f32_16x16x32_bf16 v[6:9], v[174:177], v[214:217], v[6:9]
	v_mfma_f32_16x16x32_bf16 v[2:5], v[182:185], v[214:217], v[2:5]
	v_mfma_f32_16x16x32_bf16 v[2:5], v[178:181], v[210:213], v[2:5]
	v_mfma_f32_16x16x32_bf16 v[10:13], v[178:181], v[202:205], v[10:13]
	v_mfma_f32_16x16x32_bf16 v[10:13], v[182:185], v[206:209], v[10:13]
	v_mfma_f32_16x16x32_bf16 v[14:17], v[174:177], v[206:209], v[14:17]
	v_mfma_f32_16x16x32_bf16 v[14:17], v[170:173], v[202:205], v[14:17]
	v_mfma_f32_16x16x32_bf16 v[30:33], v[170:173], v[194:197], v[30:33]
	v_mfma_f32_16x16x32_bf16 v[30:33], v[174:177], v[198:201], v[30:33]
	v_mfma_f32_16x16x32_bf16 v[26:29], v[182:185], v[198:201], v[26:29]
	v_mfma_f32_16x16x32_bf16 v[26:29], v[178:181], v[194:197], v[26:29]
	v_mfma_f32_16x16x32_bf16 v[42:45], v[178:181], v[186:189], v[42:45]
	v_mfma_f32_16x16x32_bf16 v[42:45], v[182:185], v[190:193], v[42:45]
	v_mfma_f32_16x16x32_bf16 v[46:49], v[174:177], v[190:193], v[46:49]
	v_mfma_f32_16x16x32_bf16 v[46:49], v[170:173], v[186:189], v[46:49]
	s_barrier
	s_add_u32 s10, s10, 0x100
	s_addc_u32 s11, s11, 0
	s_cmp_ge_u32 s38, s17
	s_mov_b32 s13, s38
	s_cbranch_scc0 .LBB0_2632
	s_lshl_b32 s4, s16, 21
	v_readlane_b32 s2, v249, 29
	v_lshl_or_b32 v1, s18, 8, v148
	v_mov_b32_e32 v139, 0
	s_add_u32 s4, s2, s4
	v_readlane_b32 s2, v249, 31
	v_or_b32_e32 v130, s23, v1
	v_cvt_pk_bf16_f32 v70, v70, v71
	v_cvt_pk_bf16_f32 v71, v72, v73
	v_cvt_pk_bf16_f32 v72, v66, v67
	v_add_u32_e32 v66, 0x80, v138
	v_mov_b32_e32 v67, v139
	s_addc_u32 s5, s2, 0
	v_ashrrev_i32_e32 v131, 31, v130
	v_lshlrev_b64 v[132:133], 13, v[138:139]
	v_cvt_pk_bf16_f32 v110, v110, v111
	v_cvt_pk_bf16_f32 v111, v112, v113
	v_cvt_pk_bf16_f32 v112, v106, v107
	v_or_b32_e32 v106, 16, v138
	v_mov_b32_e32 v107, v139
	v_lshlrev_b64 v[66:67], 13, v[66:67]
	v_cvt_pk_bf16_f32 v46, v46, v47
	v_cvt_pk_bf16_f32 v47, v48, v49
	v_cvt_pk_bf16_f32 v48, v42, v43
	v_add_u32_e32 v42, 0x90, v138
	v_mov_b32_e32 v43, v139
	v_lshl_add_u64 v[132:133], s[4:5], 0, v[132:133]
	v_lshlrev_b64 v[130:131], 1, v[130:131]
	v_lshlrev_b64 v[106:107], 13, v[106:107]
	v_cvt_pk_bf16_f32 v94, v94, v95
	v_cvt_pk_bf16_f32 v95, v96, v97
	v_cvt_pk_bf16_f32 v96, v90, v91
	v_or_b32_e32 v90, 32, v138
	v_mov_b32_e32 v91, v139
	v_lshl_add_u64 v[66:67], s[4:5], 0, v[66:67]
	v_lshlrev_b64 v[42:43], 13, v[42:43]
	v_cvt_pk_bf16_f32 v30, v30, v31
	v_cvt_pk_bf16_f32 v31, v32, v33
	v_cvt_pk_bf16_f32 v32, v26, v27
	v_add_u32_e32 v26, 0xa0, v138
	v_mov_b32_e32 v27, v139
	v_lshl_add_u64 v[132:133], v[132:133], 0, v[130:131]
	v_cvt_pk_bf16_f32 v113, v108, v109
	v_lshl_add_u64 v[106:107], s[4:5], 0, v[106:107]
	v_lshlrev_b64 v[90:91], 13, v[90:91]
	v_cvt_pk_bf16_f32 v78, v78, v79
	v_cvt_pk_bf16_f32 v79, v80, v81
	v_cvt_pk_bf16_f32 v80, v74, v75
	v_or_b32_e32 v74, 48, v138
	v_mov_b32_e32 v75, v139
	v_lshl_add_u64 v[66:67], v[66:67], 0, v[130:131]
	v_cvt_pk_bf16_f32 v49, v44, v45
	v_lshl_add_u64 v[42:43], s[4:5], 0, v[42:43]
	v_lshlrev_b64 v[26:27], 13, v[26:27]
	v_add_u32_e32 v138, 0xb0, v138
	global_store_dwordx4 v[132:133], v[110:113], off offset:256
	v_cvt_pk_bf16_f32 v97, v92, v93
	v_lshl_add_u64 v[90:91], s[4:5], 0, v[90:91]
	v_lshl_add_u64 v[110:111], v[106:107], 0, v[130:131]
	v_lshlrev_b64 v[74:75], 13, v[74:75]
	global_store_dwordx4 v[66:67], v[46:49], off offset:256
	v_cvt_pk_bf16_f32 v33, v28, v29
	v_lshl_add_u64 v[26:27], s[4:5], 0, v[26:27]
	v_lshl_add_u64 v[46:47], v[42:43], 0, v[130:131]
	v_cvt_pk_bf16_f32 v14, v14, v15
	v_cvt_pk_bf16_f32 v15, v16, v17
	v_cvt_pk_bf16_f32 v16, v10, v11
	v_lshlrev_b64 v[10:11], 13, v[138:139]
	global_store_dwordx4 v[110:111], v[94:97], off offset:256
	v_cvt_pk_bf16_f32 v81, v76, v77
	v_lshl_add_u64 v[74:75], s[4:5], 0, v[74:75]
	v_lshl_add_u64 v[94:95], v[90:91], 0, v[130:131]
	global_store_dwordx4 v[46:47], v[30:33], off offset:256
	v_cvt_pk_bf16_f32 v17, v12, v13
	v_lshl_add_u64 v[10:11], s[4:5], 0, v[10:11]
	v_lshl_add_u64 v[30:31], v[26:27], 0, v[130:131]
	v_cvt_pk_bf16_f32 v126, v126, v127
	v_cvt_pk_bf16_f32 v127, v128, v129
	v_cvt_pk_bf16_f32 v128, v122, v123
	v_cvt_pk_bf16_f32 v129, v124, v125
	v_cvt_pk_bf16_f32 v106, v118, v119
	v_cvt_pk_bf16_f32 v107, v120, v121
	v_cvt_pk_bf16_f32 v108, v114, v115
	v_cvt_pk_bf16_f32 v109, v116, v117
	v_cvt_pk_bf16_f32 v90, v102, v103
	v_cvt_pk_bf16_f32 v91, v104, v105
	v_cvt_pk_bf16_f32 v92, v98, v99
	v_cvt_pk_bf16_f32 v93, v100, v101
	global_store_dwordx4 v[94:95], v[78:81], off offset:256
	v_cvt_pk_bf16_f32 v76, v82, v83
	v_cvt_pk_bf16_f32 v77, v84, v85
	v_lshl_add_u64 v[78:79], v[74:75], 0, v[130:131]
	v_cvt_pk_bf16_f32 v74, v86, v87
	v_cvt_pk_bf16_f32 v75, v88, v89
	v_cvt_pk_bf16_f32 v73, v68, v69
	v_cvt_pk_bf16_f32 v62, v62, v63
	v_cvt_pk_bf16_f32 v63, v64, v65
	v_cvt_pk_bf16_f32 v64, v58, v59
	v_cvt_pk_bf16_f32 v65, v60, v61
	v_cvt_pk_bf16_f32 v42, v54, v55
	v_cvt_pk_bf16_f32 v43, v56, v57
	v_cvt_pk_bf16_f32 v44, v50, v51
	v_cvt_pk_bf16_f32 v45, v52, v53
	v_cvt_pk_bf16_f32 v26, v38, v39
	v_cvt_pk_bf16_f32 v27, v40, v41
	v_cvt_pk_bf16_f32 v28, v34, v35
	v_cvt_pk_bf16_f32 v29, v36, v37
	global_store_dwordx4 v[30:31], v[14:17], off offset:256
	v_cvt_pk_bf16_f32 v12, v18, v19
	v_cvt_pk_bf16_f32 v13, v20, v21
	v_lshl_add_u64 v[14:15], v[10:11], 0, v[130:131]
	v_cvt_pk_bf16_f32 v10, v22, v23
	v_cvt_pk_bf16_f32 v11, v24, v25
	v_cvt_pk_bf16_f32 v6, v6, v7
	v_cvt_pk_bf16_f32 v7, v8, v9
	v_cvt_pk_bf16_f32 v8, v2, v3
	v_cvt_pk_bf16_f32 v9, v4, v5
	global_store_dwordx4 v[132:133], v[126:129], off
	global_store_dwordx4 v[110:111], v[106:109], off
	global_store_dwordx4 v[94:95], v[90:93], off
	global_store_dwordx4 v[78:79], v[74:77], off
	global_store_dwordx4 v[78:79], v[70:73], off offset:256
	global_store_dwordx4 v[66:67], v[62:65], off
	global_store_dwordx4 v[46:47], v[42:45], off
	global_store_dwordx4 v[30:31], v[26:29], off
	global_store_dwordx4 v[14:15], v[10:13], off
	global_store_dwordx4 v[14:15], v[6:9], off offset:256
	s_waitcnt vmcnt(0)
	s_cmpk_lt_u32 s3, 0x100
	s_cbranch_scc0 .LBB0_2635
	s_barrier
